# de-serialised epilogues: ss/base loads hoisted, counted vmcnt instead of vmcnt(0) in EpiRelu2 and 3 EpiResB copies
# speedup vs baseline: 1.0004x; 1.0004x over previous
; __device__ __forceinline__ u32x4 pack8(f32x4 a, f32x4 b) { u32x4 w; w.x = cvt_pk_bf16(a[0], a[1]); w.y = cvt_pk_bf16(a[2], a[3]); w.z = cvt_pk_bf16(b[0], b[1]); w.w = cvt_pk_bf16(b[2], b[3]); return w; }
;     __device__ __forceinline__ void operator()(const f32x4 (&acc)[2][2][4][2], const Unit& u, int wr, int wc, int fr, int fq) const {
;         const int row0 = u.pm * BM + wr * 64 + fr, col = u.pn * BM + wc * 64 + 8 * fq;
; #pragma unroll
;         for (int ai = 0; ai < 2; ++ai)
; #pragma unroll
;             for (int m = 0; m < 4; ++m) {
;                 const int row = row0 + ai * HALF + m * 16; const size_t off = (size_t)row * 2048 + col;
;                 float s = 0.f;
; #pragma unroll
;                 for (int bj = 0; bj < 2; ++bj) {
;                     f32x4 b0, b1;
;                     if (BASE_F32) { const float* bp = (const float*)base + off + bj * 32; b0 = *(const f32x4*)bp; b1 = *(const f32x4*)(bp + 4); }
;                     else { const u32x4 w = *(const u32x4*)((const bf16_t*)base + off + bj * 32);
;                         b0 = (f32x4){__uint_as_float(w.x << 16), __uint_as_float(w.x & 0xffff0000u), __uint_as_float(w.y << 16), __uint_as_float(w.y & 0xffff0000u)};
;                         b1 = (f32x4){__uint_as_float(w.z << 16), __uint_as_float(w.z & 0xffff0000u), __uint_as_float(w.w << 16), __uint_as_float(w.w & 0xffff0000u)}; }
;                     const f32x4 h0 = b0 + acc[ai][bj][m][0], h1 = b1 + acc[ai][bj][m][1];
;                     s += (h0[0] * h0[0] + h0[1] * h0[1]) + (h0[2] * h0[2] + h0[3] * h0[3]) + (h1[0] * h1[0] + h1[1] * h1[1]) + (h1[2] * h1[2] + h1[3] * h1[3]);
;                     *(u32x4*)(H + off + bj * 32) = pack8(h0, h1);
;                 }
;                 s += __shfl_xor(s, 16); s += __shfl_xor(s, 32);
;                 if (fq == 0) __hip_atomic_fetch_add(ss + row, s, __ATOMIC_RELAXED, __HIP_MEMORY_SCOPE_AGENT);
;                 if (m & 1) asm volatile("" ::: "memory");
;             }
.LBB0_331:
	v_lshl_add_u32 v136, s22, 8, v138
	v_ashrrev_i32_e32 v137, 31, v136
	v_lshl_or_b32 v134, s24, 8, v140
	v_lshlrev_b64 v[142:143], 12, v[136:137]
	v_ashrrev_i32_e32 v135, 31, v134
	v_lshl_add_u64 v[142:143], s[6:7], 0, v[142:143]
	v_lshl_add_u64 v[146:147], v[134:135], 1, v[142:143]
	v_mov_b32_e32 v168, v136
	v_ashrrev_i32_e32 v169, 31, v168
	v_lshlrev_b64 v[168:169], 12, v[168:169]
	v_lshl_add_u64 v[168:169], s[6:7], 0, v[168:169]
	v_lshl_add_u64 v[168:169], v[134:135], 1, v[168:169]
	global_load_dwordx4 v[152:155], v[168:169], off
	global_load_dwordx4 v[156:159], v[168:169], off offset:64
	v_add_u32_e32 v168, 0x10, v136
	v_ashrrev_i32_e32 v169, 31, v168
	v_lshlrev_b64 v[168:169], 12, v[168:169]
	v_lshl_add_u64 v[168:169], s[6:7], 0, v[168:169]
	v_lshl_add_u64 v[168:169], v[134:135], 1, v[168:169]
	global_load_dwordx4 v[160:163], v[168:169], off
	global_load_dwordx4 v[164:167], v[168:169], off offset:64
	v_add_u32_e32 v168, 0x20, v136
	v_ashrrev_i32_e32 v169, 31, v168
	v_lshlrev_b64 v[168:169], 12, v[168:169]
	v_lshl_add_u64 v[168:169], s[6:7], 0, v[168:169]
	v_lshl_add_u64 v[168:169], v[134:135], 1, v[168:169]
	global_load_dwordx4 v[178:181], v[168:169], off
	global_load_dwordx4 v[182:185], v[168:169], off offset:64
	v_add_u32_e32 v168, 0x30, v136
	v_ashrrev_i32_e32 v169, 31, v168
	v_lshlrev_b64 v[168:169], 12, v[168:169]
	v_lshl_add_u64 v[168:169], s[6:7], 0, v[168:169]
	v_lshl_add_u64 v[168:169], v[134:135], 1, v[168:169]
	global_load_dwordx4 v[186:189], v[168:169], off
	global_load_dwordx4 v[190:193], v[168:169], off offset:64
	v_add_u32_e32 v168, 0x80, v136
	v_ashrrev_i32_e32 v169, 31, v168
	v_lshlrev_b64 v[168:169], 12, v[168:169]
	v_lshl_add_u64 v[168:169], s[6:7], 0, v[168:169]
	v_lshl_add_u64 v[168:169], v[134:135], 1, v[168:169]
	global_load_dwordx4 v[194:197], v[168:169], off
	global_load_dwordx4 v[198:201], v[168:169], off offset:64
	v_add_u32_e32 v168, 0x90, v136
	v_ashrrev_i32_e32 v169, 31, v168
	v_lshlrev_b64 v[168:169], 12, v[168:169]
	v_lshl_add_u64 v[168:169], s[6:7], 0, v[168:169]
	v_lshl_add_u64 v[168:169], v[134:135], 1, v[168:169]
	global_load_dwordx4 v[212:215], v[168:169], off
	global_load_dwordx4 v[216:219], v[168:169], off offset:64
	s_nop 1
	s_waitcnt vmcnt(11)
	v_mov_b32_e32 v142, v152
	v_mov_b32_e32 v143, v153
	v_mov_b32_e32 v144, v154
	v_mov_b32_e32 v145, v155
	s_nop 0
	v_lshlrev_b32_e32 v148, 16, v142
	v_and_b32_e32 v149, 0xffff0000, v142
	v_lshlrev_b32_e32 v142, 16, v143
	v_and_b32_e32 v143, 0xffff0000, v143
	v_lshlrev_b32_e32 v150, 16, v144
	v_and_b32_e32 v151, 0xffff0000, v144
	v_lshlrev_b32_e32 v144, 16, v145
	v_and_b32_e32 v145, 0xffff0000, v145
	v_pk_add_f32 v[126:127], v[126:127], v[142:143]
	v_pk_add_f32 v[124:125], v[124:125], v[148:149]
	v_pk_add_f32 v[142:143], v[122:123], v[144:145]
	v_pk_add_f32 v[122:123], v[120:121], v[150:151]
	v_mul_f32_e32 v120, v125, v125
	v_mul_f32_e32 v121, v127, v127
	v_fmac_f32_e32 v120, v124, v124
	v_fmac_f32_e32 v121, v126, v126
	v_add_f32_e32 v120, v120, v121
	v_mul_f32_e32 v121, v123, v123
	v_fmac_f32_e32 v121, v122, v122
	v_add_f32_e32 v120, v121, v120
	v_mul_f32_e32 v121, v143, v143
	v_fmac_f32_e32 v121, v142, v142
	v_add_f32_e32 v144, v121, v120
	v_cvt_pk_bf16_f32 v120, v124, v125
	v_cvt_pk_bf16_f32 v121, v126, v127
	v_cvt_pk_bf16_f32 v122, v122, v123
	v_cvt_pk_bf16_f32 v123, v142, v143
	global_store_dwordx4 v[146:147], v[120:123], off
	s_nop 1
	s_waitcnt vmcnt(11)
	v_mov_b32_e32 v120, v156
	v_mov_b32_e32 v121, v157
	v_mov_b32_e32 v122, v158
	v_mov_b32_e32 v123, v159
	v_add_u32_e32 v168, 0xa0, v136
	v_ashrrev_i32_e32 v169, 31, v168
	v_lshlrev_b64 v[168:169], 12, v[168:169]
	v_lshl_add_u64 v[168:169], s[6:7], 0, v[168:169]
	v_lshl_add_u64 v[168:169], v[134:135], 1, v[168:169]
	global_load_dwordx4 v[152:155], v[168:169], off
	global_load_dwordx4 v[156:159], v[168:169], off offset:64
	s_nop 0
	v_lshlrev_b32_e32 v124, 16, v120
	v_and_b32_e32 v125, 0xffff0000, v120
	v_lshlrev_b32_e32 v120, 16, v121
	v_and_b32_e32 v121, 0xffff0000, v121
	v_lshlrev_b32_e32 v126, 16, v122
	v_and_b32_e32 v127, 0xffff0000, v122
	v_lshlrev_b32_e32 v122, 16, v123
	v_and_b32_e32 v123, 0xffff0000, v123
	v_pk_add_f32 v[118:119], v[118:119], v[120:121]
	v_pk_add_f32 v[116:117], v[116:117], v[124:125]
	v_pk_add_f32 v[120:121], v[114:115], v[122:123]
	v_pk_add_f32 v[114:115], v[112:113], v[126:127]
	v_mul_f32_e32 v112, v117, v117
	v_mul_f32_e32 v113, v119, v119
	v_fmac_f32_e32 v112, v116, v116
	v_fmac_f32_e32 v113, v118, v118
	v_add_f32_e32 v112, v112, v113
	v_mul_f32_e32 v113, v115, v115
	v_fmac_f32_e32 v113, v114, v114
	v_add_f32_e32 v112, v113, v112
	v_mul_f32_e32 v113, v121, v121
	v_fmac_f32_e32 v113, v120, v120
	v_add_f32_e32 v112, v113, v112
	v_add_f32_e32 v122, v144, v112
	v_cvt_pk_bf16_f32 v112, v116, v117
	v_cvt_pk_bf16_f32 v113, v118, v119
	v_cvt_pk_bf16_f32 v114, v114, v115
	v_cvt_pk_bf16_f32 v115, v120, v121
	global_store_dwordx4 v[146:147], v[112:115], off offset:64
	s_nop 1
	v_and_b32_e32 v113, 64, v209
	v_xor_b32_e32 v112, 16, v209
	v_add_u32_e32 v113, 64, v113
	v_cmp_lt_i32_e32 vcc, v112, v113
	v_xor_b32_e32 v115, 32, v209
	s_nop 0
	v_cndmask_b32_e32 v112, v209, v112, vcc
	v_lshlrev_b32_e32 v114, 2, v112
	ds_bpermute_b32 v112, v114, v122
	v_cmp_lt_i32_e32 vcc, v115, v113
	s_waitcnt lgkmcnt(0)
	v_add_f32_e32 v112, v122, v112
	v_cndmask_b32_e32 v113, v209, v115, vcc
	v_lshlrev_b32_e32 v115, 2, v113
	ds_bpermute_b32 v113, v115, v112
	s_and_saveexec_b64 s[22:23], s[2:3]
	s_cbranch_execz .LBB0_333
	v_lshl_add_u64 v[116:117], v[136:137], 2, s[8:9]
	s_waitcnt lgkmcnt(0)
	v_add_f32_e32 v112, v112, v113
	global_atomic_add_f32 v[116:117], v112, off
; __device__ __forceinline__ u32x4 pack8(f32x4 a, f32x4 b) { u32x4 w; w.x = cvt_pk_bf16(a[0], a[1]); w.y = cvt_pk_bf16(a[2], a[3]); w.z = cvt_pk_bf16(b[0], b[1]); w.w = cvt_pk_bf16(b[2], b[3]); return w; }
;     __device__ __forceinline__ void operator()(const f32x4 (&acc)[2][2][4][2], const Unit& u, int wr, int wc, int fr, int fq) const {
;         const int row0 = u.pm * BM + wr * 64 + fr, col = u.pn * BM + wc * 64 + 8 * fq;
; #pragma unroll
;         for (int ai = 0; ai < 2; ++ai)
; #pragma unroll
;             for (int m = 0; m < 4; ++m) {
;                 const int row = row0 + ai * HALF + m * 16; const size_t off = (size_t)row * 2048 + col;
;                 float s = 0.f;
; #pragma unroll
;                 for (int bj = 0; bj < 2; ++bj) {
;                     f32x4 b0, b1;
;                     if (BASE_F32) { const float* bp = (const float*)base + off + bj * 32; b0 = *(const f32x4*)bp; b1 = *(const f32x4*)(bp + 4); }
;                     else { const u32x4 w = *(const u32x4*)((const bf16_t*)base + off + bj * 32);
;                         b0 = (f32x4){__uint_as_float(w.x << 16), __uint_as_float(w.x & 0xffff0000u), __uint_as_float(w.y << 16), __uint_as_float(w.y & 0xffff0000u)};
;                         b1 = (f32x4){__uint_as_float(w.z << 16), __uint_as_float(w.z & 0xffff0000u), __uint_as_float(w.w << 16), __uint_as_float(w.w & 0xffff0000u)}; }
;                     const f32x4 h0 = b0 + acc[ai][bj][m][0], h1 = b1 + acc[ai][bj][m][1];
;                     s += (h0[0] * h0[0] + h0[1] * h0[1]) + (h0[2] * h0[2] + h0[3] * h0[3]) + (h1[0] * h1[0] + h1[1] * h1[1]) + (h1[2] * h1[2] + h1[3] * h1[3]);
;                     *(u32x4*)(H + off + bj * 32) = pack8(h0, h1);
;                 }
;                 s += __shfl_xor(s, 16); s += __shfl_xor(s, 32);
;                 if (fq == 0) __hip_atomic_fetch_add(ss + row, s, __ATOMIC_RELAXED, __HIP_MEMORY_SCOPE_AGENT);
;                 if (m & 1) asm volatile("" ::: "memory");
;             }
.LBB0_333:
	s_or_b64 exec, exec, s[22:23]
	v_or_b32_e32 v112, 16, v136
	s_waitcnt lgkmcnt(0)
	v_ashrrev_i32_e32 v113, 31, v112
	v_lshlrev_b64 v[116:117], 12, v[112:113]
	v_lshl_add_u64 v[116:117], s[6:7], 0, v[116:117]
	v_lshl_add_u64 v[120:121], v[134:135], 1, v[116:117]
	s_nop 1
	s_waitcnt vmcnt(13)
	v_mov_b32_e32 v116, v160
	v_mov_b32_e32 v117, v161
	v_mov_b32_e32 v118, v162
	v_mov_b32_e32 v119, v163
	s_nop 0
	v_lshlrev_b32_e32 v122, 16, v116
	v_and_b32_e32 v123, 0xffff0000, v116
	v_lshlrev_b32_e32 v116, 16, v117
	v_and_b32_e32 v117, 0xffff0000, v117
	v_lshlrev_b32_e32 v124, 16, v118
	v_and_b32_e32 v125, 0xffff0000, v118
	v_lshlrev_b32_e32 v118, 16, v119
	v_and_b32_e32 v119, 0xffff0000, v119
	v_pk_add_f32 v[116:117], v[110:111], v[116:117]
	v_pk_add_f32 v[122:123], v[108:109], v[122:123]
	v_pk_add_f32 v[118:119], v[106:107], v[118:119]
	v_pk_add_f32 v[124:125], v[104:105], v[124:125]
	v_cvt_pk_bf16_f32 v104, v122, v123
	v_cvt_pk_bf16_f32 v105, v116, v117
	v_mul_f32_e32 v123, v123, v123
	v_cvt_pk_bf16_f32 v106, v124, v125
	v_cvt_pk_bf16_f32 v107, v118, v119
	s_nop 1
	s_waitcnt vmcnt(12)
	v_mov_b32_e32 v108, v164
	v_mov_b32_e32 v109, v165
	v_mov_b32_e32 v110, v166
	v_mov_b32_e32 v111, v167
	v_add_u32_e32 v168, 0xb0, v136
	v_ashrrev_i32_e32 v169, 31, v168
	v_lshlrev_b64 v[168:169], 12, v[168:169]
	v_lshl_add_u64 v[168:169], s[6:7], 0, v[168:169]
	v_lshl_add_u64 v[168:169], v[134:135], 1, v[168:169]
	global_load_dwordx4 v[160:163], v[168:169], off
	global_load_dwordx4 v[164:167], v[168:169], off offset:64
	v_mul_f32_e32 v117, v117, v117
	v_mul_f32_e32 v125, v125, v125
	v_fmac_f32_e32 v123, v122, v122
	v_fmac_f32_e32 v117, v116, v116
	v_mul_f32_e32 v119, v119, v119
	v_fmac_f32_e32 v125, v124, v124
	v_add_f32_e32 v116, v123, v117
	v_fmac_f32_e32 v119, v118, v118
	v_add_f32_e32 v116, v125, v116
	v_add_f32_e32 v122, v119, v116
	global_store_dwordx4 v[120:121], v[104:107], off
	s_nop 0
	v_lshlrev_b32_e32 v116, 16, v108
	v_and_b32_e32 v117, 0xffff0000, v108
	v_lshlrev_b32_e32 v108, 16, v109
	v_and_b32_e32 v109, 0xffff0000, v109
	v_lshlrev_b32_e32 v118, 16, v110
	v_and_b32_e32 v119, 0xffff0000, v110
	v_lshlrev_b32_e32 v110, 16, v111
	v_and_b32_e32 v111, 0xffff0000, v111
	v_pk_add_f32 v[102:103], v[102:103], v[108:109]
	v_pk_add_f32 v[100:101], v[100:101], v[116:117]
	v_pk_add_f32 v[108:109], v[98:99], v[110:111]
	v_pk_add_f32 v[110:111], v[96:97], v[118:119]
	v_mul_f32_e32 v96, v101, v101
	v_mul_f32_e32 v97, v103, v103
	v_mul_f32_e32 v98, v111, v111
	v_fmac_f32_e32 v96, v100, v100
	v_fmac_f32_e32 v97, v102, v102
	v_mul_f32_e32 v99, v109, v109
	v_fmac_f32_e32 v98, v110, v110
	v_add_f32_e32 v96, v96, v97
	v_add_f32_e32 v96, v98, v96
	v_fmac_f32_e32 v99, v108, v108
	v_add_f32_e32 v96, v99, v96
	v_add_f32_e32 v96, v122, v96
	ds_bpermute_b32 v97, v114, v96
	v_cvt_pk_bf16_f32 v98, v100, v101
	v_cvt_pk_bf16_f32 v99, v102, v103
	v_cvt_pk_bf16_f32 v100, v110, v111
	v_cvt_pk_bf16_f32 v101, v108, v109
	s_waitcnt lgkmcnt(0)
	v_add_f32_e32 v96, v96, v97
	ds_bpermute_b32 v97, v115, v96
	global_store_dwordx4 v[120:121], v[98:101], off offset:64
	s_and_saveexec_b64 s[22:23], s[2:3]
	s_cbranch_execz .LBB0_335
	v_lshl_add_u64 v[98:99], v[112:113], 2, s[8:9]
	s_waitcnt lgkmcnt(0)
	v_add_f32_e32 v96, v96, v97
	global_atomic_add_f32 v[98:99], v96, off
.LBB0_335:
	s_or_b64 exec, exec, s[22:23]
	v_or_b32_e32 v96, 32, v136
	s_waitcnt lgkmcnt(0)
	v_ashrrev_i32_e32 v97, 31, v96
	v_lshlrev_b64 v[98:99], 12, v[96:97]
	v_lshl_add_u64 v[98:99], s[6:7], 0, v[98:99]
	v_lshl_add_u64 v[102:103], v[134:135], 1, v[98:99]
	s_nop 1
	s_waitcnt vmcnt(15)
	v_mov_b32_e32 v98, v178
	v_mov_b32_e32 v99, v179
	v_mov_b32_e32 v100, v180
	v_mov_b32_e32 v101, v181
	s_nop 0
	v_lshlrev_b32_e32 v104, 16, v98
	v_and_b32_e32 v105, 0xffff0000, v98
	v_lshlrev_b32_e32 v98, 16, v99
	v_and_b32_e32 v99, 0xffff0000, v99
	v_lshlrev_b32_e32 v106, 16, v100
	v_and_b32_e32 v107, 0xffff0000, v100
	v_lshlrev_b32_e32 v100, 16, v101
	v_and_b32_e32 v101, 0xffff0000, v101
	v_pk_add_f32 v[98:99], v[94:95], v[98:99]
	v_pk_add_f32 v[104:105], v[92:93], v[104:105]
	v_pk_add_f32 v[100:101], v[90:91], v[100:101]
	v_pk_add_f32 v[106:107], v[88:89], v[106:107]
	v_cvt_pk_bf16_f32 v88, v104, v105
	v_cvt_pk_bf16_f32 v89, v98, v99
	v_mul_f32_e32 v105, v105, v105
	v_cvt_pk_bf16_f32 v90, v106, v107
	v_cvt_pk_bf16_f32 v91, v100, v101
	s_nop 1
	s_waitcnt vmcnt(14)
	v_mov_b32_e32 v92, v182
	v_mov_b32_e32 v93, v183
	v_mov_b32_e32 v94, v184
	v_mov_b32_e32 v95, v185
	v_mul_f32_e32 v99, v99, v99
	v_mul_f32_e32 v107, v107, v107
	v_fmac_f32_e32 v105, v104, v104
	v_fmac_f32_e32 v99, v98, v98
	v_mul_f32_e32 v101, v101, v101
	v_fmac_f32_e32 v107, v106, v106
	v_add_f32_e32 v98, v105, v99
	v_fmac_f32_e32 v101, v100, v100
	v_add_f32_e32 v98, v107, v98
	v_add_f32_e32 v104, v101, v98
	global_store_dwordx4 v[102:103], v[88:91], off
	s_nop 0
	v_lshlrev_b32_e32 v98, 16, v92
	v_and_b32_e32 v99, 0xffff0000, v92
	v_lshlrev_b32_e32 v92, 16, v93
	v_and_b32_e32 v93, 0xffff0000, v93
	v_lshlrev_b32_e32 v100, 16, v94
	v_and_b32_e32 v101, 0xffff0000, v94
	v_lshlrev_b32_e32 v94, 16, v95
	v_and_b32_e32 v95, 0xffff0000, v95
	v_pk_add_f32 v[86:87], v[86:87], v[92:93]
	v_pk_add_f32 v[84:85], v[84:85], v[98:99]
	v_pk_add_f32 v[92:93], v[82:83], v[94:95]
	v_pk_add_f32 v[94:95], v[80:81], v[100:101]
	v_mul_f32_e32 v80, v85, v85
	v_mul_f32_e32 v81, v87, v87
	v_mul_f32_e32 v82, v95, v95
	v_fmac_f32_e32 v80, v84, v84
	v_fmac_f32_e32 v81, v86, v86
	v_mul_f32_e32 v83, v93, v93
	v_fmac_f32_e32 v82, v94, v94
	v_add_f32_e32 v80, v80, v81
	v_add_f32_e32 v80, v82, v80
	v_fmac_f32_e32 v83, v92, v92
	v_add_f32_e32 v80, v83, v80
	v_add_f32_e32 v80, v104, v80
	ds_bpermute_b32 v81, v114, v80
	v_cvt_pk_bf16_f32 v82, v84, v85
	v_cvt_pk_bf16_f32 v83, v86, v87
	v_cvt_pk_bf16_f32 v84, v94, v95
	v_cvt_pk_bf16_f32 v85, v92, v93
	s_waitcnt lgkmcnt(0)
	v_add_f32_e32 v80, v80, v81
	ds_bpermute_b32 v81, v115, v80
	global_store_dwordx4 v[102:103], v[82:85], off offset:64
	s_and_saveexec_b64 s[22:23], s[2:3]
	s_cbranch_execz .LBB0_337
	v_lshl_add_u64 v[82:83], v[96:97], 2, s[8:9]
	s_waitcnt lgkmcnt(0)
	v_add_f32_e32 v80, v80, v81
	global_atomic_add_f32 v[82:83], v80, off
; __device__ __forceinline__ u32x4 pack8(f32x4 a, f32x4 b) { u32x4 w; w.x = cvt_pk_bf16(a[0], a[1]); w.y = cvt_pk_bf16(a[2], a[3]); w.z = cvt_pk_bf16(b[0], b[1]); w.w = cvt_pk_bf16(b[2], b[3]); return w; }
;     __device__ __forceinline__ void operator()(const f32x4 (&acc)[2][2][4][2], const Unit& u, int wr, int wc, int fr, int fq) const {
;         const int row0 = u.pm * BM + wr * 64 + fr, col = u.pn * BM + wc * 64 + 8 * fq;
; #pragma unroll
;         for (int ai = 0; ai < 2; ++ai)
; #pragma unroll
;             for (int m = 0; m < 4; ++m) {
;                 const int row = row0 + ai * HALF + m * 16; const size_t off = (size_t)row * 2048 + col;
;                 float s = 0.f;
; #pragma unroll
;                 for (int bj = 0; bj < 2; ++bj) {
;                     f32x4 b0, b1;
;                     if (BASE_F32) { const float* bp = (const float*)base + off + bj * 32; b0 = *(const f32x4*)bp; b1 = *(const f32x4*)(bp + 4); }
;                     else { const u32x4 w = *(const u32x4*)((const bf16_t*)base + off + bj * 32);
;                         b0 = (f32x4){__uint_as_float(w.x << 16), __uint_as_float(w.x & 0xffff0000u), __uint_as_float(w.y << 16), __uint_as_float(w.y & 0xffff0000u)};
;                         b1 = (f32x4){__uint_as_float(w.z << 16), __uint_as_float(w.z & 0xffff0000u), __uint_as_float(w.w << 16), __uint_as_float(w.w & 0xffff0000u)}; }
;                     const f32x4 h0 = b0 + acc[ai][bj][m][0], h1 = b1 + acc[ai][bj][m][1];
;                     s += (h0[0] * h0[0] + h0[1] * h0[1]) + (h0[2] * h0[2] + h0[3] * h0[3]) + (h1[0] * h1[0] + h1[1] * h1[1]) + (h1[2] * h1[2] + h1[3] * h1[3]);
;                     *(u32x4*)(H + off + bj * 32) = pack8(h0, h1);
;                 }
;                 s += __shfl_xor(s, 16); s += __shfl_xor(s, 32);
;                 if (fq == 0) __hip_atomic_fetch_add(ss + row, s, __ATOMIC_RELAXED, __HIP_MEMORY_SCOPE_AGENT);
;                 if (m & 1) asm volatile("" ::: "memory");
;             }
.LBB0_337:
	s_or_b64 exec, exec, s[22:23]
	v_or_b32_e32 v80, 48, v136
	s_waitcnt lgkmcnt(0)
	v_ashrrev_i32_e32 v81, 31, v80
	v_lshlrev_b64 v[82:83], 12, v[80:81]
	v_lshl_add_u64 v[82:83], s[6:7], 0, v[82:83]
	v_lshl_add_u64 v[86:87], v[134:135], 1, v[82:83]
	s_nop 1
	s_waitcnt vmcnt(15)
	v_mov_b32_e32 v82, v186
	v_mov_b32_e32 v83, v187
	v_mov_b32_e32 v84, v188
	v_mov_b32_e32 v85, v189
	s_nop 0
	v_lshlrev_b32_e32 v88, 16, v82
	v_and_b32_e32 v89, 0xffff0000, v82
	v_lshlrev_b32_e32 v82, 16, v83
	v_and_b32_e32 v83, 0xffff0000, v83
	v_lshlrev_b32_e32 v90, 16, v84
	v_and_b32_e32 v91, 0xffff0000, v84
	v_lshlrev_b32_e32 v84, 16, v85
	v_and_b32_e32 v85, 0xffff0000, v85
	v_pk_add_f32 v[82:83], v[78:79], v[82:83]
	v_pk_add_f32 v[88:89], v[76:77], v[88:89]
	v_pk_add_f32 v[84:85], v[74:75], v[84:85]
	v_pk_add_f32 v[90:91], v[72:73], v[90:91]
	v_cvt_pk_bf16_f32 v72, v88, v89
	v_cvt_pk_bf16_f32 v73, v82, v83
	v_mul_f32_e32 v89, v89, v89
	v_cvt_pk_bf16_f32 v74, v90, v91
	v_cvt_pk_bf16_f32 v75, v84, v85
	s_nop 1
	s_waitcnt vmcnt(14)
	v_mov_b32_e32 v76, v190
	v_mov_b32_e32 v77, v191
	v_mov_b32_e32 v78, v192
	v_mov_b32_e32 v79, v193
	v_mul_f32_e32 v83, v83, v83
	v_mul_f32_e32 v91, v91, v91
	v_fmac_f32_e32 v89, v88, v88
	v_fmac_f32_e32 v83, v82, v82
	v_mul_f32_e32 v85, v85, v85
	v_fmac_f32_e32 v91, v90, v90
	v_add_f32_e32 v82, v89, v83
	v_fmac_f32_e32 v85, v84, v84
	v_add_f32_e32 v82, v91, v82
	v_add_f32_e32 v88, v85, v82
	global_store_dwordx4 v[86:87], v[72:75], off
	s_nop 0
	v_lshlrev_b32_e32 v82, 16, v76
	v_and_b32_e32 v83, 0xffff0000, v76
	v_lshlrev_b32_e32 v76, 16, v77
	v_and_b32_e32 v77, 0xffff0000, v77
	v_lshlrev_b32_e32 v84, 16, v78
	v_and_b32_e32 v85, 0xffff0000, v78
	v_lshlrev_b32_e32 v78, 16, v79
	v_and_b32_e32 v79, 0xffff0000, v79
	v_pk_add_f32 v[70:71], v[70:71], v[76:77]
	v_pk_add_f32 v[68:69], v[68:69], v[82:83]
	v_pk_add_f32 v[76:77], v[66:67], v[78:79]
	v_pk_add_f32 v[78:79], v[64:65], v[84:85]
	v_mul_f32_e32 v64, v69, v69
	v_mul_f32_e32 v65, v71, v71
	v_mul_f32_e32 v66, v79, v79
	v_fmac_f32_e32 v64, v68, v68
	v_fmac_f32_e32 v65, v70, v70
	v_mul_f32_e32 v67, v77, v77
	v_fmac_f32_e32 v66, v78, v78
	v_add_f32_e32 v64, v64, v65
	v_add_f32_e32 v64, v66, v64
	v_fmac_f32_e32 v67, v76, v76
	v_add_f32_e32 v64, v67, v64
	v_add_f32_e32 v64, v88, v64
	ds_bpermute_b32 v65, v114, v64
	v_cvt_pk_bf16_f32 v66, v68, v69
	v_cvt_pk_bf16_f32 v67, v70, v71
	v_cvt_pk_bf16_f32 v68, v78, v79
	v_cvt_pk_bf16_f32 v69, v76, v77
	s_waitcnt lgkmcnt(0)
	v_add_f32_e32 v64, v64, v65
	ds_bpermute_b32 v65, v115, v64
	global_store_dwordx4 v[86:87], v[66:69], off offset:64
	s_and_saveexec_b64 s[22:23], s[2:3]
	s_cbranch_execz .LBB0_339
	v_lshl_add_u64 v[66:67], v[80:81], 2, s[8:9]
	s_waitcnt lgkmcnt(0)
	v_add_f32_e32 v64, v64, v65
	global_atomic_add_f32 v[66:67], v64, off
.LBB0_339:
	s_or_b64 exec, exec, s[22:23]
	v_add_u32_e32 v64, 0x80, v136
	s_waitcnt lgkmcnt(0)
	v_ashrrev_i32_e32 v65, 31, v64
	v_lshlrev_b64 v[66:67], 12, v[64:65]
	v_lshl_add_u64 v[66:67], s[6:7], 0, v[66:67]
	v_lshl_add_u64 v[70:71], v[134:135], 1, v[66:67]
	s_nop 1
	s_waitcnt vmcnt(15)
	v_mov_b32_e32 v66, v194
	v_mov_b32_e32 v67, v195
	v_mov_b32_e32 v68, v196
	v_mov_b32_e32 v69, v197
	s_nop 0
	v_lshlrev_b32_e32 v72, 16, v66
	v_and_b32_e32 v73, 0xffff0000, v66
	v_lshlrev_b32_e32 v66, 16, v67
	v_and_b32_e32 v67, 0xffff0000, v67
	v_lshlrev_b32_e32 v74, 16, v68
	v_and_b32_e32 v75, 0xffff0000, v68
	v_lshlrev_b32_e32 v68, 16, v69
	v_and_b32_e32 v69, 0xffff0000, v69
	v_pk_add_f32 v[66:67], v[62:63], v[66:67]
	v_pk_add_f32 v[72:73], v[60:61], v[72:73]
	v_pk_add_f32 v[68:69], v[58:59], v[68:69]
	v_pk_add_f32 v[74:75], v[56:57], v[74:75]
	v_cvt_pk_bf16_f32 v56, v72, v73
	v_cvt_pk_bf16_f32 v57, v66, v67
	v_mul_f32_e32 v73, v73, v73
	v_cvt_pk_bf16_f32 v58, v74, v75
	v_cvt_pk_bf16_f32 v59, v68, v69
	s_nop 1
	s_waitcnt vmcnt(14)
	v_mov_b32_e32 v60, v198
	v_mov_b32_e32 v61, v199
	v_mov_b32_e32 v62, v200
	v_mov_b32_e32 v63, v201
	v_mul_f32_e32 v67, v67, v67
	v_mul_f32_e32 v75, v75, v75
	v_fmac_f32_e32 v73, v72, v72
	v_fmac_f32_e32 v67, v66, v66
	v_mul_f32_e32 v69, v69, v69
	v_fmac_f32_e32 v75, v74, v74
	v_add_f32_e32 v66, v73, v67
	v_fmac_f32_e32 v69, v68, v68
	v_add_f32_e32 v66, v75, v66
	v_add_f32_e32 v72, v69, v66
	global_store_dwordx4 v[70:71], v[56:59], off
	s_nop 0
	v_lshlrev_b32_e32 v66, 16, v60
	v_and_b32_e32 v67, 0xffff0000, v60
	v_lshlrev_b32_e32 v60, 16, v61
	v_and_b32_e32 v61, 0xffff0000, v61
	v_lshlrev_b32_e32 v68, 16, v62
	v_and_b32_e32 v69, 0xffff0000, v62
	v_lshlrev_b32_e32 v62, 16, v63
	v_and_b32_e32 v63, 0xffff0000, v63
	v_pk_add_f32 v[54:55], v[54:55], v[60:61]
	v_pk_add_f32 v[52:53], v[52:53], v[66:67]
	v_pk_add_f32 v[60:61], v[50:51], v[62:63]
	v_pk_add_f32 v[62:63], v[48:49], v[68:69]
	v_mul_f32_e32 v48, v53, v53
	v_mul_f32_e32 v49, v55, v55
	v_mul_f32_e32 v50, v63, v63
	v_fmac_f32_e32 v48, v52, v52
	v_fmac_f32_e32 v49, v54, v54
	v_mul_f32_e32 v51, v61, v61
	v_fmac_f32_e32 v50, v62, v62
	v_add_f32_e32 v48, v48, v49
	v_add_f32_e32 v48, v50, v48
	v_fmac_f32_e32 v51, v60, v60
	v_add_f32_e32 v48, v51, v48
	v_add_f32_e32 v48, v72, v48
	ds_bpermute_b32 v49, v114, v48
	v_cvt_pk_bf16_f32 v50, v52, v53
	v_cvt_pk_bf16_f32 v51, v54, v55
	v_cvt_pk_bf16_f32 v52, v62, v63
	v_cvt_pk_bf16_f32 v53, v60, v61
	s_waitcnt lgkmcnt(0)
	v_add_f32_e32 v48, v48, v49
	ds_bpermute_b32 v49, v115, v48
	global_store_dwordx4 v[70:71], v[50:53], off offset:64
	s_and_saveexec_b64 s[22:23], s[2:3]
	s_cbranch_execz .LBB0_341
	v_lshl_add_u64 v[50:51], v[64:65], 2, s[8:9]
	s_waitcnt lgkmcnt(0)
	v_add_f32_e32 v48, v48, v49
	global_atomic_add_f32 v[50:51], v48, off
; __device__ __forceinline__ u32x4 pack8(f32x4 a, f32x4 b) { u32x4 w; w.x = cvt_pk_bf16(a[0], a[1]); w.y = cvt_pk_bf16(a[2], a[3]); w.z = cvt_pk_bf16(b[0], b[1]); w.w = cvt_pk_bf16(b[2], b[3]); return w; }
;     __device__ __forceinline__ void operator()(const f32x4 (&acc)[2][2][4][2], const Unit& u, int wr, int wc, int fr, int fq) const {
;         const int row0 = u.pm * BM + wr * 64 + fr, col = u.pn * BM + wc * 64 + 8 * fq;
; #pragma unroll
;         for (int ai = 0; ai < 2; ++ai)
; #pragma unroll
;             for (int m = 0; m < 4; ++m) {
;                 const int row = row0 + ai * HALF + m * 16; const size_t off = (size_t)row * 2048 + col;
;                 float s = 0.f;
; #pragma unroll
;                 for (int bj = 0; bj < 2; ++bj) {
;                     f32x4 b0, b1;
;                     if (BASE_F32) { const float* bp = (const float*)base + off + bj * 32; b0 = *(const f32x4*)bp; b1 = *(const f32x4*)(bp + 4); }
;                     else { const u32x4 w = *(const u32x4*)((const bf16_t*)base + off + bj * 32);
;                         b0 = (f32x4){__uint_as_float(w.x << 16), __uint_as_float(w.x & 0xffff0000u), __uint_as_float(w.y << 16), __uint_as_float(w.y & 0xffff0000u)};
;                         b1 = (f32x4){__uint_as_float(w.z << 16), __uint_as_float(w.z & 0xffff0000u), __uint_as_float(w.w << 16), __uint_as_float(w.w & 0xffff0000u)}; }
;                     const f32x4 h0 = b0 + acc[ai][bj][m][0], h1 = b1 + acc[ai][bj][m][1];
;                     s += (h0[0] * h0[0] + h0[1] * h0[1]) + (h0[2] * h0[2] + h0[3] * h0[3]) + (h1[0] * h1[0] + h1[1] * h1[1]) + (h1[2] * h1[2] + h1[3] * h1[3]);
;                     *(u32x4*)(H + off + bj * 32) = pack8(h0, h1);
;                 }
;                 s += __shfl_xor(s, 16); s += __shfl_xor(s, 32);
;                 if (fq == 0) __hip_atomic_fetch_add(ss + row, s, __ATOMIC_RELAXED, __HIP_MEMORY_SCOPE_AGENT);
;                 if (m & 1) asm volatile("" ::: "memory");
;             }
.LBB0_341:
	s_or_b64 exec, exec, s[22:23]
	v_add_u32_e32 v48, 0x90, v136
	s_waitcnt lgkmcnt(0)
	v_ashrrev_i32_e32 v49, 31, v48
	v_lshlrev_b64 v[50:51], 12, v[48:49]
	v_lshl_add_u64 v[50:51], s[6:7], 0, v[50:51]
	v_lshl_add_u64 v[54:55], v[134:135], 1, v[50:51]
	s_nop 1
	s_waitcnt vmcnt(15)
	v_mov_b32_e32 v50, v212
	v_mov_b32_e32 v51, v213
	v_mov_b32_e32 v52, v214
	v_mov_b32_e32 v53, v215
	s_nop 0
	v_lshlrev_b32_e32 v56, 16, v50
	v_and_b32_e32 v57, 0xffff0000, v50
	v_lshlrev_b32_e32 v50, 16, v51
	v_and_b32_e32 v51, 0xffff0000, v51
	v_lshlrev_b32_e32 v58, 16, v52
	v_and_b32_e32 v59, 0xffff0000, v52
	v_lshlrev_b32_e32 v52, 16, v53
	v_and_b32_e32 v53, 0xffff0000, v53
	v_pk_add_f32 v[50:51], v[46:47], v[50:51]
	v_pk_add_f32 v[56:57], v[44:45], v[56:57]
	v_pk_add_f32 v[52:53], v[42:43], v[52:53]
	v_pk_add_f32 v[58:59], v[40:41], v[58:59]
	v_cvt_pk_bf16_f32 v40, v56, v57
	v_cvt_pk_bf16_f32 v41, v50, v51
	v_mul_f32_e32 v57, v57, v57
	v_cvt_pk_bf16_f32 v42, v58, v59
	v_cvt_pk_bf16_f32 v43, v52, v53
	s_nop 1
	s_waitcnt vmcnt(14)
	v_mov_b32_e32 v44, v216
	v_mov_b32_e32 v45, v217
	v_mov_b32_e32 v46, v218
	v_mov_b32_e32 v47, v219
	v_mul_f32_e32 v51, v51, v51
	v_mul_f32_e32 v59, v59, v59
	v_fmac_f32_e32 v57, v56, v56
	v_fmac_f32_e32 v51, v50, v50
	v_mul_f32_e32 v53, v53, v53
	v_fmac_f32_e32 v59, v58, v58
	v_add_f32_e32 v50, v57, v51
	v_fmac_f32_e32 v53, v52, v52
	v_add_f32_e32 v50, v59, v50
	v_add_f32_e32 v56, v53, v50
	global_store_dwordx4 v[54:55], v[40:43], off
	s_nop 0
	v_lshlrev_b32_e32 v50, 16, v44
	v_and_b32_e32 v51, 0xffff0000, v44
	v_lshlrev_b32_e32 v44, 16, v45
	v_and_b32_e32 v45, 0xffff0000, v45
	v_lshlrev_b32_e32 v52, 16, v46
	v_and_b32_e32 v53, 0xffff0000, v46
	v_lshlrev_b32_e32 v46, 16, v47
	v_and_b32_e32 v47, 0xffff0000, v47
	v_pk_add_f32 v[38:39], v[38:39], v[44:45]
	v_pk_add_f32 v[36:37], v[36:37], v[50:51]
	v_pk_add_f32 v[44:45], v[34:35], v[46:47]
	v_pk_add_f32 v[46:47], v[32:33], v[52:53]
	v_mul_f32_e32 v32, v37, v37
	v_mul_f32_e32 v33, v39, v39
	v_mul_f32_e32 v34, v47, v47
	v_fmac_f32_e32 v32, v36, v36
	v_fmac_f32_e32 v33, v38, v38
	v_mul_f32_e32 v35, v45, v45
	v_fmac_f32_e32 v34, v46, v46
	v_add_f32_e32 v32, v32, v33
	v_add_f32_e32 v32, v34, v32
	v_fmac_f32_e32 v35, v44, v44
	v_add_f32_e32 v32, v35, v32
	v_add_f32_e32 v32, v56, v32
	ds_bpermute_b32 v33, v114, v32
	v_cvt_pk_bf16_f32 v34, v36, v37
	v_cvt_pk_bf16_f32 v35, v38, v39
	v_cvt_pk_bf16_f32 v36, v46, v47
	v_cvt_pk_bf16_f32 v37, v44, v45
	s_waitcnt lgkmcnt(0)
	v_add_f32_e32 v32, v32, v33
	ds_bpermute_b32 v33, v115, v32
	global_store_dwordx4 v[54:55], v[34:37], off offset:64
	s_and_saveexec_b64 s[22:23], s[2:3]
	s_cbranch_execz .LBB0_343
	v_lshl_add_u64 v[34:35], v[48:49], 2, s[8:9]
	s_waitcnt lgkmcnt(0)
	v_add_f32_e32 v32, v32, v33
	global_atomic_add_f32 v[34:35], v32, off
; __device__ __forceinline__ u32x4 pack8(f32x4 a, f32x4 b) { u32x4 w; w.x = cvt_pk_bf16(a[0], a[1]); w.y = cvt_pk_bf16(a[2], a[3]); w.z = cvt_pk_bf16(b[0], b[1]); w.w = cvt_pk_bf16(b[2], b[3]); return w; }
;     __device__ __forceinline__ void operator()(const f32x4 (&acc)[2][2][4][2], const Unit& u, int wr, int wc, int fr, int fq) const {
;         const int row0 = u.pm * BM + wr * 64 + fr, col = u.pn * BM + wc * 64 + 8 * fq;
; #pragma unroll
;         for (int ai = 0; ai < 2; ++ai)
; #pragma unroll
;             for (int m = 0; m < 4; ++m) {
;                 const int row = row0 + ai * HALF + m * 16; const size_t off = (size_t)row * 2048 + col;
;                 float s = 0.f;
; #pragma unroll
;                 for (int bj = 0; bj < 2; ++bj) {
;                     f32x4 b0, b1;
;                     if (BASE_F32) { const float* bp = (const float*)base + off + bj * 32; b0 = *(const f32x4*)bp; b1 = *(const f32x4*)(bp + 4); }
;                     else { const u32x4 w = *(const u32x4*)((const bf16_t*)base + off + bj * 32);
;                         b0 = (f32x4){__uint_as_float(w.x << 16), __uint_as_float(w.x & 0xffff0000u), __uint_as_float(w.y << 16), __uint_as_float(w.y & 0xffff0000u)};
;                         b1 = (f32x4){__uint_as_float(w.z << 16), __uint_as_float(w.z & 0xffff0000u), __uint_as_float(w.w << 16), __uint_as_float(w.w & 0xffff0000u)}; }
;                     const f32x4 h0 = b0 + acc[ai][bj][m][0], h1 = b1 + acc[ai][bj][m][1];
;                     s += (h0[0] * h0[0] + h0[1] * h0[1]) + (h0[2] * h0[2] + h0[3] * h0[3]) + (h1[0] * h1[0] + h1[1] * h1[1]) + (h1[2] * h1[2] + h1[3] * h1[3]);
;                     *(u32x4*)(H + off + bj * 32) = pack8(h0, h1);
;                 }
;                 s += __shfl_xor(s, 16); s += __shfl_xor(s, 32);
;                 if (fq == 0) __hip_atomic_fetch_add(ss + row, s, __ATOMIC_RELAXED, __HIP_MEMORY_SCOPE_AGENT);
;                 if (m & 1) asm volatile("" ::: "memory");
;             }
.LBB0_343:
	s_or_b64 exec, exec, s[22:23]
	v_add_u32_e32 v32, 0xa0, v136
	s_waitcnt lgkmcnt(0)
	v_ashrrev_i32_e32 v33, 31, v32
	v_lshlrev_b64 v[34:35], 12, v[32:33]
	v_lshl_add_u64 v[34:35], s[6:7], 0, v[34:35]
	v_lshl_add_u64 v[38:39], v[134:135], 1, v[34:35]
	s_nop 1
	s_waitcnt vmcnt(14)
	v_mov_b32_e32 v34, v152
	v_mov_b32_e32 v35, v153
	v_mov_b32_e32 v36, v154
	v_mov_b32_e32 v37, v155
	s_nop 0
	v_lshlrev_b32_e32 v40, 16, v34
	v_and_b32_e32 v41, 0xffff0000, v34
	v_lshlrev_b32_e32 v34, 16, v35
	v_and_b32_e32 v35, 0xffff0000, v35
	v_lshlrev_b32_e32 v42, 16, v36
	v_and_b32_e32 v43, 0xffff0000, v36
	v_lshlrev_b32_e32 v36, 16, v37
	v_and_b32_e32 v37, 0xffff0000, v37
	v_pk_add_f32 v[34:35], v[30:31], v[34:35]
	v_pk_add_f32 v[40:41], v[28:29], v[40:41]
	v_pk_add_f32 v[36:37], v[26:27], v[36:37]
	v_pk_add_f32 v[42:43], v[24:25], v[42:43]
	v_cvt_pk_bf16_f32 v24, v40, v41
	v_cvt_pk_bf16_f32 v25, v34, v35
	v_mul_f32_e32 v41, v41, v41
	v_cvt_pk_bf16_f32 v26, v42, v43
	v_cvt_pk_bf16_f32 v27, v36, v37
	s_nop 1
	s_waitcnt vmcnt(13)
	v_mov_b32_e32 v28, v156
	v_mov_b32_e32 v29, v157
	v_mov_b32_e32 v30, v158
	v_mov_b32_e32 v31, v159
	v_mul_f32_e32 v35, v35, v35
	v_mul_f32_e32 v43, v43, v43
	v_fmac_f32_e32 v41, v40, v40
	v_fmac_f32_e32 v35, v34, v34
	v_mul_f32_e32 v37, v37, v37
	v_fmac_f32_e32 v43, v42, v42
	v_add_f32_e32 v34, v41, v35
	v_fmac_f32_e32 v37, v36, v36
	v_add_f32_e32 v34, v43, v34
	v_add_f32_e32 v40, v37, v34
	global_store_dwordx4 v[38:39], v[24:27], off
	s_nop 0
	v_lshlrev_b32_e32 v34, 16, v28
	v_and_b32_e32 v35, 0xffff0000, v28
	v_lshlrev_b32_e32 v28, 16, v29
	v_and_b32_e32 v29, 0xffff0000, v29
	v_lshlrev_b32_e32 v36, 16, v30
	v_and_b32_e32 v37, 0xffff0000, v30
	v_lshlrev_b32_e32 v30, 16, v31
	v_and_b32_e32 v31, 0xffff0000, v31
	v_pk_add_f32 v[22:23], v[22:23], v[28:29]
	v_pk_add_f32 v[20:21], v[20:21], v[34:35]
	v_pk_add_f32 v[28:29], v[18:19], v[30:31]
	v_pk_add_f32 v[30:31], v[16:17], v[36:37]
	v_mul_f32_e32 v16, v21, v21
	v_mul_f32_e32 v17, v23, v23
	v_mul_f32_e32 v18, v31, v31
	v_fmac_f32_e32 v16, v20, v20
	v_fmac_f32_e32 v17, v22, v22
	v_mul_f32_e32 v19, v29, v29
	v_fmac_f32_e32 v18, v30, v30
	v_add_f32_e32 v16, v16, v17
	v_add_f32_e32 v16, v18, v16
	v_fmac_f32_e32 v19, v28, v28
	v_add_f32_e32 v16, v19, v16
	v_add_f32_e32 v16, v40, v16
	ds_bpermute_b32 v17, v114, v16
	v_cvt_pk_bf16_f32 v18, v20, v21
	v_cvt_pk_bf16_f32 v19, v22, v23
	v_cvt_pk_bf16_f32 v20, v30, v31
	v_cvt_pk_bf16_f32 v21, v28, v29
	s_waitcnt lgkmcnt(0)
	v_add_f32_e32 v16, v16, v17
	ds_bpermute_b32 v17, v115, v16
	global_store_dwordx4 v[38:39], v[18:21], off offset:64
	s_and_saveexec_b64 s[22:23], s[2:3]
	s_cbranch_execz .LBB0_345
	v_lshl_add_u64 v[18:19], v[32:33], 2, s[8:9]
	s_waitcnt lgkmcnt(0)
	v_add_f32_e32 v16, v16, v17
	global_atomic_add_f32 v[18:19], v16, off
.LBB0_345:
	s_or_b64 exec, exec, s[22:23]
	v_add_u32_e32 v16, 0xb0, v136
	s_waitcnt lgkmcnt(0)
	v_ashrrev_i32_e32 v17, 31, v16
	v_lshlrev_b64 v[18:19], 12, v[16:17]
	v_lshl_add_u64 v[18:19], s[6:7], 0, v[18:19]
	v_lshl_add_u64 v[22:23], v[134:135], 1, v[18:19]
	s_nop 1
	s_waitcnt vmcnt(13)
	v_mov_b32_e32 v18, v160
	v_mov_b32_e32 v19, v161
	v_mov_b32_e32 v20, v162
	v_mov_b32_e32 v21, v163
	s_nop 0
	v_lshlrev_b32_e32 v24, 16, v18
	v_and_b32_e32 v25, 0xffff0000, v18
	v_lshlrev_b32_e32 v18, 16, v19
	v_and_b32_e32 v19, 0xffff0000, v19
	v_lshlrev_b32_e32 v26, 16, v20
	v_and_b32_e32 v27, 0xffff0000, v20
	v_lshlrev_b32_e32 v20, 16, v21
	v_and_b32_e32 v21, 0xffff0000, v21
	v_pk_add_f32 v[18:19], v[14:15], v[18:19]
	v_pk_add_f32 v[24:25], v[12:13], v[24:25]
	v_pk_add_f32 v[20:21], v[10:11], v[20:21]
	v_pk_add_f32 v[26:27], v[8:9], v[26:27]
	v_cvt_pk_bf16_f32 v8, v24, v25
	v_cvt_pk_bf16_f32 v9, v18, v19
	v_mul_f32_e32 v25, v25, v25
	v_cvt_pk_bf16_f32 v10, v26, v27
	v_cvt_pk_bf16_f32 v11, v20, v21
	s_nop 1
	s_waitcnt vmcnt(12)
	v_mov_b32_e32 v12, v164
	v_mov_b32_e32 v13, v165
	v_mov_b32_e32 v14, v166
	v_mov_b32_e32 v15, v167
	v_mul_f32_e32 v19, v19, v19
	v_mul_f32_e32 v27, v27, v27
	v_fmac_f32_e32 v25, v24, v24
	v_fmac_f32_e32 v19, v18, v18
	v_mul_f32_e32 v21, v21, v21
	v_fmac_f32_e32 v27, v26, v26
	v_add_f32_e32 v18, v25, v19
	v_fmac_f32_e32 v21, v20, v20
	v_add_f32_e32 v18, v27, v18
	v_add_f32_e32 v24, v21, v18
	global_store_dwordx4 v[22:23], v[8:11], off
	s_nop 0
	v_lshlrev_b32_e32 v18, 16, v12
	v_and_b32_e32 v19, 0xffff0000, v12
	v_lshlrev_b32_e32 v12, 16, v13
	v_and_b32_e32 v13, 0xffff0000, v13
	v_lshlrev_b32_e32 v20, 16, v14
	v_and_b32_e32 v21, 0xffff0000, v14
	v_lshlrev_b32_e32 v14, 16, v15
	v_and_b32_e32 v15, 0xffff0000, v15
	v_pk_add_f32 v[6:7], v[6:7], v[12:13]
	v_pk_add_f32 v[4:5], v[4:5], v[18:19]
	v_pk_add_f32 v[12:13], v[2:3], v[14:15]
	v_pk_add_f32 v[14:15], v[0:1], v[20:21]
	v_mul_f32_e32 v0, v5, v5
	v_mul_f32_e32 v1, v7, v7
	v_mul_f32_e32 v2, v15, v15
	v_fmac_f32_e32 v0, v4, v4
	v_fmac_f32_e32 v1, v6, v6
	v_mul_f32_e32 v3, v13, v13
	v_fmac_f32_e32 v2, v14, v14
	v_add_f32_e32 v0, v0, v1
	v_add_f32_e32 v0, v2, v0
	v_fmac_f32_e32 v3, v12, v12
	v_add_f32_e32 v0, v3, v0
	v_add_f32_e32 v0, v24, v0
	ds_bpermute_b32 v1, v114, v0
	v_cvt_pk_bf16_f32 v2, v4, v5
	v_cvt_pk_bf16_f32 v3, v6, v7
	v_cvt_pk_bf16_f32 v4, v14, v15
	v_cvt_pk_bf16_f32 v5, v12, v13
	s_waitcnt lgkmcnt(0)
	v_add_f32_e32 v0, v0, v1
	ds_bpermute_b32 v1, v115, v0
	global_store_dwordx4 v[22:23], v[2:5], off offset:64
	s_and_saveexec_b64 s[22:23], s[2:3]
	s_cbranch_execz .LBB0_347
	v_lshl_add_u64 v[2:3], v[16:17], 2, s[8:9]
	s_waitcnt lgkmcnt(0)
	v_add_f32_e32 v0, v0, v1
	global_atomic_add_f32 v[2:3], v0, off

; __device__ __forceinline__ u32x4 pack8(f32x4 a, f32x4 b) { u32x4 w; w.x = cvt_pk_bf16(a[0], a[1]); w.y = cvt_pk_bf16(a[2], a[3]); w.z = cvt_pk_bf16(b[0], b[1]); w.w = cvt_pk_bf16(b[2], b[3]); return w; }
;     __device__ __forceinline__ void operator()(const f32x4 (&acc)[2][2][4][2], const Unit& u, int wr, int wc, int fr, int fq) const {
;         const int row0 = u.pm * BM + wr * 64 + fr, col = u.pn * BM + wc * 64 + 8 * fq;
; #pragma unroll
;         for (int ai = 0; ai < 2; ++ai)
; #pragma unroll
;             for (int m = 0; m < 4; ++m) {
;                 const int row = row0 + ai * HALF + m * 16; const size_t off = (size_t)row * 2048 + col;
;                 float s = 0.f;
; #pragma unroll
;                 for (int bj = 0; bj < 2; ++bj) {
;                     f32x4 b0, b1;
;                     if (BASE_F32) { const float* bp = (const float*)base + off + bj * 32; b0 = *(const f32x4*)bp; b1 = *(const f32x4*)(bp + 4); }
;                     else { const u32x4 w = *(const u32x4*)((const bf16_t*)base + off + bj * 32);
;                         b0 = (f32x4){__uint_as_float(w.x << 16), __uint_as_float(w.x & 0xffff0000u), __uint_as_float(w.y << 16), __uint_as_float(w.y & 0xffff0000u)};
;                         b1 = (f32x4){__uint_as_float(w.z << 16), __uint_as_float(w.z & 0xffff0000u), __uint_as_float(w.w << 16), __uint_as_float(w.w & 0xffff0000u)}; }
;                     const f32x4 h0 = b0 + acc[ai][bj][m][0], h1 = b1 + acc[ai][bj][m][1];
;                     s += (h0[0] * h0[0] + h0[1] * h0[1]) + (h0[2] * h0[2] + h0[3] * h0[3]) + (h1[0] * h1[0] + h1[1] * h1[1]) + (h1[2] * h1[2] + h1[3] * h1[3]);
;                     *(u32x4*)(H + off + bj * 32) = pack8(h0, h1);
;                 }
;                 s += __shfl_xor(s, 16); s += __shfl_xor(s, 32);
;                 if (fq == 0) __hip_atomic_fetch_add(ss + row, s, __ATOMIC_RELAXED, __HIP_MEMORY_SCOPE_AGENT);
;                 if (m & 1) asm volatile("" ::: "memory");
;             }
.LBB0_620:
	v_lshl_add_u32 v136, s26, 8, v139
	v_ashrrev_i32_e32 v137, 31, v136
	v_lshl_or_b32 v134, s28, 8, v141
	v_lshlrev_b64 v[144:145], 12, v[136:137]
	v_ashrrev_i32_e32 v135, 31, v134
	v_lshl_add_u64 v[144:145], s[10:11], 0, v[144:145]
	v_lshl_add_u64 v[148:149], v[134:135], 1, v[144:145]
	v_mov_b32_e32 v170, v136
	v_ashrrev_i32_e32 v171, 31, v170
	v_lshlrev_b64 v[170:171], 12, v[170:171]
	v_lshl_add_u64 v[170:171], s[10:11], 0, v[170:171]
	v_lshl_add_u64 v[170:171], v[134:135], 1, v[170:171]
	global_load_dwordx4 v[154:157], v[170:171], off
	global_load_dwordx4 v[158:161], v[170:171], off offset:64
	v_add_u32_e32 v170, 0x10, v136
	v_ashrrev_i32_e32 v171, 31, v170
	v_lshlrev_b64 v[170:171], 12, v[170:171]
	v_lshl_add_u64 v[170:171], s[10:11], 0, v[170:171]
	v_lshl_add_u64 v[170:171], v[134:135], 1, v[170:171]
	global_load_dwordx4 v[162:165], v[170:171], off
	global_load_dwordx4 v[166:169], v[170:171], off offset:64
	v_add_u32_e32 v170, 0x20, v136
	v_ashrrev_i32_e32 v171, 31, v170
	v_lshlrev_b64 v[170:171], 12, v[170:171]
	v_lshl_add_u64 v[170:171], s[10:11], 0, v[170:171]
	v_lshl_add_u64 v[170:171], v[134:135], 1, v[170:171]
	global_load_dwordx4 v[182:185], v[170:171], off
	global_load_dwordx4 v[186:189], v[170:171], off offset:64
	v_add_u32_e32 v170, 0x30, v136
	v_ashrrev_i32_e32 v171, 31, v170
	v_lshlrev_b64 v[170:171], 12, v[170:171]
	v_lshl_add_u64 v[170:171], s[10:11], 0, v[170:171]
	v_lshl_add_u64 v[170:171], v[134:135], 1, v[170:171]
	global_load_dwordx4 v[190:193], v[170:171], off
	global_load_dwordx4 v[194:197], v[170:171], off offset:64
	v_add_u32_e32 v170, 0x80, v136
	v_ashrrev_i32_e32 v171, 31, v170
	v_lshlrev_b64 v[170:171], 12, v[170:171]
	v_lshl_add_u64 v[170:171], s[10:11], 0, v[170:171]
	v_lshl_add_u64 v[170:171], v[134:135], 1, v[170:171]
	global_load_dwordx4 v[198:201], v[170:171], off
	global_load_dwordx4 v[212:215], v[170:171], off offset:64
	v_add_u32_e32 v170, 0x90, v136
	v_ashrrev_i32_e32 v171, 31, v170
	v_lshlrev_b64 v[170:171], 12, v[170:171]
	v_lshl_add_u64 v[170:171], s[10:11], 0, v[170:171]
	v_lshl_add_u64 v[170:171], v[134:135], 1, v[170:171]
	global_load_dwordx4 v[216:219], v[170:171], off
	global_load_dwordx4 v[220:223], v[170:171], off offset:64
	s_nop 1
	s_waitcnt vmcnt(11)
	v_mov_b32_e32 v144, v154
	v_mov_b32_e32 v145, v155
	v_mov_b32_e32 v146, v156
	v_mov_b32_e32 v147, v157
	s_nop 0
	v_lshlrev_b32_e32 v150, 16, v144
	v_and_b32_e32 v151, 0xffff0000, v144
	v_lshlrev_b32_e32 v144, 16, v145
	v_and_b32_e32 v145, 0xffff0000, v145
	v_lshlrev_b32_e32 v152, 16, v146
	v_and_b32_e32 v153, 0xffff0000, v146
	v_lshlrev_b32_e32 v146, 16, v147
	v_and_b32_e32 v147, 0xffff0000, v147
	v_pk_add_f32 v[126:127], v[126:127], v[144:145]
	v_pk_add_f32 v[124:125], v[124:125], v[150:151]
	v_pk_add_f32 v[144:145], v[122:123], v[146:147]
	v_pk_add_f32 v[122:123], v[120:121], v[152:153]
	v_mul_f32_e32 v120, v125, v125
	v_mul_f32_e32 v121, v127, v127
	v_fmac_f32_e32 v120, v124, v124
	v_fmac_f32_e32 v121, v126, v126
	v_add_f32_e32 v120, v120, v121
	v_mul_f32_e32 v121, v123, v123
	v_fmac_f32_e32 v121, v122, v122
	v_add_f32_e32 v120, v121, v120
	v_mul_f32_e32 v121, v145, v145
	v_fmac_f32_e32 v121, v144, v144
	v_add_f32_e32 v143, v121, v120
	v_cvt_pk_bf16_f32 v120, v124, v125
	v_cvt_pk_bf16_f32 v121, v126, v127
	v_cvt_pk_bf16_f32 v122, v122, v123
	v_cvt_pk_bf16_f32 v123, v144, v145
	global_store_dwordx4 v[148:149], v[120:123], off
	s_nop 1
	s_waitcnt vmcnt(11)
	v_mov_b32_e32 v120, v158
	v_mov_b32_e32 v121, v159
	v_mov_b32_e32 v122, v160
	v_mov_b32_e32 v123, v161
	v_add_u32_e32 v170, 0xa0, v136
	v_ashrrev_i32_e32 v171, 31, v170
	v_lshlrev_b64 v[170:171], 12, v[170:171]
	v_lshl_add_u64 v[170:171], s[10:11], 0, v[170:171]
	v_lshl_add_u64 v[170:171], v[134:135], 1, v[170:171]
	global_load_dwordx4 v[154:157], v[170:171], off
	global_load_dwordx4 v[158:161], v[170:171], off offset:64
	s_nop 0
	v_lshlrev_b32_e32 v124, 16, v120
	v_and_b32_e32 v125, 0xffff0000, v120
	v_lshlrev_b32_e32 v120, 16, v121
	v_and_b32_e32 v121, 0xffff0000, v121
	v_lshlrev_b32_e32 v126, 16, v122
	v_and_b32_e32 v127, 0xffff0000, v122
	v_lshlrev_b32_e32 v122, 16, v123
	v_and_b32_e32 v123, 0xffff0000, v123
	v_pk_add_f32 v[118:119], v[118:119], v[120:121]
	v_pk_add_f32 v[116:117], v[116:117], v[124:125]
	v_pk_add_f32 v[120:121], v[114:115], v[122:123]
	v_pk_add_f32 v[114:115], v[112:113], v[126:127]
	v_mul_f32_e32 v112, v117, v117
	v_mul_f32_e32 v113, v119, v119
	v_fmac_f32_e32 v112, v116, v116
	v_fmac_f32_e32 v113, v118, v118
	v_add_f32_e32 v112, v112, v113
	v_mul_f32_e32 v113, v115, v115
	v_fmac_f32_e32 v113, v114, v114
	v_add_f32_e32 v112, v113, v112
	v_mul_f32_e32 v113, v121, v121
	v_fmac_f32_e32 v113, v120, v120
	v_add_f32_e32 v112, v113, v112
	v_add_f32_e32 v122, v143, v112
	v_cvt_pk_bf16_f32 v112, v116, v117
	v_cvt_pk_bf16_f32 v113, v118, v119
	v_cvt_pk_bf16_f32 v114, v114, v115
	v_cvt_pk_bf16_f32 v115, v120, v121
	global_store_dwordx4 v[148:149], v[112:115], off offset:64
	s_nop 1
	v_and_b32_e32 v113, 64, v209
	v_xor_b32_e32 v112, 16, v209
	v_add_u32_e32 v113, 64, v113
	v_cmp_lt_i32_e32 vcc, v112, v113
	v_xor_b32_e32 v115, 32, v209
	s_nop 0
	v_cndmask_b32_e32 v112, v209, v112, vcc
	v_lshlrev_b32_e32 v114, 2, v112
	ds_bpermute_b32 v112, v114, v122
	v_cmp_lt_i32_e32 vcc, v115, v113
	s_waitcnt lgkmcnt(0)
	v_add_f32_e32 v112, v122, v112
	v_cndmask_b32_e32 v113, v209, v115, vcc
	v_lshlrev_b32_e32 v115, 2, v113
	ds_bpermute_b32 v113, v115, v112
	s_and_saveexec_b64 s[26:27], s[2:3]
	s_cbranch_execz .LBB0_622
	v_lshl_add_u64 v[116:117], v[136:137], 2, s[12:13]
	s_waitcnt lgkmcnt(0)
	v_add_f32_e32 v112, v112, v113
	global_atomic_add_f32 v[116:117], v112, off
; __device__ __forceinline__ u32x4 pack8(f32x4 a, f32x4 b) { u32x4 w; w.x = cvt_pk_bf16(a[0], a[1]); w.y = cvt_pk_bf16(a[2], a[3]); w.z = cvt_pk_bf16(b[0], b[1]); w.w = cvt_pk_bf16(b[2], b[3]); return w; }
;     __device__ __forceinline__ void operator()(const f32x4 (&acc)[2][2][4][2], const Unit& u, int wr, int wc, int fr, int fq) const {
;         const int row0 = u.pm * BM + wr * 64 + fr, col = u.pn * BM + wc * 64 + 8 * fq;
; #pragma unroll
;         for (int ai = 0; ai < 2; ++ai)
; #pragma unroll
;             for (int m = 0; m < 4; ++m) {
;                 const int row = row0 + ai * HALF + m * 16; const size_t off = (size_t)row * 2048 + col;
;                 float s = 0.f;
; #pragma unroll
;                 for (int bj = 0; bj < 2; ++bj) {
;                     f32x4 b0, b1;
;                     if (BASE_F32) { const float* bp = (const float*)base + off + bj * 32; b0 = *(const f32x4*)bp; b1 = *(const f32x4*)(bp + 4); }
;                     else { const u32x4 w = *(const u32x4*)((const bf16_t*)base + off + bj * 32);
;                         b0 = (f32x4){__uint_as_float(w.x << 16), __uint_as_float(w.x & 0xffff0000u), __uint_as_float(w.y << 16), __uint_as_float(w.y & 0xffff0000u)};
;                         b1 = (f32x4){__uint_as_float(w.z << 16), __uint_as_float(w.z & 0xffff0000u), __uint_as_float(w.w << 16), __uint_as_float(w.w & 0xffff0000u)}; }
;                     const f32x4 h0 = b0 + acc[ai][bj][m][0], h1 = b1 + acc[ai][bj][m][1];
;                     s += (h0[0] * h0[0] + h0[1] * h0[1]) + (h0[2] * h0[2] + h0[3] * h0[3]) + (h1[0] * h1[0] + h1[1] * h1[1]) + (h1[2] * h1[2] + h1[3] * h1[3]);
;                     *(u32x4*)(H + off + bj * 32) = pack8(h0, h1);
;                 }
;                 s += __shfl_xor(s, 16); s += __shfl_xor(s, 32);
;                 if (fq == 0) __hip_atomic_fetch_add(ss + row, s, __ATOMIC_RELAXED, __HIP_MEMORY_SCOPE_AGENT);
;                 if (m & 1) asm volatile("" ::: "memory");
;             }
.LBB0_622:
	s_or_b64 exec, exec, s[26:27]
	v_or_b32_e32 v112, 16, v136
	s_waitcnt lgkmcnt(0)
	v_ashrrev_i32_e32 v113, 31, v112
	v_lshlrev_b64 v[116:117], 12, v[112:113]
	v_lshl_add_u64 v[116:117], s[10:11], 0, v[116:117]
	v_lshl_add_u64 v[120:121], v[134:135], 1, v[116:117]
	s_nop 1
	s_waitcnt vmcnt(13)
	v_mov_b32_e32 v116, v162
	v_mov_b32_e32 v117, v163
	v_mov_b32_e32 v118, v164
	v_mov_b32_e32 v119, v165
	s_nop 0
	v_lshlrev_b32_e32 v122, 16, v116
	v_and_b32_e32 v123, 0xffff0000, v116
	v_lshlrev_b32_e32 v116, 16, v117
	v_and_b32_e32 v117, 0xffff0000, v117
	v_lshlrev_b32_e32 v124, 16, v118
	v_and_b32_e32 v125, 0xffff0000, v118
	v_lshlrev_b32_e32 v118, 16, v119
	v_and_b32_e32 v119, 0xffff0000, v119
	v_pk_add_f32 v[116:117], v[110:111], v[116:117]
	v_pk_add_f32 v[122:123], v[108:109], v[122:123]
	v_pk_add_f32 v[118:119], v[106:107], v[118:119]
	v_pk_add_f32 v[124:125], v[104:105], v[124:125]
	v_cvt_pk_bf16_f32 v104, v122, v123
	v_cvt_pk_bf16_f32 v105, v116, v117
	v_mul_f32_e32 v123, v123, v123
	v_cvt_pk_bf16_f32 v106, v124, v125
	v_cvt_pk_bf16_f32 v107, v118, v119
	s_nop 1
	s_waitcnt vmcnt(12)
	v_mov_b32_e32 v108, v166
	v_mov_b32_e32 v109, v167
	v_mov_b32_e32 v110, v168
	v_mov_b32_e32 v111, v169
	v_add_u32_e32 v170, 0xb0, v136
	v_ashrrev_i32_e32 v171, 31, v170
	v_lshlrev_b64 v[170:171], 12, v[170:171]
	v_lshl_add_u64 v[170:171], s[10:11], 0, v[170:171]
	v_lshl_add_u64 v[170:171], v[134:135], 1, v[170:171]
	global_load_dwordx4 v[162:165], v[170:171], off
	global_load_dwordx4 v[166:169], v[170:171], off offset:64
	v_mul_f32_e32 v117, v117, v117
	v_mul_f32_e32 v125, v125, v125
	v_fmac_f32_e32 v123, v122, v122
	v_fmac_f32_e32 v117, v116, v116
	v_mul_f32_e32 v119, v119, v119
	v_fmac_f32_e32 v125, v124, v124
	v_add_f32_e32 v116, v123, v117
	v_fmac_f32_e32 v119, v118, v118
	v_add_f32_e32 v116, v125, v116
	v_add_f32_e32 v122, v119, v116
	global_store_dwordx4 v[120:121], v[104:107], off
	s_nop 0
	v_lshlrev_b32_e32 v116, 16, v108
	v_and_b32_e32 v117, 0xffff0000, v108
	v_lshlrev_b32_e32 v108, 16, v109
	v_and_b32_e32 v109, 0xffff0000, v109
	v_lshlrev_b32_e32 v118, 16, v110
	v_and_b32_e32 v119, 0xffff0000, v110
	v_lshlrev_b32_e32 v110, 16, v111
	v_and_b32_e32 v111, 0xffff0000, v111
	v_pk_add_f32 v[102:103], v[102:103], v[108:109]
	v_pk_add_f32 v[100:101], v[100:101], v[116:117]
	v_pk_add_f32 v[108:109], v[98:99], v[110:111]
	v_pk_add_f32 v[110:111], v[96:97], v[118:119]
	v_mul_f32_e32 v96, v101, v101
	v_mul_f32_e32 v97, v103, v103
	v_mul_f32_e32 v98, v111, v111
	v_fmac_f32_e32 v96, v100, v100
	v_fmac_f32_e32 v97, v102, v102
	v_mul_f32_e32 v99, v109, v109
	v_fmac_f32_e32 v98, v110, v110
	v_add_f32_e32 v96, v96, v97
	v_add_f32_e32 v96, v98, v96
	v_fmac_f32_e32 v99, v108, v108
	v_add_f32_e32 v96, v99, v96
	v_add_f32_e32 v96, v122, v96
	ds_bpermute_b32 v97, v114, v96
	v_cvt_pk_bf16_f32 v98, v100, v101
	v_cvt_pk_bf16_f32 v99, v102, v103
	v_cvt_pk_bf16_f32 v100, v110, v111
	v_cvt_pk_bf16_f32 v101, v108, v109
	s_waitcnt lgkmcnt(0)
	v_add_f32_e32 v96, v96, v97
	ds_bpermute_b32 v97, v115, v96
	global_store_dwordx4 v[120:121], v[98:101], off offset:64
	s_and_saveexec_b64 s[26:27], s[2:3]
	s_cbranch_execz .LBB0_624
	v_lshl_add_u64 v[98:99], v[112:113], 2, s[12:13]
	s_waitcnt lgkmcnt(0)
	v_add_f32_e32 v96, v96, v97
	global_atomic_add_f32 v[98:99], v96, off
.LBB0_624:
	s_or_b64 exec, exec, s[26:27]
	v_or_b32_e32 v96, 32, v136
	s_waitcnt lgkmcnt(0)
	v_ashrrev_i32_e32 v97, 31, v96
	v_lshlrev_b64 v[98:99], 12, v[96:97]
	v_lshl_add_u64 v[98:99], s[10:11], 0, v[98:99]
	v_lshl_add_u64 v[102:103], v[134:135], 1, v[98:99]
	s_nop 1
	s_waitcnt vmcnt(15)
	v_mov_b32_e32 v98, v182
	v_mov_b32_e32 v99, v183
	v_mov_b32_e32 v100, v184
	v_mov_b32_e32 v101, v185
	s_nop 0
	v_lshlrev_b32_e32 v104, 16, v98
	v_and_b32_e32 v105, 0xffff0000, v98
	v_lshlrev_b32_e32 v98, 16, v99
	v_and_b32_e32 v99, 0xffff0000, v99
	v_lshlrev_b32_e32 v106, 16, v100
	v_and_b32_e32 v107, 0xffff0000, v100
	v_lshlrev_b32_e32 v100, 16, v101
	v_and_b32_e32 v101, 0xffff0000, v101
	v_pk_add_f32 v[98:99], v[94:95], v[98:99]
	v_pk_add_f32 v[104:105], v[92:93], v[104:105]
	v_pk_add_f32 v[100:101], v[90:91], v[100:101]
	v_pk_add_f32 v[106:107], v[88:89], v[106:107]
	v_cvt_pk_bf16_f32 v88, v104, v105
	v_cvt_pk_bf16_f32 v89, v98, v99
	v_mul_f32_e32 v105, v105, v105
	v_cvt_pk_bf16_f32 v90, v106, v107
	v_cvt_pk_bf16_f32 v91, v100, v101
	s_nop 1
	s_waitcnt vmcnt(14)
	v_mov_b32_e32 v92, v186
	v_mov_b32_e32 v93, v187
	v_mov_b32_e32 v94, v188
	v_mov_b32_e32 v95, v189
	v_mul_f32_e32 v99, v99, v99
	v_mul_f32_e32 v107, v107, v107
	v_fmac_f32_e32 v105, v104, v104
	v_fmac_f32_e32 v99, v98, v98
	v_mul_f32_e32 v101, v101, v101
	v_fmac_f32_e32 v107, v106, v106
	v_add_f32_e32 v98, v105, v99
	v_fmac_f32_e32 v101, v100, v100
	v_add_f32_e32 v98, v107, v98
	v_add_f32_e32 v104, v101, v98
	global_store_dwordx4 v[102:103], v[88:91], off
	s_nop 0
	v_lshlrev_b32_e32 v98, 16, v92
	v_and_b32_e32 v99, 0xffff0000, v92
	v_lshlrev_b32_e32 v92, 16, v93
	v_and_b32_e32 v93, 0xffff0000, v93
	v_lshlrev_b32_e32 v100, 16, v94
	v_and_b32_e32 v101, 0xffff0000, v94
	v_lshlrev_b32_e32 v94, 16, v95
	v_and_b32_e32 v95, 0xffff0000, v95
	v_pk_add_f32 v[86:87], v[86:87], v[92:93]
	v_pk_add_f32 v[84:85], v[84:85], v[98:99]
	v_pk_add_f32 v[92:93], v[82:83], v[94:95]
	v_pk_add_f32 v[94:95], v[80:81], v[100:101]
	v_mul_f32_e32 v80, v85, v85
	v_mul_f32_e32 v81, v87, v87
	v_mul_f32_e32 v82, v95, v95
	v_fmac_f32_e32 v80, v84, v84
	v_fmac_f32_e32 v81, v86, v86
	v_mul_f32_e32 v83, v93, v93
	v_fmac_f32_e32 v82, v94, v94
	v_add_f32_e32 v80, v80, v81
	v_add_f32_e32 v80, v82, v80
	v_fmac_f32_e32 v83, v92, v92
	v_add_f32_e32 v80, v83, v80
	v_add_f32_e32 v80, v104, v80
	ds_bpermute_b32 v81, v114, v80
	v_cvt_pk_bf16_f32 v82, v84, v85
	v_cvt_pk_bf16_f32 v83, v86, v87
	v_cvt_pk_bf16_f32 v84, v94, v95
	v_cvt_pk_bf16_f32 v85, v92, v93
	s_waitcnt lgkmcnt(0)
	v_add_f32_e32 v80, v80, v81
	ds_bpermute_b32 v81, v115, v80
	global_store_dwordx4 v[102:103], v[82:85], off offset:64
	s_and_saveexec_b64 s[26:27], s[2:3]
	s_cbranch_execz .LBB0_626
	v_lshl_add_u64 v[82:83], v[96:97], 2, s[12:13]
	s_waitcnt lgkmcnt(0)
	v_add_f32_e32 v80, v80, v81
	global_atomic_add_f32 v[82:83], v80, off
; __device__ __forceinline__ u32x4 pack8(f32x4 a, f32x4 b) { u32x4 w; w.x = cvt_pk_bf16(a[0], a[1]); w.y = cvt_pk_bf16(a[2], a[3]); w.z = cvt_pk_bf16(b[0], b[1]); w.w = cvt_pk_bf16(b[2], b[3]); return w; }
;     __device__ __forceinline__ void operator()(const f32x4 (&acc)[2][2][4][2], const Unit& u, int wr, int wc, int fr, int fq) const {
;         const int row0 = u.pm * BM + wr * 64 + fr, col = u.pn * BM + wc * 64 + 8 * fq;
; #pragma unroll
;         for (int ai = 0; ai < 2; ++ai)
; #pragma unroll
;             for (int m = 0; m < 4; ++m) {
;                 const int row = row0 + ai * HALF + m * 16; const size_t off = (size_t)row * 2048 + col;
;                 float s = 0.f;
; #pragma unroll
;                 for (int bj = 0; bj < 2; ++bj) {
;                     f32x4 b0, b1;
;                     if (BASE_F32) { const float* bp = (const float*)base + off + bj * 32; b0 = *(const f32x4*)bp; b1 = *(const f32x4*)(bp + 4); }
;                     else { const u32x4 w = *(const u32x4*)((const bf16_t*)base + off + bj * 32);
;                         b0 = (f32x4){__uint_as_float(w.x << 16), __uint_as_float(w.x & 0xffff0000u), __uint_as_float(w.y << 16), __uint_as_float(w.y & 0xffff0000u)};
;                         b1 = (f32x4){__uint_as_float(w.z << 16), __uint_as_float(w.z & 0xffff0000u), __uint_as_float(w.w << 16), __uint_as_float(w.w & 0xffff0000u)}; }
;                     const f32x4 h0 = b0 + acc[ai][bj][m][0], h1 = b1 + acc[ai][bj][m][1];
;                     s += (h0[0] * h0[0] + h0[1] * h0[1]) + (h0[2] * h0[2] + h0[3] * h0[3]) + (h1[0] * h1[0] + h1[1] * h1[1]) + (h1[2] * h1[2] + h1[3] * h1[3]);
;                     *(u32x4*)(H + off + bj * 32) = pack8(h0, h1);
;                 }
;                 s += __shfl_xor(s, 16); s += __shfl_xor(s, 32);
;                 if (fq == 0) __hip_atomic_fetch_add(ss + row, s, __ATOMIC_RELAXED, __HIP_MEMORY_SCOPE_AGENT);
;                 if (m & 1) asm volatile("" ::: "memory");
;             }
.LBB0_626:
	s_or_b64 exec, exec, s[26:27]
	v_or_b32_e32 v80, 48, v136
	s_waitcnt lgkmcnt(0)
	v_ashrrev_i32_e32 v81, 31, v80
	v_lshlrev_b64 v[82:83], 12, v[80:81]
	v_lshl_add_u64 v[82:83], s[10:11], 0, v[82:83]
	v_lshl_add_u64 v[86:87], v[134:135], 1, v[82:83]
	s_nop 1
	s_waitcnt vmcnt(15)
	v_mov_b32_e32 v82, v190
	v_mov_b32_e32 v83, v191
	v_mov_b32_e32 v84, v192
	v_mov_b32_e32 v85, v193
	s_nop 0
	v_lshlrev_b32_e32 v88, 16, v82
	v_and_b32_e32 v89, 0xffff0000, v82
	v_lshlrev_b32_e32 v82, 16, v83
	v_and_b32_e32 v83, 0xffff0000, v83
	v_lshlrev_b32_e32 v90, 16, v84
	v_and_b32_e32 v91, 0xffff0000, v84
	v_lshlrev_b32_e32 v84, 16, v85
	v_and_b32_e32 v85, 0xffff0000, v85
	v_pk_add_f32 v[82:83], v[78:79], v[82:83]
	v_pk_add_f32 v[88:89], v[76:77], v[88:89]
	v_pk_add_f32 v[84:85], v[74:75], v[84:85]
	v_pk_add_f32 v[90:91], v[72:73], v[90:91]
	v_cvt_pk_bf16_f32 v72, v88, v89
	v_cvt_pk_bf16_f32 v73, v82, v83
	v_mul_f32_e32 v89, v89, v89
	v_cvt_pk_bf16_f32 v74, v90, v91
	v_cvt_pk_bf16_f32 v75, v84, v85
	s_nop 1
	s_waitcnt vmcnt(14)
	v_mov_b32_e32 v76, v194
	v_mov_b32_e32 v77, v195
	v_mov_b32_e32 v78, v196
	v_mov_b32_e32 v79, v197
	v_mul_f32_e32 v83, v83, v83
	v_mul_f32_e32 v91, v91, v91
	v_fmac_f32_e32 v89, v88, v88
	v_fmac_f32_e32 v83, v82, v82
	v_mul_f32_e32 v85, v85, v85
	v_fmac_f32_e32 v91, v90, v90
	v_add_f32_e32 v82, v89, v83
	v_fmac_f32_e32 v85, v84, v84
	v_add_f32_e32 v82, v91, v82
	v_add_f32_e32 v88, v85, v82
	global_store_dwordx4 v[86:87], v[72:75], off
	s_nop 0
	v_lshlrev_b32_e32 v82, 16, v76
	v_and_b32_e32 v83, 0xffff0000, v76
	v_lshlrev_b32_e32 v76, 16, v77
	v_and_b32_e32 v77, 0xffff0000, v77
	v_lshlrev_b32_e32 v84, 16, v78
	v_and_b32_e32 v85, 0xffff0000, v78
	v_lshlrev_b32_e32 v78, 16, v79
	v_and_b32_e32 v79, 0xffff0000, v79
	v_pk_add_f32 v[70:71], v[70:71], v[76:77]
	v_pk_add_f32 v[68:69], v[68:69], v[82:83]
	v_pk_add_f32 v[76:77], v[66:67], v[78:79]
	v_pk_add_f32 v[78:79], v[64:65], v[84:85]
	v_mul_f32_e32 v64, v69, v69
	v_mul_f32_e32 v65, v71, v71
	v_mul_f32_e32 v66, v79, v79
	v_fmac_f32_e32 v64, v68, v68
	v_fmac_f32_e32 v65, v70, v70
	v_mul_f32_e32 v67, v77, v77
	v_fmac_f32_e32 v66, v78, v78
	v_add_f32_e32 v64, v64, v65
	v_add_f32_e32 v64, v66, v64
	v_fmac_f32_e32 v67, v76, v76
	v_add_f32_e32 v64, v67, v64
	v_add_f32_e32 v64, v88, v64
	ds_bpermute_b32 v65, v114, v64
	v_cvt_pk_bf16_f32 v66, v68, v69
	v_cvt_pk_bf16_f32 v67, v70, v71
	v_cvt_pk_bf16_f32 v68, v78, v79
	v_cvt_pk_bf16_f32 v69, v76, v77
	s_waitcnt lgkmcnt(0)
	v_add_f32_e32 v64, v64, v65
	ds_bpermute_b32 v65, v115, v64
	global_store_dwordx4 v[86:87], v[66:69], off offset:64
	s_and_saveexec_b64 s[26:27], s[2:3]
	s_cbranch_execz .LBB0_628
	v_lshl_add_u64 v[66:67], v[80:81], 2, s[12:13]
	s_waitcnt lgkmcnt(0)
	v_add_f32_e32 v64, v64, v65
	global_atomic_add_f32 v[66:67], v64, off
.LBB0_628:
	s_or_b64 exec, exec, s[26:27]
	v_add_u32_e32 v64, 0x80, v136
	s_waitcnt lgkmcnt(0)
	v_ashrrev_i32_e32 v65, 31, v64
	v_lshlrev_b64 v[66:67], 12, v[64:65]
	v_lshl_add_u64 v[66:67], s[10:11], 0, v[66:67]
	v_lshl_add_u64 v[70:71], v[134:135], 1, v[66:67]
	s_nop 1
	s_waitcnt vmcnt(15)
	v_mov_b32_e32 v66, v198
	v_mov_b32_e32 v67, v199
	v_mov_b32_e32 v68, v200
	v_mov_b32_e32 v69, v201
	s_nop 0
	v_lshlrev_b32_e32 v72, 16, v66
	v_and_b32_e32 v73, 0xffff0000, v66
	v_lshlrev_b32_e32 v66, 16, v67
	v_and_b32_e32 v67, 0xffff0000, v67
	v_lshlrev_b32_e32 v74, 16, v68
	v_and_b32_e32 v75, 0xffff0000, v68
	v_lshlrev_b32_e32 v68, 16, v69
	v_and_b32_e32 v69, 0xffff0000, v69
	v_pk_add_f32 v[66:67], v[62:63], v[66:67]
	v_pk_add_f32 v[72:73], v[60:61], v[72:73]
	v_pk_add_f32 v[68:69], v[58:59], v[68:69]
	v_pk_add_f32 v[74:75], v[56:57], v[74:75]
	v_cvt_pk_bf16_f32 v56, v72, v73
	v_cvt_pk_bf16_f32 v57, v66, v67
	v_mul_f32_e32 v73, v73, v73
	v_cvt_pk_bf16_f32 v58, v74, v75
	v_cvt_pk_bf16_f32 v59, v68, v69
	s_nop 1
	s_waitcnt vmcnt(14)
	v_mov_b32_e32 v60, v212
	v_mov_b32_e32 v61, v213
	v_mov_b32_e32 v62, v214
	v_mov_b32_e32 v63, v215
	v_mul_f32_e32 v67, v67, v67
	v_mul_f32_e32 v75, v75, v75
	v_fmac_f32_e32 v73, v72, v72
	v_fmac_f32_e32 v67, v66, v66
	v_mul_f32_e32 v69, v69, v69
	v_fmac_f32_e32 v75, v74, v74
	v_add_f32_e32 v66, v73, v67
	v_fmac_f32_e32 v69, v68, v68
	v_add_f32_e32 v66, v75, v66
	v_add_f32_e32 v72, v69, v66
	global_store_dwordx4 v[70:71], v[56:59], off
	s_nop 0
	v_lshlrev_b32_e32 v66, 16, v60
	v_and_b32_e32 v67, 0xffff0000, v60
	v_lshlrev_b32_e32 v60, 16, v61
	v_and_b32_e32 v61, 0xffff0000, v61
	v_lshlrev_b32_e32 v68, 16, v62
	v_and_b32_e32 v69, 0xffff0000, v62
	v_lshlrev_b32_e32 v62, 16, v63
	v_and_b32_e32 v63, 0xffff0000, v63
	v_pk_add_f32 v[54:55], v[54:55], v[60:61]
	v_pk_add_f32 v[52:53], v[52:53], v[66:67]
	v_pk_add_f32 v[60:61], v[50:51], v[62:63]
	v_pk_add_f32 v[62:63], v[48:49], v[68:69]
	v_mul_f32_e32 v48, v53, v53
	v_mul_f32_e32 v49, v55, v55
	v_mul_f32_e32 v50, v63, v63
	v_fmac_f32_e32 v48, v52, v52
	v_fmac_f32_e32 v49, v54, v54
	v_mul_f32_e32 v51, v61, v61
	v_fmac_f32_e32 v50, v62, v62
	v_add_f32_e32 v48, v48, v49
	v_add_f32_e32 v48, v50, v48
	v_fmac_f32_e32 v51, v60, v60
	v_add_f32_e32 v48, v51, v48
	v_add_f32_e32 v48, v72, v48
	ds_bpermute_b32 v49, v114, v48
	v_cvt_pk_bf16_f32 v50, v52, v53
	v_cvt_pk_bf16_f32 v51, v54, v55
	v_cvt_pk_bf16_f32 v52, v62, v63
	v_cvt_pk_bf16_f32 v53, v60, v61
	s_waitcnt lgkmcnt(0)
	v_add_f32_e32 v48, v48, v49
	ds_bpermute_b32 v49, v115, v48
	global_store_dwordx4 v[70:71], v[50:53], off offset:64
	s_and_saveexec_b64 s[26:27], s[2:3]
	s_cbranch_execz .LBB0_630
	v_lshl_add_u64 v[50:51], v[64:65], 2, s[12:13]
	s_waitcnt lgkmcnt(0)
	v_add_f32_e32 v48, v48, v49
	global_atomic_add_f32 v[50:51], v48, off
; __device__ __forceinline__ u32x4 pack8(f32x4 a, f32x4 b) { u32x4 w; w.x = cvt_pk_bf16(a[0], a[1]); w.y = cvt_pk_bf16(a[2], a[3]); w.z = cvt_pk_bf16(b[0], b[1]); w.w = cvt_pk_bf16(b[2], b[3]); return w; }
;     __device__ __forceinline__ void operator()(const f32x4 (&acc)[2][2][4][2], const Unit& u, int wr, int wc, int fr, int fq) const {
;         const int row0 = u.pm * BM + wr * 64 + fr, col = u.pn * BM + wc * 64 + 8 * fq;
; #pragma unroll
;         for (int ai = 0; ai < 2; ++ai)
; #pragma unroll
;             for (int m = 0; m < 4; ++m) {
;                 const int row = row0 + ai * HALF + m * 16; const size_t off = (size_t)row * 2048 + col;
;                 float s = 0.f;
; #pragma unroll
;                 for (int bj = 0; bj < 2; ++bj) {
;                     f32x4 b0, b1;
;                     if (BASE_F32) { const float* bp = (const float*)base + off + bj * 32; b0 = *(const f32x4*)bp; b1 = *(const f32x4*)(bp + 4); }
;                     else { const u32x4 w = *(const u32x4*)((const bf16_t*)base + off + bj * 32);
;                         b0 = (f32x4){__uint_as_float(w.x << 16), __uint_as_float(w.x & 0xffff0000u), __uint_as_float(w.y << 16), __uint_as_float(w.y & 0xffff0000u)};
;                         b1 = (f32x4){__uint_as_float(w.z << 16), __uint_as_float(w.z & 0xffff0000u), __uint_as_float(w.w << 16), __uint_as_float(w.w & 0xffff0000u)}; }
;                     const f32x4 h0 = b0 + acc[ai][bj][m][0], h1 = b1 + acc[ai][bj][m][1];
;                     s += (h0[0] * h0[0] + h0[1] * h0[1]) + (h0[2] * h0[2] + h0[3] * h0[3]) + (h1[0] * h1[0] + h1[1] * h1[1]) + (h1[2] * h1[2] + h1[3] * h1[3]);
;                     *(u32x4*)(H + off + bj * 32) = pack8(h0, h1);
;                 }
;                 s += __shfl_xor(s, 16); s += __shfl_xor(s, 32);
;                 if (fq == 0) __hip_atomic_fetch_add(ss + row, s, __ATOMIC_RELAXED, __HIP_MEMORY_SCOPE_AGENT);
;                 if (m & 1) asm volatile("" ::: "memory");
;             }
.LBB0_630:
	s_or_b64 exec, exec, s[26:27]
	v_add_u32_e32 v48, 0x90, v136
	s_waitcnt lgkmcnt(0)
	v_ashrrev_i32_e32 v49, 31, v48
	v_lshlrev_b64 v[50:51], 12, v[48:49]
	v_lshl_add_u64 v[50:51], s[10:11], 0, v[50:51]
	v_lshl_add_u64 v[54:55], v[134:135], 1, v[50:51]
	s_nop 1
	s_waitcnt vmcnt(15)
	v_mov_b32_e32 v50, v216
	v_mov_b32_e32 v51, v217
	v_mov_b32_e32 v52, v218
	v_mov_b32_e32 v53, v219
	s_nop 0
	v_lshlrev_b32_e32 v56, 16, v50
	v_and_b32_e32 v57, 0xffff0000, v50
	v_lshlrev_b32_e32 v50, 16, v51
	v_and_b32_e32 v51, 0xffff0000, v51
	v_lshlrev_b32_e32 v58, 16, v52
	v_and_b32_e32 v59, 0xffff0000, v52
	v_lshlrev_b32_e32 v52, 16, v53
	v_and_b32_e32 v53, 0xffff0000, v53
	v_pk_add_f32 v[50:51], v[46:47], v[50:51]
	v_pk_add_f32 v[56:57], v[44:45], v[56:57]
	v_pk_add_f32 v[52:53], v[42:43], v[52:53]
	v_pk_add_f32 v[58:59], v[40:41], v[58:59]
	v_cvt_pk_bf16_f32 v40, v56, v57
	v_cvt_pk_bf16_f32 v41, v50, v51
	v_mul_f32_e32 v57, v57, v57
	v_cvt_pk_bf16_f32 v42, v58, v59
	v_cvt_pk_bf16_f32 v43, v52, v53
	s_nop 1
	s_waitcnt vmcnt(14)
	v_mov_b32_e32 v44, v220
	v_mov_b32_e32 v45, v221
	v_mov_b32_e32 v46, v222
	v_mov_b32_e32 v47, v223
	v_mul_f32_e32 v51, v51, v51
	v_mul_f32_e32 v59, v59, v59
	v_fmac_f32_e32 v57, v56, v56
	v_fmac_f32_e32 v51, v50, v50
	v_mul_f32_e32 v53, v53, v53
	v_fmac_f32_e32 v59, v58, v58
	v_add_f32_e32 v50, v57, v51
	v_fmac_f32_e32 v53, v52, v52
	v_add_f32_e32 v50, v59, v50
	v_add_f32_e32 v56, v53, v50
	global_store_dwordx4 v[54:55], v[40:43], off
	s_nop 0
	v_lshlrev_b32_e32 v50, 16, v44
	v_and_b32_e32 v51, 0xffff0000, v44
	v_lshlrev_b32_e32 v44, 16, v45
	v_and_b32_e32 v45, 0xffff0000, v45
	v_lshlrev_b32_e32 v52, 16, v46
	v_and_b32_e32 v53, 0xffff0000, v46
	v_lshlrev_b32_e32 v46, 16, v47
	v_and_b32_e32 v47, 0xffff0000, v47
	v_pk_add_f32 v[38:39], v[38:39], v[44:45]
	v_pk_add_f32 v[36:37], v[36:37], v[50:51]
	v_pk_add_f32 v[44:45], v[34:35], v[46:47]
	v_pk_add_f32 v[46:47], v[32:33], v[52:53]
	v_mul_f32_e32 v32, v37, v37
	v_mul_f32_e32 v33, v39, v39
	v_mul_f32_e32 v34, v47, v47
	v_fmac_f32_e32 v32, v36, v36
	v_fmac_f32_e32 v33, v38, v38
	v_mul_f32_e32 v35, v45, v45
	v_fmac_f32_e32 v34, v46, v46
	v_add_f32_e32 v32, v32, v33
	v_add_f32_e32 v32, v34, v32
	v_fmac_f32_e32 v35, v44, v44
	v_add_f32_e32 v32, v35, v32
	v_add_f32_e32 v32, v56, v32
	ds_bpermute_b32 v33, v114, v32
	v_cvt_pk_bf16_f32 v34, v36, v37
	v_cvt_pk_bf16_f32 v35, v38, v39
	v_cvt_pk_bf16_f32 v36, v46, v47
	v_cvt_pk_bf16_f32 v37, v44, v45
	s_waitcnt lgkmcnt(0)
	v_add_f32_e32 v32, v32, v33
	ds_bpermute_b32 v33, v115, v32
	global_store_dwordx4 v[54:55], v[34:37], off offset:64
	s_and_saveexec_b64 s[26:27], s[2:3]
	s_cbranch_execz .LBB0_632
	v_lshl_add_u64 v[34:35], v[48:49], 2, s[12:13]
	s_waitcnt lgkmcnt(0)
	v_add_f32_e32 v32, v32, v33
	global_atomic_add_f32 v[34:35], v32, off
; __device__ __forceinline__ u32x4 pack8(f32x4 a, f32x4 b) { u32x4 w; w.x = cvt_pk_bf16(a[0], a[1]); w.y = cvt_pk_bf16(a[2], a[3]); w.z = cvt_pk_bf16(b[0], b[1]); w.w = cvt_pk_bf16(b[2], b[3]); return w; }
;     __device__ __forceinline__ void operator()(const f32x4 (&acc)[2][2][4][2], const Unit& u, int wr, int wc, int fr, int fq) const {
;         const int row0 = u.pm * BM + wr * 64 + fr, col = u.pn * BM + wc * 64 + 8 * fq;
; #pragma unroll
;         for (int ai = 0; ai < 2; ++ai)
; #pragma unroll
;             for (int m = 0; m < 4; ++m) {
;                 const int row = row0 + ai * HALF + m * 16; const size_t off = (size_t)row * 2048 + col;
;                 float s = 0.f;
; #pragma unroll
;                 for (int bj = 0; bj < 2; ++bj) {
;                     f32x4 b0, b1;
;                     if (BASE_F32) { const float* bp = (const float*)base + off + bj * 32; b0 = *(const f32x4*)bp; b1 = *(const f32x4*)(bp + 4); }
;                     else { const u32x4 w = *(const u32x4*)((const bf16_t*)base + off + bj * 32);
;                         b0 = (f32x4){__uint_as_float(w.x << 16), __uint_as_float(w.x & 0xffff0000u), __uint_as_float(w.y << 16), __uint_as_float(w.y & 0xffff0000u)};
;                         b1 = (f32x4){__uint_as_float(w.z << 16), __uint_as_float(w.z & 0xffff0000u), __uint_as_float(w.w << 16), __uint_as_float(w.w & 0xffff0000u)}; }
;                     const f32x4 h0 = b0 + acc[ai][bj][m][0], h1 = b1 + acc[ai][bj][m][1];
;                     s += (h0[0] * h0[0] + h0[1] * h0[1]) + (h0[2] * h0[2] + h0[3] * h0[3]) + (h1[0] * h1[0] + h1[1] * h1[1]) + (h1[2] * h1[2] + h1[3] * h1[3]);
;                     *(u32x4*)(H + off + bj * 32) = pack8(h0, h1);
;                 }
;                 s += __shfl_xor(s, 16); s += __shfl_xor(s, 32);
;                 if (fq == 0) __hip_atomic_fetch_add(ss + row, s, __ATOMIC_RELAXED, __HIP_MEMORY_SCOPE_AGENT);
;                 if (m & 1) asm volatile("" ::: "memory");
;             }
.LBB0_632:
	s_or_b64 exec, exec, s[26:27]
	v_add_u32_e32 v32, 0xa0, v136
	s_waitcnt lgkmcnt(0)
	v_ashrrev_i32_e32 v33, 31, v32
	v_lshlrev_b64 v[34:35], 12, v[32:33]
	v_lshl_add_u64 v[34:35], s[10:11], 0, v[34:35]
	v_lshl_add_u64 v[38:39], v[134:135], 1, v[34:35]
	s_nop 1
	s_waitcnt vmcnt(14)
	v_mov_b32_e32 v34, v154
	v_mov_b32_e32 v35, v155
	v_mov_b32_e32 v36, v156
	v_mov_b32_e32 v37, v157
	s_nop 0
	v_lshlrev_b32_e32 v40, 16, v34
	v_and_b32_e32 v41, 0xffff0000, v34
	v_lshlrev_b32_e32 v34, 16, v35
	v_and_b32_e32 v35, 0xffff0000, v35
	v_lshlrev_b32_e32 v42, 16, v36
	v_and_b32_e32 v43, 0xffff0000, v36
	v_lshlrev_b32_e32 v36, 16, v37
	v_and_b32_e32 v37, 0xffff0000, v37
	v_pk_add_f32 v[34:35], v[30:31], v[34:35]
	v_pk_add_f32 v[40:41], v[28:29], v[40:41]
	v_pk_add_f32 v[36:37], v[26:27], v[36:37]
	v_pk_add_f32 v[42:43], v[24:25], v[42:43]
	v_cvt_pk_bf16_f32 v24, v40, v41
	v_cvt_pk_bf16_f32 v25, v34, v35
	v_mul_f32_e32 v41, v41, v41
	v_cvt_pk_bf16_f32 v26, v42, v43
	v_cvt_pk_bf16_f32 v27, v36, v37
	s_nop 1
	s_waitcnt vmcnt(13)
	v_mov_b32_e32 v28, v158
	v_mov_b32_e32 v29, v159
	v_mov_b32_e32 v30, v160
	v_mov_b32_e32 v31, v161
	v_mul_f32_e32 v35, v35, v35
	v_mul_f32_e32 v43, v43, v43
	v_fmac_f32_e32 v41, v40, v40
	v_fmac_f32_e32 v35, v34, v34
	v_mul_f32_e32 v37, v37, v37
	v_fmac_f32_e32 v43, v42, v42
	v_add_f32_e32 v34, v41, v35
	v_fmac_f32_e32 v37, v36, v36
	v_add_f32_e32 v34, v43, v34
	v_add_f32_e32 v40, v37, v34
	global_store_dwordx4 v[38:39], v[24:27], off
	s_nop 0
	v_lshlrev_b32_e32 v34, 16, v28
	v_and_b32_e32 v35, 0xffff0000, v28
	v_lshlrev_b32_e32 v28, 16, v29
	v_and_b32_e32 v29, 0xffff0000, v29
	v_lshlrev_b32_e32 v36, 16, v30
	v_and_b32_e32 v37, 0xffff0000, v30
	v_lshlrev_b32_e32 v30, 16, v31
	v_and_b32_e32 v31, 0xffff0000, v31
	v_pk_add_f32 v[22:23], v[22:23], v[28:29]
	v_pk_add_f32 v[20:21], v[20:21], v[34:35]
	v_pk_add_f32 v[28:29], v[18:19], v[30:31]
	v_pk_add_f32 v[30:31], v[16:17], v[36:37]
	v_mul_f32_e32 v16, v21, v21
	v_mul_f32_e32 v17, v23, v23
	v_mul_f32_e32 v18, v31, v31
	v_fmac_f32_e32 v16, v20, v20
	v_fmac_f32_e32 v17, v22, v22
	v_mul_f32_e32 v19, v29, v29
	v_fmac_f32_e32 v18, v30, v30
	v_add_f32_e32 v16, v16, v17
	v_add_f32_e32 v16, v18, v16
	v_fmac_f32_e32 v19, v28, v28
	v_add_f32_e32 v16, v19, v16
	v_add_f32_e32 v16, v40, v16
	ds_bpermute_b32 v17, v114, v16
	v_cvt_pk_bf16_f32 v18, v20, v21
	v_cvt_pk_bf16_f32 v19, v22, v23
	v_cvt_pk_bf16_f32 v20, v30, v31
	v_cvt_pk_bf16_f32 v21, v28, v29
	s_waitcnt lgkmcnt(0)
	v_add_f32_e32 v16, v16, v17
	ds_bpermute_b32 v17, v115, v16
	global_store_dwordx4 v[38:39], v[18:21], off offset:64
	s_and_saveexec_b64 s[26:27], s[2:3]
	s_cbranch_execz .LBB0_634
	v_lshl_add_u64 v[18:19], v[32:33], 2, s[12:13]
	s_waitcnt lgkmcnt(0)
	v_add_f32_e32 v16, v16, v17
	global_atomic_add_f32 v[18:19], v16, off
.LBB0_634:
	s_or_b64 exec, exec, s[26:27]
	v_add_u32_e32 v16, 0xb0, v136
	s_waitcnt lgkmcnt(0)
	v_ashrrev_i32_e32 v17, 31, v16
	v_lshlrev_b64 v[18:19], 12, v[16:17]
	v_lshl_add_u64 v[18:19], s[10:11], 0, v[18:19]
	v_lshl_add_u64 v[22:23], v[134:135], 1, v[18:19]
	s_nop 1
	s_waitcnt vmcnt(13)
	v_mov_b32_e32 v18, v162
	v_mov_b32_e32 v19, v163
	v_mov_b32_e32 v20, v164
	v_mov_b32_e32 v21, v165
	s_nop 0
	v_lshlrev_b32_e32 v24, 16, v18
	v_and_b32_e32 v25, 0xffff0000, v18
	v_lshlrev_b32_e32 v18, 16, v19
	v_and_b32_e32 v19, 0xffff0000, v19
	v_lshlrev_b32_e32 v26, 16, v20
	v_and_b32_e32 v27, 0xffff0000, v20
	v_lshlrev_b32_e32 v20, 16, v21
	v_and_b32_e32 v21, 0xffff0000, v21
	v_pk_add_f32 v[18:19], v[14:15], v[18:19]
	v_pk_add_f32 v[24:25], v[12:13], v[24:25]
	v_pk_add_f32 v[20:21], v[10:11], v[20:21]
	v_pk_add_f32 v[26:27], v[8:9], v[26:27]
	v_cvt_pk_bf16_f32 v8, v24, v25
	v_cvt_pk_bf16_f32 v9, v18, v19
	v_mul_f32_e32 v25, v25, v25
	v_cvt_pk_bf16_f32 v10, v26, v27
	v_cvt_pk_bf16_f32 v11, v20, v21
	s_nop 1
	s_waitcnt vmcnt(12)
	v_mov_b32_e32 v12, v166
	v_mov_b32_e32 v13, v167
	v_mov_b32_e32 v14, v168
	v_mov_b32_e32 v15, v169
	v_mul_f32_e32 v19, v19, v19
	v_mul_f32_e32 v27, v27, v27
	v_fmac_f32_e32 v25, v24, v24
	v_fmac_f32_e32 v19, v18, v18
	v_mul_f32_e32 v21, v21, v21
	v_fmac_f32_e32 v27, v26, v26
	v_add_f32_e32 v18, v25, v19
	v_fmac_f32_e32 v21, v20, v20
	v_add_f32_e32 v18, v27, v18
	v_add_f32_e32 v24, v21, v18
	global_store_dwordx4 v[22:23], v[8:11], off
	s_nop 0
	v_lshlrev_b32_e32 v18, 16, v12
	v_and_b32_e32 v19, 0xffff0000, v12
	v_lshlrev_b32_e32 v12, 16, v13
	v_and_b32_e32 v13, 0xffff0000, v13
	v_lshlrev_b32_e32 v20, 16, v14
	v_and_b32_e32 v21, 0xffff0000, v14
	v_lshlrev_b32_e32 v14, 16, v15
	v_and_b32_e32 v15, 0xffff0000, v15
	v_pk_add_f32 v[6:7], v[6:7], v[12:13]
	v_pk_add_f32 v[4:5], v[4:5], v[18:19]
	v_pk_add_f32 v[12:13], v[2:3], v[14:15]
	v_pk_add_f32 v[14:15], v[0:1], v[20:21]
	v_mul_f32_e32 v0, v5, v5
	v_mul_f32_e32 v1, v7, v7
	v_mul_f32_e32 v2, v15, v15
	v_fmac_f32_e32 v0, v4, v4
	v_fmac_f32_e32 v1, v6, v6
	v_mul_f32_e32 v3, v13, v13
	v_fmac_f32_e32 v2, v14, v14
	v_add_f32_e32 v0, v0, v1
	v_add_f32_e32 v0, v2, v0
	v_fmac_f32_e32 v3, v12, v12
	v_add_f32_e32 v0, v3, v0
	v_add_f32_e32 v0, v24, v0
	ds_bpermute_b32 v1, v114, v0
	v_cvt_pk_bf16_f32 v2, v4, v5
	v_cvt_pk_bf16_f32 v3, v6, v7
	v_cvt_pk_bf16_f32 v4, v14, v15
	v_cvt_pk_bf16_f32 v5, v12, v13
	s_waitcnt lgkmcnt(0)
	v_add_f32_e32 v0, v0, v1
	ds_bpermute_b32 v1, v115, v0
	global_store_dwordx4 v[22:23], v[2:5], off offset:64
	s_and_saveexec_b64 s[26:27], s[2:3]
	s_cbranch_execz .LBB0_636
	v_lshl_add_u64 v[2:3], v[16:17], 2, s[12:13]
	s_waitcnt lgkmcnt(0)
	v_add_f32_e32 v0, v0, v1
	global_atomic_add_f32 v[2:3], v0, off

; #define PG8_BAR __builtin_amdgcn_s_barrier()
; __device__ __forceinline__ u32x4 pack8(f32x4 a, f32x4 b) { u32x4 w; w.x = cvt_pk_bf16(a[0], a[1]); w.y = cvt_pk_bf16(a[2], a[3]); w.z = cvt_pk_bf16(b[0], b[1]); w.w = cvt_pk_bf16(b[2], b[3]); return w; }
; __device__ __forceinline__ float rs_of(const float* ss, int row) { return 1.0f / sqrtf(ss[row] * (1.0f / 2048.0f) + 1e-5f); }
; template <class Epi, class Sched, bool ALIGN_EPI = false, bool SP2 = false>
; __device__ __forceinline__ void gemm_phase(PG8_LAS unsigned char* lds, const Gemm g, const Sched& S, const Epi& E) {
;     ...
;         if constexpr (ALIGN_EPI) { if (wr == 0) PG8_BAR; }
;     __device__ __forceinline__ void operator()(const f32x4 (&acc)[2][2][4][2], const Unit& u, int wr, int wc, int fr, int fq) const {
;         const int row0 = u.pm * BM + wr * 64 + fr;
;         const bool hb = (fr & 8) != 0;
;         const int srow0 = u.pm * BM + wr * 64 + (fr & 7), scol = u.pn * BM + wc * 64 + (hb ? 32 : 0) + 8 * fq;
;         const f32x4 z = {0.f, 0.f, 0.f, 0.f};
; #pragma unroll
;         for (int ai = 0; ai < 2; ++ai)
; #pragma unroll
;             for (int m = 0; m < 4; ++m) {
;                 const int row = row0 + ai * HALF + m * 16; const float rr = ss ? rs_of(ss, row) : 1.0f;
;                 u32x4 v[2];
; #pragma unroll
;                 for (int bj = 0; bj < 2; ++bj) {
;                     f32x4 a = __builtin_elementwise_max(acc[ai][bj][m][0], z) * rr, b = __builtin_elementwise_max(acc[ai][bj][m][1], z) * rr;
;                     v[bj] = pack8(a * a, b * b);
.LBB0_715:
	s_lshl_b32 s0, s0, 8
	s_add_i32 s0, s0, s62
	v_or_b32_e32 v134, s0, v142
	v_ashrrev_i32_e32 v135, 31, v134
	v_lshl_add_u64 v[134:135], v[134:135], 2, s[12:13]
	global_load_dword v160, v[134:135], off
	global_load_dword v161, v[134:135], off offset:64
	global_load_dword v162, v[134:135], off offset:128
	global_load_dword v163, v[134:135], off offset:192
	global_load_dword v164, v[134:135], off offset:512
	global_load_dword v165, v[134:135], off offset:576
	global_load_dword v166, v[134:135], off offset:640
	global_load_dword v167, v[134:135], off offset:704
	s_and_b64 vcc, exec, s[14:15]
	s_cbranch_vccz .LBB0_717
	s_barrier
.LBB0_717:
	v_or_b32_e32 v136, s0, v144
	v_lshl_or_b32 v138, s1, 8, v145
	v_max_f32_e32 v127, v127, v127
	v_max_f32_e32 v126, v126, v126
	v_max_f32_e32 v125, v125, v125
	v_max_f32_e32 v124, v124, v124
	v_max_f32_e32 v123, v123, v123
	v_max_f32_e32 v122, v122, v122
	v_max_f32_e32 v121, v121, v121
	v_max_f32_e32 v120, v120, v120
	v_max_f32_e32 v115, v115, v115
	v_max_f32_e32 v114, v114, v114
	v_max_f32_e32 v113, v113, v113
	v_max_f32_e32 v112, v112, v112
	v_max_f32_e32 v127, 0, v127
	v_max_f32_e32 v126, 0, v126
	v_max_f32_e32 v125, 0, v125
	v_max_f32_e32 v124, 0, v124
	v_max_f32_e32 v123, 0, v123
	v_max_f32_e32 v122, 0, v122
	v_max_f32_e32 v121, 0, v121
	v_max_f32_e32 v120, 0, v120
	v_max_f32_e32 v119, v119, v119
	v_max_f32_e32 v118, v118, v118
	v_max_f32_e32 v117, v117, v117
	v_max_f32_e32 v116, v116, v116
	v_max_f32_e32 v115, 0, v115
	v_max_f32_e32 v114, 0, v114
	v_max_f32_e32 v113, 0, v113
	v_max_f32_e32 v112, 0, v112
	v_max_f32_e32 v119, 0, v119
	v_max_f32_e32 v118, 0, v118
	v_max_f32_e32 v117, 0, v117
	v_max_f32_e32 v116, 0, v116
	v_ashrrev_i32_e32 v139, 31, v138
	v_max_f32_e32 v111, v111, v111
	v_max_f32_e32 v110, v110, v110
	v_max_f32_e32 v109, v109, v109
	v_max_f32_e32 v108, v108, v108
	v_max_f32_e32 v107, v107, v107
	v_max_f32_e32 v106, v106, v106
	v_max_f32_e32 v105, v105, v105
	v_max_f32_e32 v104, v104, v104
	v_max_f32_e32 v97, v97, v97
	v_max_f32_e32 v96, v96, v96
	v_max_f32_e32 v111, 0, v111
	v_max_f32_e32 v110, 0, v110
	v_max_f32_e32 v109, 0, v109
	v_max_f32_e32 v108, 0, v108
	v_max_f32_e32 v107, 0, v107
	v_max_f32_e32 v106, 0, v106
	v_max_f32_e32 v105, 0, v105
	v_max_f32_e32 v104, 0, v104
	v_max_f32_e32 v103, v103, v103
	v_max_f32_e32 v102, v102, v102
	v_max_f32_e32 v101, v101, v101
	v_max_f32_e32 v100, v100, v100
	v_max_f32_e32 v99, v99, v99
	v_max_f32_e32 v98, v98, v98
	v_max_f32_e32 v97, 0, v97
	v_max_f32_e32 v96, 0, v96
	v_max_f32_e32 v103, 0, v103
	v_max_f32_e32 v102, 0, v102
	v_max_f32_e32 v101, 0, v101
	v_max_f32_e32 v100, 0, v100
	v_max_f32_e32 v99, 0, v99
	v_max_f32_e32 v98, 0, v98
	v_max_f32_e32 v95, v95, v95
	v_max_f32_e32 v94, v94, v94
	v_max_f32_e32 v93, v93, v93
	v_max_f32_e32 v92, v92, v92
	v_max_f32_e32 v91, v91, v91
	v_max_f32_e32 v90, v90, v90
	v_max_f32_e32 v89, v89, v89
	v_max_f32_e32 v88, v88, v88
	v_max_f32_e32 v81, v81, v81
	v_max_f32_e32 v80, v80, v80
	v_max_f32_e32 v95, 0, v95
	v_max_f32_e32 v94, 0, v94
	s_waitcnt vmcnt(7)
	v_fmamk_f32 v137, v160, 0x3a000000, v205
	v_cmp_gt_f32_e32 vcc, s83, v137
	v_mul_f32_e32 v140, 0x4f800000, v137
	v_max_f32_e32 v93, 0, v93
	v_cndmask_b32_e32 v137, v137, v140, vcc
	v_sqrt_f32_e32 v140, v137
	v_max_f32_e32 v92, 0, v92
	v_max_f32_e32 v91, 0, v91
	v_max_f32_e32 v90, 0, v90
	v_add_u32_e32 v147, -1, v140
	v_fma_f32 v148, -v147, v140, v137
	v_cmp_ge_f32_e64 s[0:1], 0, v148
	v_add_u32_e32 v148, 1, v140
	v_max_f32_e32 v89, 0, v89
	v_cndmask_b32_e64 v147, v140, v147, s[0:1]
	v_fma_f32 v140, -v148, v140, v137
	v_cmp_lt_f32_e64 s[0:1], 0, v140
	v_max_f32_e32 v88, 0, v88
	v_max_f32_e32 v87, v87, v87
	v_cndmask_b32_e64 v140, v147, v148, s[0:1]
	v_mul_f32_e32 v147, 0x37800000, v140
	v_cndmask_b32_e32 v140, v140, v147, vcc
	v_cmp_class_f32_e32 vcc, v137, v206
	v_max_f32_e32 v86, v86, v86
	v_max_f32_e32 v85, v85, v85
	v_cndmask_b32_e32 v137, v140, v137, vcc
	v_div_scale_f32 v140, s[0:1], v137, v137, 1.0
	v_rcp_f32_e32 v147, v140
	v_max_f32_e32 v84, v84, v84
	v_max_f32_e32 v83, v83, v83
	v_max_f32_e32 v82, v82, v82
	v_fma_f32 v148, -v140, v147, 1.0
	v_fmac_f32_e32 v147, v148, v147
	v_div_scale_f32 v148, vcc, 1.0, v137, 1.0
	v_mul_f32_e32 v149, v148, v147
	v_fma_f32 v150, -v140, v149, v148
	v_fmac_f32_e32 v149, v150, v147
	v_fma_f32 v140, -v140, v149, v148
	v_div_fmas_f32 v140, v140, v147, v149
	v_div_fixup_f32 v140, v140, v137, 1.0
	v_pk_mul_f32 v[124:125], v[124:125], v[140:141] op_sel_hi:[1,0]
	v_pk_mul_f32 v[126:127], v[126:127], v[140:141] op_sel_hi:[1,0]
	v_pk_mul_f32 v[120:121], v[120:121], v[140:141] op_sel_hi:[1,0]
	v_pk_mul_f32 v[122:123], v[122:123], v[140:141] op_sel_hi:[1,0]
	v_pk_mul_f32 v[112:113], v[112:113], v[140:141] op_sel_hi:[1,0]
	v_pk_mul_f32 v[114:115], v[114:115], v[140:141] op_sel_hi:[1,0]
	v_pk_mul_f32 v[126:127], v[126:127], v[126:127]
	v_pk_mul_f32 v[124:125], v[124:125], v[124:125]
	v_pk_mul_f32 v[122:123], v[122:123], v[122:123]
	v_pk_mul_f32 v[120:121], v[120:121], v[120:121]
	v_pk_mul_f32 v[116:117], v[116:117], v[140:141] op_sel_hi:[1,0]
	v_pk_mul_f32 v[118:119], v[118:119], v[140:141] op_sel_hi:[1,0]
	v_pk_mul_f32 v[114:115], v[114:115], v[114:115]
	v_pk_mul_f32 v[112:113], v[112:113], v[112:113]
	v_cvt_pk_bf16_f32 v124, v124, v125
	v_cvt_pk_bf16_f32 v125, v126, v127
	v_cvt_pk_bf16_f32 v120, v120, v121
	v_cvt_pk_bf16_f32 v121, v122, v123
	v_pk_mul_f32 v[118:119], v[118:119], v[118:119]
	v_pk_mul_f32 v[116:117], v[116:117], v[116:117]
	v_max_f32_e32 v81, 0, v81
	v_cvt_pk_bf16_f32 v122, v116, v117
	v_cvt_pk_bf16_f32 v123, v118, v119
	v_cvt_pk_bf16_f32 v126, v112, v113
	v_cvt_pk_bf16_f32 v115, v114, v115
; __device__ __forceinline__ u32x4 pack8(f32x4 a, f32x4 b) { u32x4 w; w.x = cvt_pk_bf16(a[0], a[1]); w.y = cvt_pk_bf16(a[2], a[3]); w.z = cvt_pk_bf16(b[0], b[1]); w.w = cvt_pk_bf16(b[2], b[3]); return w; }
; __device__ __forceinline__ float rs_of(const float* ss, int row) { return 1.0f / sqrtf(ss[row] * (1.0f / 2048.0f) + 1e-5f); }
;     __device__ __forceinline__ void operator()(const f32x4 (&acc)[2][2][4][2], const Unit& u, int wr, int wc, int fr, int fq) const {
;     ...
;                 const int row = row0 + ai * HALF + m * 16; const float rr = ss ? rs_of(ss, row) : 1.0f;
;                 u32x4 v[2];
; #pragma unroll
;                 for (int bj = 0; bj < 2; ++bj) {
;                     f32x4 a = __builtin_elementwise_max(acc[ai][bj][m][0], z) * rr, b = __builtin_elementwise_max(acc[ai][bj][m][1], z) * rr;
;                     v[bj] = pack8(a * a, b * b);
;                 }
;                 line_xchg(v[0], v[1], hb);
;                 bf16_t* p = O + (size_t)(srow0 + ai * HALF + m * 16) * ldc + scol;
;                 __builtin_nontemporal_store(v[0], (u32x4*)p); __builtin_nontemporal_store(v[1], (u32x4*)(p + (size_t)8 * ldc));
	v_max_f32_e32 v80, 0, v80
	v_cndmask_b32_e64 v113, v126, v120, s[2:3]
	v_cndmask_b32_e64 v114, v123, v125, s[2:3]
	v_cndmask_b32_e64 v112, v115, v121, s[2:3]
	v_mov_b32_dpp v137, v113 row_ror:8 row_mask:0xf bank_mask:0xf
	v_mov_b32_dpp v114, v114 row_ror:8 row_mask:0xf bank_mask:0xf
	v_cndmask_b32_e64 v116, v122, v124, s[2:3]
	v_mov_b32_dpp v140, v112 row_ror:8 row_mask:0xf bank_mask:0xf
	v_cndmask_b32_e64 v117, v125, v114, s[2:3]
	v_cndmask_b32_e64 v118, v120, v137, s[2:3]
	v_cndmask_b32_e64 v113, v114, v123, s[2:3]
	v_cndmask_b32_e64 v114, v137, v126, s[2:3]
	v_ashrrev_i32_e32 v137, 31, v136
	v_mov_b32_dpp v127, v116 row_ror:8 row_mask:0xf bank_mask:0xf
	v_cndmask_b32_e64 v119, v121, v140, s[2:3]
	v_lshlrev_b64 v[120:121], 14, v[136:137]
	v_cndmask_b32_e64 v112, v127, v122, s[2:3]
	v_lshl_add_u64 v[120:121], s[10:11], 0, v[120:121]
	v_lshlrev_b64 v[122:123], 1, v[138:139]
	v_cndmask_b32_e64 v116, v124, v127, s[2:3]
	v_lshl_add_u64 v[120:121], v[120:121], 0, v[122:123]
	global_store_dwordx4 v[120:121], v[116:119], off nt
	v_cndmask_b32_e64 v115, v140, v115, s[2:3]
	v_max_f32_e32 v87, 0, v87
	v_add_co_u32_e32 v116, vcc, s79, v120
	v_max_f32_e32 v86, 0, v86
	s_nop 0
	v_addc_co_u32_e32 v117, vcc, 0, v121, vcc
	global_store_dwordx4 v[116:117], v[112:115], off nt
	v_max_f32_e32 v85, 0, v85
	v_max_f32_e32 v84, 0, v84
	v_max_f32_e32 v83, 0, v83
	v_max_f32_e32 v82, 0, v82
	v_max_f32_e32 v79, v79, v79
	v_max_f32_e32 v78, v78, v78
	v_max_f32_e32 v77, v77, v77
	v_max_f32_e32 v76, v76, v76
	v_max_f32_e32 v75, v75, v75
	v_max_f32_e32 v74, v74, v74
	v_max_f32_e32 v73, v73, v73
	v_max_f32_e32 v72, v72, v72
	v_max_f32_e32 v65, v65, v65
	v_max_f32_e32 v64, v64, v64
	v_max_f32_e32 v79, 0, v79
	v_max_f32_e32 v78, 0, v78
	v_max_f32_e32 v77, 0, v77
	v_max_f32_e32 v76, 0, v76
	v_max_f32_e32 v75, 0, v75
	v_max_f32_e32 v74, 0, v74
	v_max_f32_e32 v73, 0, v73
	v_max_f32_e32 v72, 0, v72
	v_max_f32_e32 v71, v71, v71
	v_max_f32_e32 v70, v70, v70
	v_max_f32_e32 v69, v69, v69
	v_max_f32_e32 v68, v68, v68
	v_max_f32_e32 v67, v67, v67
	v_max_f32_e32 v66, v66, v66
	v_max_f32_e32 v65, 0, v65
	v_max_f32_e32 v64, 0, v64
	v_max_f32_e32 v71, 0, v71
	v_max_f32_e32 v70, 0, v70
	v_max_f32_e32 v69, 0, v69
	v_max_f32_e32 v68, 0, v68
	v_max_f32_e32 v67, 0, v67
	v_max_f32_e32 v66, 0, v66
	v_max_f32_e32 v63, v63, v63
	v_max_f32_e32 v62, v62, v62
	v_max_f32_e32 v61, v61, v61
	v_max_f32_e32 v60, v60, v60
	v_max_f32_e32 v59, v59, v59
	v_max_f32_e32 v58, v58, v58
	v_max_f32_e32 v57, v57, v57
	v_max_f32_e32 v56, v56, v56
	v_max_f32_e32 v49, v49, v49
	v_max_f32_e32 v48, v48, v48
	v_max_f32_e32 v63, 0, v63
	v_max_f32_e32 v62, 0, v62
	v_max_f32_e32 v61, 0, v61
	v_max_f32_e32 v60, 0, v60
	v_max_f32_e32 v59, 0, v59
	v_max_f32_e32 v58, 0, v58
	v_max_f32_e32 v57, 0, v57
	v_max_f32_e32 v56, 0, v56
	v_max_f32_e32 v55, v55, v55
	v_max_f32_e32 v54, v54, v54
	v_max_f32_e32 v53, v53, v53
	v_max_f32_e32 v52, v52, v52
	v_max_f32_e32 v51, v51, v51
	v_max_f32_e32 v50, v50, v50
	v_max_f32_e32 v49, 0, v49
	v_max_f32_e32 v48, 0, v48
	v_max_f32_e32 v55, 0, v55
	v_max_f32_e32 v54, 0, v54
	v_max_f32_e32 v53, 0, v53
	v_max_f32_e32 v52, 0, v52
	v_max_f32_e32 v51, 0, v51
	v_max_f32_e32 v50, 0, v50
	v_max_f32_e32 v45, v45, v45
	v_max_f32_e32 v44, v44, v44
	v_max_f32_e32 v41, v41, v41
	v_max_f32_e32 v40, v40, v40
	v_max_f32_e32 v39, v39, v39
	v_max_f32_e32 v38, v38, v38
	v_max_f32_e32 v37, v37, v37
	v_max_f32_e32 v36, v36, v36
	v_max_f32_e32 v33, v33, v33
	v_max_f32_e32 v32, v32, v32
	v_max_f32_e32 v47, v47, v47
	s_waitcnt vmcnt(8)
	v_fmamk_f32 v112, v161, 0x3a000000, v205
	v_cmp_gt_f32_e32 vcc, s83, v112
	v_mul_f32_e32 v113, 0x4f800000, v112
	v_max_f32_e32 v46, v46, v46
	v_cndmask_b32_e32 v112, v112, v113, vcc
	v_sqrt_f32_e32 v113, v112
	v_max_f32_e32 v45, 0, v45
	v_max_f32_e32 v44, 0, v44
	v_max_f32_e32 v43, v43, v43
	v_add_u32_e32 v114, -1, v113
	v_fma_f32 v115, -v114, v113, v112
	v_cmp_ge_f32_e64 s[0:1], 0, v115
	v_add_u32_e32 v115, 1, v113
	v_max_f32_e32 v42, v42, v42
	v_cndmask_b32_e64 v114, v113, v114, s[0:1]
	v_fma_f32 v113, -v115, v113, v112
	v_cmp_lt_f32_e64 s[0:1], 0, v113
	v_max_f32_e32 v41, 0, v41
	v_max_f32_e32 v40, 0, v40
	v_cndmask_b32_e64 v113, v114, v115, s[0:1]
	v_mul_f32_e32 v114, 0x37800000, v113
	v_cndmask_b32_e32 v113, v113, v114, vcc
	v_cmp_class_f32_e32 vcc, v112, v206
	v_max_f32_e32 v39, 0, v39
	v_max_f32_e32 v38, 0, v38
	v_cndmask_b32_e32 v112, v113, v112, vcc
	v_div_scale_f32 v113, s[0:1], v112, v112, 1.0
	v_rcp_f32_e32 v114, v113
	v_max_f32_e32 v37, 0, v37
	v_max_f32_e32 v36, 0, v36
	v_max_f32_e32 v35, v35, v35
	v_fma_f32 v115, -v113, v114, 1.0
	v_fmac_f32_e32 v114, v115, v114
	v_div_scale_f32 v115, vcc, 1.0, v112, 1.0
	v_mul_f32_e32 v116, v115, v114
	v_fma_f32 v117, -v113, v116, v115
	v_fmac_f32_e32 v116, v117, v114
	v_fma_f32 v113, -v113, v116, v115
	v_div_fmas_f32 v113, v113, v114, v116
	v_div_fixup_f32 v112, v113, v112, 1.0
	v_pk_mul_f32 v[108:109], v[108:109], v[112:113] op_sel_hi:[1,0]
	v_pk_mul_f32 v[110:111], v[110:111], v[112:113] op_sel_hi:[1,0]
	v_pk_mul_f32 v[104:105], v[104:105], v[112:113] op_sel_hi:[1,0]
	v_pk_mul_f32 v[106:107], v[106:107], v[112:113] op_sel_hi:[1,0]
	v_pk_mul_f32 v[96:97], v[96:97], v[112:113] op_sel_hi:[1,0]
	v_pk_mul_f32 v[110:111], v[110:111], v[110:111]
	v_pk_mul_f32 v[108:109], v[108:109], v[108:109]
	v_pk_mul_f32 v[106:107], v[106:107], v[106:107]
	v_pk_mul_f32 v[104:105], v[104:105], v[104:105]
	v_pk_mul_f32 v[100:101], v[100:101], v[112:113] op_sel_hi:[1,0]
	v_pk_mul_f32 v[102:103], v[102:103], v[112:113] op_sel_hi:[1,0]
	v_pk_mul_f32 v[98:99], v[98:99], v[112:113] op_sel_hi:[1,0]
	v_pk_mul_f32 v[96:97], v[96:97], v[96:97]
; __device__ __forceinline__ u32x4 pack8(f32x4 a, f32x4 b) { u32x4 w; w.x = cvt_pk_bf16(a[0], a[1]); w.y = cvt_pk_bf16(a[2], a[3]); w.z = cvt_pk_bf16(b[0], b[1]); w.w = cvt_pk_bf16(b[2], b[3]); return w; }
; __device__ __forceinline__ float rs_of(const float* ss, int row) { return 1.0f / sqrtf(ss[row] * (1.0f / 2048.0f) + 1e-5f); }
;     __device__ __forceinline__ void operator()(const f32x4 (&acc)[2][2][4][2], const Unit& u, int wr, int wc, int fr, int fq) const {
;     ...
;                 const int row = row0 + ai * HALF + m * 16; const float rr = ss ? rs_of(ss, row) : 1.0f;
;                 u32x4 v[2];
; #pragma unroll
;                 for (int bj = 0; bj < 2; ++bj) {
;                     f32x4 a = __builtin_elementwise_max(acc[ai][bj][m][0], z) * rr, b = __builtin_elementwise_max(acc[ai][bj][m][1], z) * rr;
;                     v[bj] = pack8(a * a, b * b);
;                 }
;                 line_xchg(v[0], v[1], hb);
;                 bf16_t* p = O + (size_t)(srow0 + ai * HALF + m * 16) * ldc + scol;
;                 __builtin_nontemporal_store(v[0], (u32x4*)p); __builtin_nontemporal_store(v[1], (u32x4*)(p + (size_t)8 * ldc));
	v_cvt_pk_bf16_f32 v108, v108, v109
	v_cvt_pk_bf16_f32 v109, v110, v111
	v_cvt_pk_bf16_f32 v104, v104, v105
	v_cvt_pk_bf16_f32 v105, v106, v107
	v_pk_mul_f32 v[102:103], v[102:103], v[102:103]
	v_pk_mul_f32 v[100:101], v[100:101], v[100:101]
	v_pk_mul_f32 v[98:99], v[98:99], v[98:99]
	v_cvt_pk_bf16_f32 v106, v100, v101
	v_cvt_pk_bf16_f32 v107, v102, v103
	v_cvt_pk_bf16_f32 v110, v96, v97
	v_max_f32_e32 v34, v34, v34
	v_cndmask_b32_e64 v97, v110, v104, s[2:3]
	v_cvt_pk_bf16_f32 v99, v98, v99
	v_cndmask_b32_e64 v98, v107, v109, s[2:3]
	v_cndmask_b32_e64 v96, v99, v105, s[2:3]
	v_mov_b32_dpp v112, v97 row_ror:8 row_mask:0xf bank_mask:0xf
	v_cndmask_b32_e64 v102, v104, v112, s[2:3]
	v_mov_b32_dpp v113, v96 row_ror:8 row_mask:0xf bank_mask:0xf
	v_or_b32_e32 v104, 16, v136
	v_cndmask_b32_e64 v103, v105, v113, s[2:3]
	v_ashrrev_i32_e32 v105, 31, v104
	v_cndmask_b32_e64 v100, v106, v108, s[2:3]
	v_lshlrev_b64 v[104:105], 14, v[104:105]
	v_mov_b32_dpp v98, v98 row_ror:8 row_mask:0xf bank_mask:0xf
	v_mov_b32_dpp v111, v100 row_ror:8 row_mask:0xf bank_mask:0xf
	v_lshl_add_u64 v[104:105], s[10:11], 0, v[104:105]
	v_cndmask_b32_e64 v100, v108, v111, s[2:3]
	v_cndmask_b32_e64 v101, v109, v98, s[2:3]
	v_lshl_add_u64 v[104:105], v[104:105], 0, v[122:123]
	global_store_dwordx4 v[104:105], v[100:103], off nt
	v_cndmask_b32_e64 v96, v111, v106, s[2:3]
	v_cndmask_b32_e64 v97, v98, v107, s[2:3]
	v_add_co_u32_e32 v100, vcc, s79, v104
	v_cndmask_b32_e64 v98, v112, v110, s[2:3]
	v_cndmask_b32_e64 v99, v113, v99, s[2:3]
	v_addc_co_u32_e32 v101, vcc, 0, v105, vcc
	global_store_dwordx4 v[100:101], v[96:99], off nt
	v_max_f32_e32 v33, 0, v33
	v_max_f32_e32 v32, 0, v32
	v_max_f32_e32 v47, 0, v47
	v_max_f32_e32 v46, 0, v46
	v_max_f32_e32 v43, 0, v43
	v_max_f32_e32 v42, 0, v42
	v_max_f32_e32 v35, 0, v35
	v_max_f32_e32 v34, 0, v34
	v_max_f32_e32 v29, v29, v29
	v_max_f32_e32 v28, v28, v28
	v_max_f32_e32 v25, v25, v25
	v_max_f32_e32 v24, v24, v24
	v_max_f32_e32 v23, v23, v23
	v_max_f32_e32 v22, v22, v22
	v_max_f32_e32 v21, v21, v21
	v_max_f32_e32 v20, v20, v20
	v_max_f32_e32 v17, v17, v17
	v_max_f32_e32 v16, v16, v16
	v_max_f32_e32 v31, v31, v31
	v_max_f32_e32 v30, v30, v30
	v_max_f32_e32 v29, 0, v29
	v_max_f32_e32 v28, 0, v28
	v_max_f32_e32 v27, v27, v27
	v_max_f32_e32 v26, v26, v26
	v_max_f32_e32 v25, 0, v25
	v_max_f32_e32 v24, 0, v24
	v_max_f32_e32 v23, 0, v23
	v_max_f32_e32 v22, 0, v22
	v_max_f32_e32 v21, 0, v21
	v_max_f32_e32 v20, 0, v20
	v_max_f32_e32 v19, v19, v19
	v_max_f32_e32 v18, v18, v18
	v_max_f32_e32 v17, 0, v17
	v_max_f32_e32 v16, 0, v16
	v_max_f32_e32 v31, 0, v31
	v_max_f32_e32 v30, 0, v30
	v_max_f32_e32 v27, 0, v27
	v_max_f32_e32 v26, 0, v26
	v_max_f32_e32 v19, 0, v19
	v_max_f32_e32 v18, 0, v18
	v_max_f32_e32 v15, v15, v15
	v_max_f32_e32 v14, v14, v14
	v_max_f32_e32 v13, v13, v13
	v_max_f32_e32 v12, v12, v12
	v_max_f32_e32 v11, v11, v11
	v_max_f32_e32 v10, v10, v10
	v_max_f32_e32 v9, v9, v9
	v_max_f32_e32 v8, v8, v8
	v_max_f32_e32 v1, v1, v1
	v_max_f32_e32 v0, v0, v0
	v_max_f32_e32 v15, 0, v15
	v_max_f32_e32 v14, 0, v14
	v_max_f32_e32 v13, 0, v13
	v_max_f32_e32 v12, 0, v12
	v_max_f32_e32 v11, 0, v11
	v_max_f32_e32 v10, 0, v10
	v_max_f32_e32 v9, 0, v9
	v_max_f32_e32 v8, 0, v8
	v_max_f32_e32 v7, v7, v7
	v_max_f32_e32 v6, v6, v6
	v_max_f32_e32 v5, v5, v5
	v_max_f32_e32 v4, v4, v4
	v_max_f32_e32 v3, v3, v3
	v_max_f32_e32 v2, v2, v2
	v_max_f32_e32 v1, 0, v1
	v_max_f32_e32 v0, 0, v0
	v_max_f32_e32 v7, 0, v7
	v_max_f32_e32 v6, 0, v6
	v_max_f32_e32 v5, 0, v5
	v_max_f32_e32 v4, 0, v4
	v_max_f32_e32 v3, 0, v3
	v_max_f32_e32 v2, 0, v2
	s_waitcnt vmcnt(9)
	v_fmamk_f32 v96, v162, 0x3a000000, v205
	v_cmp_gt_f32_e32 vcc, s83, v96
	v_mul_f32_e32 v97, 0x4f800000, v96
	s_nop 0
	v_cndmask_b32_e32 v96, v96, v97, vcc
	v_sqrt_f32_e32 v97, v96
	s_nop 0
	v_add_u32_e32 v98, -1, v97
	v_fma_f32 v99, -v98, v97, v96
	v_cmp_ge_f32_e64 s[0:1], 0, v99
	v_add_u32_e32 v99, 1, v97
	s_nop 0
	v_cndmask_b32_e64 v98, v97, v98, s[0:1]
	v_fma_f32 v97, -v99, v97, v96
	v_cmp_lt_f32_e64 s[0:1], 0, v97
	s_nop 1
	v_cndmask_b32_e64 v97, v98, v99, s[0:1]
	v_mul_f32_e32 v98, 0x37800000, v97
	v_cndmask_b32_e32 v97, v97, v98, vcc
	v_cmp_class_f32_e32 vcc, v96, v206
	s_nop 1
	v_cndmask_b32_e32 v96, v97, v96, vcc
	v_div_scale_f32 v97, s[0:1], v96, v96, 1.0
	v_rcp_f32_e32 v98, v97
	s_nop 0
	v_fma_f32 v99, -v97, v98, 1.0
	v_fmac_f32_e32 v98, v99, v98
	v_div_scale_f32 v99, vcc, 1.0, v96, 1.0
	v_mul_f32_e32 v100, v99, v98
	v_fma_f32 v101, -v97, v100, v99
	v_fmac_f32_e32 v100, v101, v98
	v_fma_f32 v97, -v97, v100, v99
	v_div_fmas_f32 v97, v97, v98, v100
	v_div_fixup_f32 v96, v97, v96, 1.0
	v_pk_mul_f32 v[92:93], v[92:93], v[96:97] op_sel_hi:[1,0]
	v_pk_mul_f32 v[94:95], v[94:95], v[96:97] op_sel_hi:[1,0]
	v_pk_mul_f32 v[88:89], v[88:89], v[96:97] op_sel_hi:[1,0]
	v_pk_mul_f32 v[90:91], v[90:91], v[96:97] op_sel_hi:[1,0]
	v_pk_mul_f32 v[80:81], v[80:81], v[96:97] op_sel_hi:[1,0]
	v_pk_mul_f32 v[94:95], v[94:95], v[94:95]
	v_pk_mul_f32 v[92:93], v[92:93], v[92:93]
	v_pk_mul_f32 v[90:91], v[90:91], v[90:91]
	v_pk_mul_f32 v[88:89], v[88:89], v[88:89]
	v_pk_mul_f32 v[84:85], v[84:85], v[96:97] op_sel_hi:[1,0]
	v_pk_mul_f32 v[86:87], v[86:87], v[96:97] op_sel_hi:[1,0]
	v_pk_mul_f32 v[82:83], v[82:83], v[96:97] op_sel_hi:[1,0]
	v_pk_mul_f32 v[80:81], v[80:81], v[80:81]
	v_cvt_pk_bf16_f32 v92, v92, v93
	v_cvt_pk_bf16_f32 v93, v94, v95
	v_cvt_pk_bf16_f32 v88, v88, v89
	v_cvt_pk_bf16_f32 v89, v90, v91
	v_pk_mul_f32 v[86:87], v[86:87], v[86:87]
	v_pk_mul_f32 v[84:85], v[84:85], v[84:85]
	v_pk_mul_f32 v[82:83], v[82:83], v[82:83]
	v_cvt_pk_bf16_f32 v90, v84, v85
	v_cvt_pk_bf16_f32 v91, v86, v87
	v_cvt_pk_bf16_f32 v94, v80, v81
	s_nop 0
	v_cndmask_b32_e64 v81, v94, v88, s[2:3]
	v_cvt_pk_bf16_f32 v83, v82, v83
	v_cndmask_b32_e64 v82, v91, v93, s[2:3]
	v_cndmask_b32_e64 v80, v83, v89, s[2:3]
	v_mov_b32_dpp v96, v81 row_ror:8 row_mask:0xf bank_mask:0xf
	v_cndmask_b32_e64 v86, v88, v96, s[2:3]
	v_mov_b32_dpp v97, v80 row_ror:8 row_mask:0xf bank_mask:0xf
	v_or_b32_e32 v88, 32, v136
	v_cndmask_b32_e64 v87, v89, v97, s[2:3]
	v_ashrrev_i32_e32 v89, 31, v88
	v_cndmask_b32_e64 v84, v90, v92, s[2:3]
	v_lshlrev_b64 v[88:89], 14, v[88:89]
	v_mov_b32_dpp v82, v82 row_ror:8 row_mask:0xf bank_mask:0xf
	v_mov_b32_dpp v95, v84 row_ror:8 row_mask:0xf bank_mask:0xf
	v_lshl_add_u64 v[88:89], s[10:11], 0, v[88:89]
	v_cndmask_b32_e64 v84, v92, v95, s[2:3]
	v_cndmask_b32_e64 v85, v93, v82, s[2:3]
	v_lshl_add_u64 v[88:89], v[88:89], 0, v[122:123]
	global_store_dwordx4 v[88:89], v[84:87], off nt
	v_cndmask_b32_e64 v80, v95, v90, s[2:3]
	v_cndmask_b32_e64 v81, v82, v91, s[2:3]
	v_add_co_u32_e32 v84, vcc, s79, v88
	v_cndmask_b32_e64 v82, v96, v94, s[2:3]
	v_cndmask_b32_e64 v83, v97, v83, s[2:3]
	v_addc_co_u32_e32 v85, vcc, 0, v89, vcc
	global_store_dwordx4 v[84:85], v[80:83], off nt
	s_nop 1
	s_waitcnt vmcnt(10)
; __device__ __forceinline__ u32x4 pack8(f32x4 a, f32x4 b) { u32x4 w; w.x = cvt_pk_bf16(a[0], a[1]); w.y = cvt_pk_bf16(a[2], a[3]); w.z = cvt_pk_bf16(b[0], b[1]); w.w = cvt_pk_bf16(b[2], b[3]); return w; }
; __device__ __forceinline__ float rs_of(const float* ss, int row) { return 1.0f / sqrtf(ss[row] * (1.0f / 2048.0f) + 1e-5f); }
;     __device__ __forceinline__ void operator()(const f32x4 (&acc)[2][2][4][2], const Unit& u, int wr, int wc, int fr, int fq) const {
;     ...
;                 const int row = row0 + ai * HALF + m * 16; const float rr = ss ? rs_of(ss, row) : 1.0f;
;                 u32x4 v[2];
; #pragma unroll
;                 for (int bj = 0; bj < 2; ++bj) {
;                     f32x4 a = __builtin_elementwise_max(acc[ai][bj][m][0], z) * rr, b = __builtin_elementwise_max(acc[ai][bj][m][1], z) * rr;
;                     v[bj] = pack8(a * a, b * b);
;                 }
;                 line_xchg(v[0], v[1], hb);
;                 bf16_t* p = O + (size_t)(srow0 + ai * HALF + m * 16) * ldc + scol;
;                 __builtin_nontemporal_store(v[0], (u32x4*)p); __builtin_nontemporal_store(v[1], (u32x4*)(p + (size_t)8 * ldc));
	v_fmamk_f32 v80, v163, 0x3a000000, v205
	v_cmp_gt_f32_e32 vcc, s83, v80
	v_mul_f32_e32 v81, 0x4f800000, v80
	s_nop 0
	v_cndmask_b32_e32 v80, v80, v81, vcc
	v_sqrt_f32_e32 v81, v80
	s_nop 0
	v_add_u32_e32 v82, -1, v81
	v_fma_f32 v83, -v82, v81, v80
	v_cmp_ge_f32_e64 s[0:1], 0, v83
	v_add_u32_e32 v83, 1, v81
	s_nop 0
	v_cndmask_b32_e64 v82, v81, v82, s[0:1]
	v_fma_f32 v81, -v83, v81, v80
	v_cmp_lt_f32_e64 s[0:1], 0, v81
	s_nop 1
	v_cndmask_b32_e64 v81, v82, v83, s[0:1]
	v_mul_f32_e32 v82, 0x37800000, v81
	v_cndmask_b32_e32 v81, v81, v82, vcc
	v_cmp_class_f32_e32 vcc, v80, v206
	s_nop 1
	v_cndmask_b32_e32 v80, v81, v80, vcc
	v_div_scale_f32 v81, s[0:1], v80, v80, 1.0
	v_rcp_f32_e32 v82, v81
	s_nop 0
	v_fma_f32 v83, -v81, v82, 1.0
	v_fmac_f32_e32 v82, v83, v82
	v_div_scale_f32 v83, vcc, 1.0, v80, 1.0
	v_mul_f32_e32 v84, v83, v82
	v_fma_f32 v85, -v81, v84, v83
	v_fmac_f32_e32 v84, v85, v82
	v_fma_f32 v81, -v81, v84, v83
	v_div_fmas_f32 v81, v81, v82, v84
	v_div_fixup_f32 v80, v81, v80, 1.0
	v_pk_mul_f32 v[76:77], v[76:77], v[80:81] op_sel_hi:[1,0]
	v_pk_mul_f32 v[78:79], v[78:79], v[80:81] op_sel_hi:[1,0]
	v_pk_mul_f32 v[72:73], v[72:73], v[80:81] op_sel_hi:[1,0]
	v_pk_mul_f32 v[74:75], v[74:75], v[80:81] op_sel_hi:[1,0]
	v_pk_mul_f32 v[64:65], v[64:65], v[80:81] op_sel_hi:[1,0]
	v_pk_mul_f32 v[78:79], v[78:79], v[78:79]
	v_pk_mul_f32 v[76:77], v[76:77], v[76:77]
	v_pk_mul_f32 v[74:75], v[74:75], v[74:75]
	v_pk_mul_f32 v[72:73], v[72:73], v[72:73]
	v_pk_mul_f32 v[68:69], v[68:69], v[80:81] op_sel_hi:[1,0]
	v_pk_mul_f32 v[70:71], v[70:71], v[80:81] op_sel_hi:[1,0]
	v_pk_mul_f32 v[66:67], v[66:67], v[80:81] op_sel_hi:[1,0]
	v_pk_mul_f32 v[64:65], v[64:65], v[64:65]
	v_cvt_pk_bf16_f32 v76, v76, v77
	v_cvt_pk_bf16_f32 v77, v78, v79
	v_cvt_pk_bf16_f32 v72, v72, v73
	v_cvt_pk_bf16_f32 v73, v74, v75
	v_pk_mul_f32 v[70:71], v[70:71], v[70:71]
	v_pk_mul_f32 v[68:69], v[68:69], v[68:69]
	v_pk_mul_f32 v[66:67], v[66:67], v[66:67]
	v_cvt_pk_bf16_f32 v74, v68, v69
	v_cvt_pk_bf16_f32 v75, v70, v71
	v_cvt_pk_bf16_f32 v78, v64, v65
	s_nop 0
	v_cndmask_b32_e64 v65, v78, v72, s[2:3]
	v_cvt_pk_bf16_f32 v67, v66, v67
	v_cndmask_b32_e64 v66, v75, v77, s[2:3]
	v_cndmask_b32_e64 v64, v67, v73, s[2:3]
	v_mov_b32_dpp v80, v65 row_ror:8 row_mask:0xf bank_mask:0xf
	v_cndmask_b32_e64 v70, v72, v80, s[2:3]
	v_mov_b32_dpp v81, v64 row_ror:8 row_mask:0xf bank_mask:0xf
	v_or_b32_e32 v72, 48, v136
	v_cndmask_b32_e64 v71, v73, v81, s[2:3]
	v_ashrrev_i32_e32 v73, 31, v72
	v_cndmask_b32_e64 v68, v74, v76, s[2:3]
	v_lshlrev_b64 v[72:73], 14, v[72:73]
	v_mov_b32_dpp v66, v66 row_ror:8 row_mask:0xf bank_mask:0xf
	v_mov_b32_dpp v79, v68 row_ror:8 row_mask:0xf bank_mask:0xf
	v_lshl_add_u64 v[72:73], s[10:11], 0, v[72:73]
	v_cndmask_b32_e64 v68, v76, v79, s[2:3]
	v_cndmask_b32_e64 v69, v77, v66, s[2:3]
	v_lshl_add_u64 v[72:73], v[72:73], 0, v[122:123]
	global_store_dwordx4 v[72:73], v[68:71], off nt
	v_cndmask_b32_e64 v64, v79, v74, s[2:3]
	v_cndmask_b32_e64 v65, v66, v75, s[2:3]
	v_add_co_u32_e32 v68, vcc, s79, v72
	v_cndmask_b32_e64 v66, v80, v78, s[2:3]
	v_cndmask_b32_e64 v67, v81, v67, s[2:3]
	v_addc_co_u32_e32 v69, vcc, 0, v73, vcc
	global_store_dwordx4 v[68:69], v[64:67], off nt
	s_nop 1
	s_waitcnt vmcnt(11)
	v_fmamk_f32 v64, v164, 0x3a000000, v205
	v_cmp_gt_f32_e32 vcc, s83, v64
	v_mul_f32_e32 v65, 0x4f800000, v64
	s_nop 0
	v_cndmask_b32_e32 v64, v64, v65, vcc
	v_sqrt_f32_e32 v65, v64
	s_nop 0
	v_add_u32_e32 v66, -1, v65
	v_fma_f32 v67, -v66, v65, v64
	v_cmp_ge_f32_e64 s[0:1], 0, v67
	v_add_u32_e32 v67, 1, v65
	s_nop 0
	v_cndmask_b32_e64 v66, v65, v66, s[0:1]
	v_fma_f32 v65, -v67, v65, v64
	v_cmp_lt_f32_e64 s[0:1], 0, v65
	s_nop 1
	v_cndmask_b32_e64 v65, v66, v67, s[0:1]
	v_mul_f32_e32 v66, 0x37800000, v65
	v_cndmask_b32_e32 v65, v65, v66, vcc
	v_cmp_class_f32_e32 vcc, v64, v206
	s_nop 1
	v_cndmask_b32_e32 v64, v65, v64, vcc
	v_div_scale_f32 v65, s[0:1], v64, v64, 1.0
	v_rcp_f32_e32 v66, v65
	s_mov_b32 s0, 0x200000
	v_fma_f32 v67, -v65, v66, 1.0
	v_fmac_f32_e32 v66, v67, v66
	v_div_scale_f32 v67, vcc, 1.0, v64, 1.0
	v_mul_f32_e32 v68, v67, v66
	v_fma_f32 v69, -v65, v68, v67
	v_fmac_f32_e32 v68, v69, v66
	v_fma_f32 v65, -v65, v68, v67
	v_div_fmas_f32 v65, v65, v66, v68
	v_div_fixup_f32 v64, v65, v64, 1.0
	v_pk_mul_f32 v[60:61], v[60:61], v[64:65] op_sel_hi:[1,0]
	v_pk_mul_f32 v[62:63], v[62:63], v[64:65] op_sel_hi:[1,0]
	v_pk_mul_f32 v[56:57], v[56:57], v[64:65] op_sel_hi:[1,0]
	v_pk_mul_f32 v[58:59], v[58:59], v[64:65] op_sel_hi:[1,0]
	v_pk_mul_f32 v[48:49], v[48:49], v[64:65] op_sel_hi:[1,0]
	v_pk_mul_f32 v[62:63], v[62:63], v[62:63]
	v_pk_mul_f32 v[60:61], v[60:61], v[60:61]
	v_pk_mul_f32 v[58:59], v[58:59], v[58:59]
	v_pk_mul_f32 v[56:57], v[56:57], v[56:57]
	v_pk_mul_f32 v[52:53], v[52:53], v[64:65] op_sel_hi:[1,0]
	v_pk_mul_f32 v[54:55], v[54:55], v[64:65] op_sel_hi:[1,0]
	v_pk_mul_f32 v[50:51], v[50:51], v[64:65] op_sel_hi:[1,0]
	v_pk_mul_f32 v[48:49], v[48:49], v[48:49]
	v_cvt_pk_bf16_f32 v60, v60, v61
	v_cvt_pk_bf16_f32 v61, v62, v63
	v_cvt_pk_bf16_f32 v56, v56, v57
	v_cvt_pk_bf16_f32 v57, v58, v59
	v_pk_mul_f32 v[54:55], v[54:55], v[54:55]
	v_pk_mul_f32 v[52:53], v[52:53], v[52:53]
	v_pk_mul_f32 v[50:51], v[50:51], v[50:51]
	v_cvt_pk_bf16_f32 v58, v52, v53
	v_cvt_pk_bf16_f32 v59, v54, v55
	v_cvt_pk_bf16_f32 v62, v48, v49
	s_nop 0
	v_cndmask_b32_e64 v49, v62, v56, s[2:3]
	v_cvt_pk_bf16_f32 v51, v50, v51
	v_cndmask_b32_e64 v50, v59, v61, s[2:3]
	v_cndmask_b32_e64 v48, v51, v57, s[2:3]
	v_cndmask_b32_e64 v52, v58, v60, s[2:3]
	v_mov_b32_dpp v64, v49 row_ror:8 row_mask:0xf bank_mask:0xf
	v_mov_b32_dpp v50, v50 row_ror:8 row_mask:0xf bank_mask:0xf
	v_mov_b32_dpp v63, v52 row_ror:8 row_mask:0xf bank_mask:0xf
	v_mov_b32_dpp v65, v48 row_ror:8 row_mask:0xf bank_mask:0xf
	v_cndmask_b32_e64 v54, v56, v64, s[2:3]
	v_add_co_u32_e32 v56, vcc, s0, v120
	v_cndmask_b32_e64 v52, v60, v63, s[2:3]
	v_cndmask_b32_e64 v53, v61, v50, s[2:3]
	v_cndmask_b32_e64 v55, v57, v65, s[2:3]
	v_addc_co_u32_e32 v57, vcc, 0, v121, vcc
	s_mov_b32 s0, 0x220000
	global_store_dwordx4 v[56:57], v[52:55], off nt
	v_cndmask_b32_e64 v48, v63, v58, s[2:3]
	v_cndmask_b32_e64 v49, v50, v59, s[2:3]
	v_add_co_u32_e32 v52, vcc, s0, v120
	v_cndmask_b32_e64 v50, v64, v62, s[2:3]
	v_cndmask_b32_e64 v51, v65, v51, s[2:3]
	v_addc_co_u32_e32 v53, vcc, 0, v121, vcc
	global_store_dwordx4 v[52:53], v[48:51], off nt
	s_nop 1
	s_waitcnt vmcnt(12)
; __device__ __forceinline__ u32x4 pack8(f32x4 a, f32x4 b) { u32x4 w; w.x = cvt_pk_bf16(a[0], a[1]); w.y = cvt_pk_bf16(a[2], a[3]); w.z = cvt_pk_bf16(b[0], b[1]); w.w = cvt_pk_bf16(b[2], b[3]); return w; }
; __device__ __forceinline__ float rs_of(const float* ss, int row) { return 1.0f / sqrtf(ss[row] * (1.0f / 2048.0f) + 1e-5f); }
;     __device__ __forceinline__ void operator()(const f32x4 (&acc)[2][2][4][2], const Unit& u, int wr, int wc, int fr, int fq) const {
;     ...
;                 const int row = row0 + ai * HALF + m * 16; const float rr = ss ? rs_of(ss, row) : 1.0f;
;                 u32x4 v[2];
; #pragma unroll
;                 for (int bj = 0; bj < 2; ++bj) {
;                     f32x4 a = __builtin_elementwise_max(acc[ai][bj][m][0], z) * rr, b = __builtin_elementwise_max(acc[ai][bj][m][1], z) * rr;
;                     v[bj] = pack8(a * a, b * b);
;                 }
;                 line_xchg(v[0], v[1], hb);
;                 bf16_t* p = O + (size_t)(srow0 + ai * HALF + m * 16) * ldc + scol;
;                 __builtin_nontemporal_store(v[0], (u32x4*)p); __builtin_nontemporal_store(v[1], (u32x4*)(p + (size_t)8 * ldc));
	v_fmamk_f32 v48, v165, 0x3a000000, v205
	v_cmp_gt_f32_e32 vcc, s83, v48
	v_mul_f32_e32 v49, 0x4f800000, v48
	s_nop 0
	v_cndmask_b32_e32 v48, v48, v49, vcc
	v_sqrt_f32_e32 v49, v48
	s_nop 0
	v_add_u32_e32 v50, -1, v49
	v_fma_f32 v51, -v50, v49, v48
	v_cmp_ge_f32_e64 s[0:1], 0, v51
	v_add_u32_e32 v51, 1, v49
	s_nop 0
	v_cndmask_b32_e64 v50, v49, v50, s[0:1]
	v_fma_f32 v49, -v51, v49, v48
	v_cmp_lt_f32_e64 s[0:1], 0, v49
	s_nop 1
	v_cndmask_b32_e64 v49, v50, v51, s[0:1]
	v_mul_f32_e32 v50, 0x37800000, v49
	v_cndmask_b32_e32 v49, v49, v50, vcc
	v_cmp_class_f32_e32 vcc, v48, v206
	s_nop 1
	v_cndmask_b32_e32 v48, v49, v48, vcc
	v_div_scale_f32 v49, s[0:1], v48, v48, 1.0
	v_rcp_f32_e32 v50, v49
	s_mov_b32 s0, 0x240000
	v_fma_f32 v51, -v49, v50, 1.0
	v_fmac_f32_e32 v50, v51, v50
	v_div_scale_f32 v51, vcc, 1.0, v48, 1.0
	v_mul_f32_e32 v52, v51, v50
	v_fma_f32 v53, -v49, v52, v51
	v_fmac_f32_e32 v52, v53, v50
	v_fma_f32 v49, -v49, v52, v51
	v_div_fmas_f32 v49, v49, v50, v52
	v_div_fixup_f32 v48, v49, v48, 1.0
	v_pk_mul_f32 v[44:45], v[44:45], v[48:49] op_sel_hi:[1,0]
	v_pk_mul_f32 v[40:41], v[40:41], v[48:49] op_sel_hi:[1,0]
	v_pk_mul_f32 v[36:37], v[36:37], v[48:49] op_sel_hi:[1,0]
	v_pk_mul_f32 v[38:39], v[38:39], v[48:49] op_sel_hi:[1,0]
	v_pk_mul_f32 v[32:33], v[32:33], v[48:49] op_sel_hi:[1,0]
	v_pk_mul_f32 v[46:47], v[46:47], v[48:49] op_sel_hi:[1,0]
	v_pk_mul_f32 v[42:43], v[42:43], v[48:49] op_sel_hi:[1,0]
	v_pk_mul_f32 v[44:45], v[44:45], v[44:45]
	v_pk_mul_f32 v[40:41], v[40:41], v[40:41]
	v_pk_mul_f32 v[34:35], v[34:35], v[48:49] op_sel_hi:[1,0]
	v_pk_mul_f32 v[38:39], v[38:39], v[38:39]
	v_pk_mul_f32 v[36:37], v[36:37], v[36:37]
	v_pk_mul_f32 v[32:33], v[32:33], v[32:33]
	v_pk_mul_f32 v[46:47], v[46:47], v[46:47]
	v_pk_mul_f32 v[42:43], v[42:43], v[42:43]
	v_cvt_pk_bf16_f32 v44, v44, v45
	v_cvt_pk_bf16_f32 v45, v46, v47
	v_cvt_pk_bf16_f32 v40, v40, v41
	v_pk_mul_f32 v[34:35], v[34:35], v[34:35]
	v_cvt_pk_bf16_f32 v41, v42, v43
	v_cvt_pk_bf16_f32 v36, v36, v37
	v_cvt_pk_bf16_f32 v37, v38, v39
	v_cvt_pk_bf16_f32 v38, v32, v33
	s_nop 0
	v_cndmask_b32_e64 v33, v38, v40, s[2:3]
	v_cvt_pk_bf16_f32 v39, v34, v35
	v_cndmask_b32_e64 v34, v37, v45, s[2:3]
	v_cndmask_b32_e64 v32, v39, v41, s[2:3]
	v_cndmask_b32_e64 v35, v36, v44, s[2:3]
	v_mov_b32_dpp v46, v33 row_ror:8 row_mask:0xf bank_mask:0xf
	v_mov_b32_dpp v43, v34 row_ror:8 row_mask:0xf bank_mask:0xf
	v_mov_b32_dpp v42, v35 row_ror:8 row_mask:0xf bank_mask:0xf
	v_mov_b32_dpp v47, v32 row_ror:8 row_mask:0xf bank_mask:0xf
	v_cndmask_b32_e64 v34, v40, v46, s[2:3]
	v_add_co_u32_e32 v40, vcc, s0, v120
	v_cndmask_b32_e64 v32, v44, v42, s[2:3]
	v_cndmask_b32_e64 v33, v45, v43, s[2:3]
	v_cndmask_b32_e64 v35, v41, v47, s[2:3]
	v_addc_co_u32_e32 v41, vcc, 0, v121, vcc
	s_mov_b32 s0, 0x260000
	global_store_dwordx4 v[40:41], v[32:35], off nt
	v_cndmask_b32_e64 v36, v42, v36, s[2:3]
	v_cndmask_b32_e64 v37, v43, v37, s[2:3]
	v_add_co_u32_e32 v32, vcc, s0, v120
	v_cndmask_b32_e64 v38, v46, v38, s[2:3]
	v_cndmask_b32_e64 v39, v47, v39, s[2:3]
	v_addc_co_u32_e32 v33, vcc, 0, v121, vcc
	global_store_dwordx4 v[32:33], v[36:39], off nt
	s_nop 1
	s_waitcnt vmcnt(13)
	v_fmamk_f32 v32, v166, 0x3a000000, v205
	v_cmp_gt_f32_e32 vcc, s83, v32
	v_mul_f32_e32 v33, 0x4f800000, v32
	s_nop 0
	v_cndmask_b32_e32 v32, v32, v33, vcc
	v_sqrt_f32_e32 v33, v32
	s_nop 0
	v_add_u32_e32 v34, -1, v33
	v_fma_f32 v35, -v34, v33, v32
	v_cmp_ge_f32_e64 s[0:1], 0, v35
	v_add_u32_e32 v35, 1, v33
	s_nop 0
	v_cndmask_b32_e64 v34, v33, v34, s[0:1]
	v_fma_f32 v33, -v35, v33, v32
	v_cmp_lt_f32_e64 s[0:1], 0, v33
	s_nop 1
	v_cndmask_b32_e64 v33, v34, v35, s[0:1]
	v_mul_f32_e32 v34, 0x37800000, v33
	v_cndmask_b32_e32 v33, v33, v34, vcc
	v_cmp_class_f32_e32 vcc, v32, v206
	s_nop 1
	v_cndmask_b32_e32 v32, v33, v32, vcc
	v_div_scale_f32 v33, s[0:1], v32, v32, 1.0
	v_rcp_f32_e32 v34, v33
	s_mov_b32 s0, 0x280000
	v_fma_f32 v35, -v33, v34, 1.0
	v_fmac_f32_e32 v34, v35, v34
	v_div_scale_f32 v35, vcc, 1.0, v32, 1.0
	v_mul_f32_e32 v36, v35, v34
	v_fma_f32 v37, -v33, v36, v35
	v_fmac_f32_e32 v36, v37, v34
	v_fma_f32 v33, -v33, v36, v35
	v_div_fmas_f32 v33, v33, v34, v36
	v_div_fixup_f32 v32, v33, v32, 1.0
	v_pk_mul_f32 v[28:29], v[28:29], v[32:33] op_sel_hi:[1,0]
	v_pk_mul_f32 v[24:25], v[24:25], v[32:33] op_sel_hi:[1,0]
	v_pk_mul_f32 v[20:21], v[20:21], v[32:33] op_sel_hi:[1,0]
	v_pk_mul_f32 v[22:23], v[22:23], v[32:33] op_sel_hi:[1,0]
	v_pk_mul_f32 v[16:17], v[16:17], v[32:33] op_sel_hi:[1,0]
	v_pk_mul_f32 v[30:31], v[30:31], v[32:33] op_sel_hi:[1,0]
	v_pk_mul_f32 v[26:27], v[26:27], v[32:33] op_sel_hi:[1,0]
	v_pk_mul_f32 v[28:29], v[28:29], v[28:29]
	v_pk_mul_f32 v[24:25], v[24:25], v[24:25]
	v_pk_mul_f32 v[18:19], v[18:19], v[32:33] op_sel_hi:[1,0]
	v_pk_mul_f32 v[22:23], v[22:23], v[22:23]
	v_pk_mul_f32 v[20:21], v[20:21], v[20:21]
	v_pk_mul_f32 v[16:17], v[16:17], v[16:17]
	v_pk_mul_f32 v[30:31], v[30:31], v[30:31]
	v_pk_mul_f32 v[26:27], v[26:27], v[26:27]
	v_cvt_pk_bf16_f32 v28, v28, v29
	v_cvt_pk_bf16_f32 v29, v30, v31
	v_cvt_pk_bf16_f32 v24, v24, v25
	v_pk_mul_f32 v[18:19], v[18:19], v[18:19]
	v_cvt_pk_bf16_f32 v25, v26, v27
	v_cvt_pk_bf16_f32 v20, v20, v21
	v_cvt_pk_bf16_f32 v21, v22, v23
	v_cvt_pk_bf16_f32 v22, v16, v17
	s_nop 0
	v_cndmask_b32_e64 v17, v22, v24, s[2:3]
	v_cvt_pk_bf16_f32 v23, v18, v19
	v_cndmask_b32_e64 v18, v21, v29, s[2:3]
	v_cndmask_b32_e64 v16, v23, v25, s[2:3]
	v_cndmask_b32_e64 v19, v20, v28, s[2:3]
	v_mov_b32_dpp v30, v17 row_ror:8 row_mask:0xf bank_mask:0xf
	v_mov_b32_dpp v27, v18 row_ror:8 row_mask:0xf bank_mask:0xf
	v_mov_b32_dpp v26, v19 row_ror:8 row_mask:0xf bank_mask:0xf
	v_mov_b32_dpp v31, v16 row_ror:8 row_mask:0xf bank_mask:0xf
	v_cndmask_b32_e64 v18, v24, v30, s[2:3]
	v_add_co_u32_e32 v24, vcc, s0, v120
	v_cndmask_b32_e64 v16, v28, v26, s[2:3]
	v_cndmask_b32_e64 v17, v29, v27, s[2:3]
	v_cndmask_b32_e64 v19, v25, v31, s[2:3]
	v_addc_co_u32_e32 v25, vcc, 0, v121, vcc
	s_mov_b32 s0, 0x2a0000
	global_store_dwordx4 v[24:25], v[16:19], off nt
	v_cndmask_b32_e64 v20, v26, v20, s[2:3]
	v_cndmask_b32_e64 v21, v27, v21, s[2:3]
	v_add_co_u32_e32 v16, vcc, s0, v120
	v_cndmask_b32_e64 v22, v30, v22, s[2:3]
	v_cndmask_b32_e64 v23, v31, v23, s[2:3]
	v_addc_co_u32_e32 v17, vcc, 0, v121, vcc
	global_store_dwordx4 v[16:17], v[20:23], off nt
	s_nop 1
	s_waitcnt vmcnt(14)
; __device__ __forceinline__ u32x4 pack8(f32x4 a, f32x4 b) { u32x4 w; w.x = cvt_pk_bf16(a[0], a[1]); w.y = cvt_pk_bf16(a[2], a[3]); w.z = cvt_pk_bf16(b[0], b[1]); w.w = cvt_pk_bf16(b[2], b[3]); return w; }
; __device__ __forceinline__ float rs_of(const float* ss, int row) { return 1.0f / sqrtf(ss[row] * (1.0f / 2048.0f) + 1e-5f); }
;     __device__ __forceinline__ void operator()(const f32x4 (&acc)[2][2][4][2], const Unit& u, int wr, int wc, int fr, int fq) const {
;     ...
;                 const int row = row0 + ai * HALF + m * 16; const float rr = ss ? rs_of(ss, row) : 1.0f;
;                 u32x4 v[2];
; #pragma unroll
;                 for (int bj = 0; bj < 2; ++bj) {
;                     f32x4 a = __builtin_elementwise_max(acc[ai][bj][m][0], z) * rr, b = __builtin_elementwise_max(acc[ai][bj][m][1], z) * rr;
;                     v[bj] = pack8(a * a, b * b);
;                 }
;                 line_xchg(v[0], v[1], hb);
;                 bf16_t* p = O + (size_t)(srow0 + ai * HALF + m * 16) * ldc + scol;
;                 __builtin_nontemporal_store(v[0], (u32x4*)p); __builtin_nontemporal_store(v[1], (u32x4*)(p + (size_t)8 * ldc));
	v_fmamk_f32 v16, v167, 0x3a000000, v205
	v_cmp_gt_f32_e32 vcc, s83, v16
	v_mul_f32_e32 v17, 0x4f800000, v16
	s_nop 0
	v_cndmask_b32_e32 v16, v16, v17, vcc
	v_sqrt_f32_e32 v17, v16
	s_nop 0
	v_add_u32_e32 v18, -1, v17
	v_fma_f32 v19, -v18, v17, v16
	v_cmp_ge_f32_e64 s[0:1], 0, v19
	v_add_u32_e32 v19, 1, v17
	s_nop 0
	v_cndmask_b32_e64 v18, v17, v18, s[0:1]
	v_fma_f32 v17, -v19, v17, v16
	v_cmp_lt_f32_e64 s[0:1], 0, v17
	s_nop 1
	v_cndmask_b32_e64 v17, v18, v19, s[0:1]
	v_mul_f32_e32 v18, 0x37800000, v17
	v_cndmask_b32_e32 v17, v17, v18, vcc
	v_cmp_class_f32_e32 vcc, v16, v206
	s_nop 1
	v_cndmask_b32_e32 v16, v17, v16, vcc
	v_div_scale_f32 v17, s[0:1], v16, v16, 1.0
	v_rcp_f32_e32 v18, v17
	s_mov_b64 s[0:1], -1
	v_fma_f32 v19, -v17, v18, 1.0
	v_fmac_f32_e32 v18, v19, v18
	v_div_scale_f32 v19, vcc, 1.0, v16, 1.0
	v_mul_f32_e32 v20, v19, v18
	v_fma_f32 v21, -v17, v20, v19
	v_fmac_f32_e32 v20, v21, v18
	v_fma_f32 v17, -v17, v20, v19
	v_div_fmas_f32 v17, v17, v18, v20
	v_div_fixup_f32 v16, v17, v16, 1.0
	v_pk_mul_f32 v[12:13], v[12:13], v[16:17] op_sel_hi:[1,0]
	v_pk_mul_f32 v[14:15], v[14:15], v[16:17] op_sel_hi:[1,0]
	v_pk_mul_f32 v[8:9], v[8:9], v[16:17] op_sel_hi:[1,0]
	v_pk_mul_f32 v[10:11], v[10:11], v[16:17] op_sel_hi:[1,0]
	v_pk_mul_f32 v[0:1], v[0:1], v[16:17] op_sel_hi:[1,0]
	v_pk_mul_f32 v[14:15], v[14:15], v[14:15]
	v_pk_mul_f32 v[12:13], v[12:13], v[12:13]
	v_pk_mul_f32 v[10:11], v[10:11], v[10:11]
	v_pk_mul_f32 v[8:9], v[8:9], v[8:9]
	v_pk_mul_f32 v[4:5], v[4:5], v[16:17] op_sel_hi:[1,0]
	v_pk_mul_f32 v[6:7], v[6:7], v[16:17] op_sel_hi:[1,0]
	v_pk_mul_f32 v[2:3], v[2:3], v[16:17] op_sel_hi:[1,0]
	v_pk_mul_f32 v[0:1], v[0:1], v[0:1]
	v_cvt_pk_bf16_f32 v12, v12, v13
	v_cvt_pk_bf16_f32 v13, v14, v15
	v_cvt_pk_bf16_f32 v8, v8, v9
	v_cvt_pk_bf16_f32 v9, v10, v11
	v_pk_mul_f32 v[6:7], v[6:7], v[6:7]
	v_pk_mul_f32 v[4:5], v[4:5], v[4:5]
	v_pk_mul_f32 v[2:3], v[2:3], v[2:3]
	v_cvt_pk_bf16_f32 v10, v4, v5
	v_cvt_pk_bf16_f32 v11, v6, v7
	v_cvt_pk_bf16_f32 v14, v0, v1
	s_nop 0
	v_cndmask_b32_e64 v1, v14, v8, s[2:3]
	v_cvt_pk_bf16_f32 v3, v2, v3
	v_cndmask_b32_e64 v2, v11, v13, s[2:3]
	v_cndmask_b32_e64 v0, v3, v9, s[2:3]
	v_cndmask_b32_e64 v4, v10, v12, s[2:3]
	v_mov_b32_dpp v16, v1 row_ror:8 row_mask:0xf bank_mask:0xf
	v_mov_b32_dpp v2, v2 row_ror:8 row_mask:0xf bank_mask:0xf
	v_mov_b32_dpp v15, v4 row_ror:8 row_mask:0xf bank_mask:0xf
	v_mov_b32_dpp v17, v0 row_ror:8 row_mask:0xf bank_mask:0xf
	v_cndmask_b32_e64 v6, v8, v16, s[2:3]
	v_add_co_u32_e32 v8, vcc, 0x2c0000, v120
	v_cndmask_b32_e64 v4, v12, v15, s[2:3]
	v_cndmask_b32_e64 v5, v13, v2, s[2:3]
	v_cndmask_b32_e64 v7, v9, v17, s[2:3]
	v_addc_co_u32_e32 v9, vcc, 0, v121, vcc
	global_store_dwordx4 v[8:9], v[4:7], off nt
	v_cndmask_b32_e64 v0, v15, v10, s[2:3]
	v_cndmask_b32_e64 v1, v2, v11, s[2:3]
	v_add_co_u32_e32 v4, vcc, 0x2e0000, v120
	v_cndmask_b32_e64 v2, v16, v14, s[2:3]
	s_nop 0
	v_addc_co_u32_e32 v5, vcc, 0, v121, vcc
	v_cndmask_b32_e64 v3, v17, v3, s[2:3]
	s_andn2_b64 vcc, exec, s[4:5]
	global_store_dwordx4 v[4:5], v[0:3], off nt
	s_cbranch_vccnz .LBB0_702
	s_andn2_b64 vcc, exec, s[8:9]
	s_cbranch_vccnz .LBB0_701
	s_barrier
	s_branch .LBB0_701

; __device__ __forceinline__ u32x4 pack8(f32x4 a, f32x4 b) { u32x4 w; w.x = cvt_pk_bf16(a[0], a[1]); w.y = cvt_pk_bf16(a[2], a[3]); w.z = cvt_pk_bf16(b[0], b[1]); w.w = cvt_pk_bf16(b[2], b[3]); return w; }
;     __device__ __forceinline__ void operator()(const f32x4 (&acc)[2][2][4][2], const Unit& u, int wr, int wc, int fr, int fq) const {
;         const int row0 = u.pm * BM + wr * 64 + fr, col = u.pn * BM + wc * 64 + 8 * fq;
; #pragma unroll
;         for (int ai = 0; ai < 2; ++ai)
; #pragma unroll
;             for (int m = 0; m < 4; ++m) {
;                 const int row = row0 + ai * HALF + m * 16; const size_t off = (size_t)row * 2048 + col;
;                 float s = 0.f;
; #pragma unroll
;                 for (int bj = 0; bj < 2; ++bj) {
;                     f32x4 b0, b1;
;                     if (BASE_F32) { const float* bp = (const float*)base + off + bj * 32; b0 = *(const f32x4*)bp; b1 = *(const f32x4*)(bp + 4); }
;                     else { const u32x4 w = *(const u32x4*)((const bf16_t*)base + off + bj * 32);
;                         b0 = (f32x4){__uint_as_float(w.x << 16), __uint_as_float(w.x & 0xffff0000u), __uint_as_float(w.y << 16), __uint_as_float(w.y & 0xffff0000u)};
;                         b1 = (f32x4){__uint_as_float(w.z << 16), __uint_as_float(w.z & 0xffff0000u), __uint_as_float(w.w << 16), __uint_as_float(w.w & 0xffff0000u)}; }
;                     const f32x4 h0 = b0 + acc[ai][bj][m][0], h1 = b1 + acc[ai][bj][m][1];
;                     s += (h0[0] * h0[0] + h0[1] * h0[1]) + (h0[2] * h0[2] + h0[3] * h0[3]) + (h1[0] * h1[0] + h1[1] * h1[1]) + (h1[2] * h1[2] + h1[3] * h1[3]);
;                     *(u32x4*)(H + off + bj * 32) = pack8(h0, h1);
;                 }
;                 s += __shfl_xor(s, 16); s += __shfl_xor(s, 32);
;                 if (fq == 0) __hip_atomic_fetch_add(ss + row, s, __ATOMIC_RELAXED, __HIP_MEMORY_SCOPE_AGENT);
;                 if (m & 1) asm volatile("" ::: "memory");
;             }
.LBB0_798:
	v_lshl_add_u32 v138, s24, 8, v141
	v_ashrrev_i32_e32 v139, 31, v138
	v_lshl_or_b32 v136, s26, 8, v143
	v_lshlrev_b64 v[134:135], 12, v[138:139]
	v_ashrrev_i32_e32 v137, 31, v136
	v_lshl_add_u64 v[134:135], s[8:9], 0, v[134:135]
	v_lshl_add_u64 v[134:135], v[136:137], 1, v[134:135]
	v_mov_b32_e32 v220, v138
	v_ashrrev_i32_e32 v221, 31, v220
	v_lshlrev_b64 v[220:221], 12, v[220:221]
	v_lshl_add_u64 v[220:221], s[8:9], 0, v[220:221]
	v_lshl_add_u64 v[220:221], v[136:137], 1, v[220:221]
	global_load_dwordx4 v[154:157], v[220:221], off
	global_load_dwordx4 v[158:161], v[220:221], off offset:64
	v_add_u32_e32 v220, 0x10, v138
	v_ashrrev_i32_e32 v221, 31, v220
	v_lshlrev_b64 v[220:221], 12, v[220:221]
	v_lshl_add_u64 v[220:221], s[8:9], 0, v[220:221]
	v_lshl_add_u64 v[220:221], v[136:137], 1, v[220:221]
	global_load_dwordx4 v[162:165], v[220:221], off
	global_load_dwordx4 v[166:169], v[220:221], off offset:64
	v_add_u32_e32 v220, 0x20, v138
	v_ashrrev_i32_e32 v221, 31, v220
	v_lshlrev_b64 v[220:221], 12, v[220:221]
	v_lshl_add_u64 v[220:221], s[8:9], 0, v[220:221]
	v_lshl_add_u64 v[220:221], v[136:137], 1, v[220:221]
	global_load_dwordx4 v[178:181], v[220:221], off
	global_load_dwordx4 v[182:185], v[220:221], off offset:64
	v_add_u32_e32 v220, 0x30, v138
	v_ashrrev_i32_e32 v221, 31, v220
	v_lshlrev_b64 v[220:221], 12, v[220:221]
	v_lshl_add_u64 v[220:221], s[8:9], 0, v[220:221]
	v_lshl_add_u64 v[220:221], v[136:137], 1, v[220:221]
	global_load_dwordx4 v[186:189], v[220:221], off
	global_load_dwordx4 v[190:193], v[220:221], off offset:64
	v_add_u32_e32 v220, 0x80, v138
	v_ashrrev_i32_e32 v221, 31, v220
	v_lshlrev_b64 v[220:221], 12, v[220:221]
	v_lshl_add_u64 v[220:221], s[8:9], 0, v[220:221]
	v_lshl_add_u64 v[220:221], v[136:137], 1, v[220:221]
	global_load_dwordx4 v[194:197], v[220:221], off
	global_load_dwordx4 v[198:201], v[220:221], off offset:64
	v_add_u32_e32 v220, 0x90, v138
	v_ashrrev_i32_e32 v221, 31, v220
	v_lshlrev_b64 v[220:221], 12, v[220:221]
	v_lshl_add_u64 v[220:221], s[8:9], 0, v[220:221]
	v_lshl_add_u64 v[220:221], v[136:137], 1, v[220:221]
	global_load_dwordx4 v[212:215], v[220:221], off
	global_load_dwordx4 v[216:219], v[220:221], off offset:64
	s_nop 1
	s_waitcnt vmcnt(11)
	v_mov_b32_e32 v146, v154
	v_mov_b32_e32 v147, v155
	v_mov_b32_e32 v148, v156
	v_mov_b32_e32 v149, v157
	s_nop 0
	v_lshlrev_b32_e32 v150, 16, v146
	v_and_b32_e32 v151, 0xffff0000, v146
	v_lshlrev_b32_e32 v146, 16, v147
	v_and_b32_e32 v147, 0xffff0000, v147
	v_lshlrev_b32_e32 v152, 16, v148
	v_and_b32_e32 v153, 0xffff0000, v148
	v_lshlrev_b32_e32 v148, 16, v149
	v_and_b32_e32 v149, 0xffff0000, v149
	v_pk_add_f32 v[126:127], v[126:127], v[146:147]
	v_pk_add_f32 v[124:125], v[124:125], v[150:151]
	v_pk_add_f32 v[146:147], v[122:123], v[148:149]
	v_pk_add_f32 v[122:123], v[120:121], v[152:153]
	v_mul_f32_e32 v120, v125, v125
	v_mul_f32_e32 v121, v127, v127
	v_fmac_f32_e32 v120, v124, v124
	v_fmac_f32_e32 v121, v126, v126
	v_add_f32_e32 v120, v120, v121
	v_mul_f32_e32 v121, v123, v123
	v_fmac_f32_e32 v121, v122, v122
	v_add_f32_e32 v120, v121, v120
	v_mul_f32_e32 v121, v147, v147
	v_fmac_f32_e32 v121, v146, v146
	v_add_f32_e32 v145, v121, v120
	v_cvt_pk_bf16_f32 v120, v124, v125
	v_cvt_pk_bf16_f32 v121, v126, v127
	v_cvt_pk_bf16_f32 v122, v122, v123
	v_cvt_pk_bf16_f32 v123, v146, v147
	global_store_dwordx4 v[134:135], v[120:123], off
	s_nop 1
	s_waitcnt vmcnt(11)
	v_mov_b32_e32 v120, v158
	v_mov_b32_e32 v121, v159
	v_mov_b32_e32 v122, v160
	v_mov_b32_e32 v123, v161
	v_add_u32_e32 v220, 0xa0, v138
	v_ashrrev_i32_e32 v221, 31, v220
	v_lshlrev_b64 v[220:221], 12, v[220:221]
	v_lshl_add_u64 v[220:221], s[8:9], 0, v[220:221]
	v_lshl_add_u64 v[220:221], v[136:137], 1, v[220:221]
	global_load_dwordx4 v[154:157], v[220:221], off
	global_load_dwordx4 v[158:161], v[220:221], off offset:64
	s_nop 0
	v_lshlrev_b32_e32 v124, 16, v120
	v_and_b32_e32 v125, 0xffff0000, v120
	v_lshlrev_b32_e32 v120, 16, v121
	v_and_b32_e32 v121, 0xffff0000, v121
	v_lshlrev_b32_e32 v126, 16, v122
	v_and_b32_e32 v127, 0xffff0000, v122
	v_lshlrev_b32_e32 v122, 16, v123
	v_and_b32_e32 v123, 0xffff0000, v123
	v_pk_add_f32 v[118:119], v[118:119], v[120:121]
	v_pk_add_f32 v[116:117], v[116:117], v[124:125]
	v_pk_add_f32 v[120:121], v[114:115], v[122:123]
	v_pk_add_f32 v[114:115], v[112:113], v[126:127]
	v_mul_f32_e32 v112, v117, v117
	v_mul_f32_e32 v113, v119, v119
	v_fmac_f32_e32 v112, v116, v116
	v_fmac_f32_e32 v113, v118, v118
	v_add_f32_e32 v112, v112, v113
	v_mul_f32_e32 v113, v115, v115
	v_fmac_f32_e32 v113, v114, v114
	v_add_f32_e32 v112, v113, v112
	v_mul_f32_e32 v113, v121, v121
	v_fmac_f32_e32 v113, v120, v120
	v_add_f32_e32 v112, v113, v112
	v_add_f32_e32 v122, v145, v112
	v_cvt_pk_bf16_f32 v112, v116, v117
	v_cvt_pk_bf16_f32 v113, v118, v119
	v_cvt_pk_bf16_f32 v114, v114, v115
	v_cvt_pk_bf16_f32 v115, v120, v121
	global_store_dwordx4 v[134:135], v[112:115], off offset:64
	s_nop 1
	v_and_b32_e32 v113, 64, v209
	v_xor_b32_e32 v112, 16, v209
	v_add_u32_e32 v113, 64, v113
	v_cmp_lt_i32_e32 vcc, v112, v113
	s_nop 1
	v_cndmask_b32_e32 v112, v209, v112, vcc
	v_lshlrev_b32_e32 v114, 2, v112
	ds_bpermute_b32 v112, v114, v122
	s_waitcnt lgkmcnt(0)
	v_add_f32_e32 v116, v122, v112
	v_xor_b32_e32 v112, 32, v209
	v_cmp_lt_i32_e32 vcc, v112, v113
	s_nop 1
	v_cndmask_b32_e32 v112, v209, v112, vcc
	v_lshlrev_b32_e32 v115, 2, v112
	ds_bpermute_b32 v117, v115, v116
	v_lshl_add_u64 v[112:113], v[138:139], 2, s[10:11]
	s_and_saveexec_b64 s[24:25], s[2:3]
	s_cbranch_execz .LBB0_800
	s_waitcnt lgkmcnt(0)
	v_add_f32_e32 v116, v116, v117
	global_atomic_add_f32 v[112:113], v116, off
; __device__ __forceinline__ u32x4 pack8(f32x4 a, f32x4 b) { u32x4 w; w.x = cvt_pk_bf16(a[0], a[1]); w.y = cvt_pk_bf16(a[2], a[3]); w.z = cvt_pk_bf16(b[0], b[1]); w.w = cvt_pk_bf16(b[2], b[3]); return w; }
;     __device__ __forceinline__ void operator()(const f32x4 (&acc)[2][2][4][2], const Unit& u, int wr, int wc, int fr, int fq) const {
;         const int row0 = u.pm * BM + wr * 64 + fr, col = u.pn * BM + wc * 64 + 8 * fq;
; #pragma unroll
;         for (int ai = 0; ai < 2; ++ai)
; #pragma unroll
;             for (int m = 0; m < 4; ++m) {
;                 const int row = row0 + ai * HALF + m * 16; const size_t off = (size_t)row * 2048 + col;
;                 float s = 0.f;
; #pragma unroll
;                 for (int bj = 0; bj < 2; ++bj) {
;                     f32x4 b0, b1;
;                     if (BASE_F32) { const float* bp = (const float*)base + off + bj * 32; b0 = *(const f32x4*)bp; b1 = *(const f32x4*)(bp + 4); }
;                     else { const u32x4 w = *(const u32x4*)((const bf16_t*)base + off + bj * 32);
;                         b0 = (f32x4){__uint_as_float(w.x << 16), __uint_as_float(w.x & 0xffff0000u), __uint_as_float(w.y << 16), __uint_as_float(w.y & 0xffff0000u)};
;                         b1 = (f32x4){__uint_as_float(w.z << 16), __uint_as_float(w.z & 0xffff0000u), __uint_as_float(w.w << 16), __uint_as_float(w.w & 0xffff0000u)}; }
;                     const f32x4 h0 = b0 + acc[ai][bj][m][0], h1 = b1 + acc[ai][bj][m][1];
;                     s += (h0[0] * h0[0] + h0[1] * h0[1]) + (h0[2] * h0[2] + h0[3] * h0[3]) + (h1[0] * h1[0] + h1[1] * h1[1]) + (h1[2] * h1[2] + h1[3] * h1[3]);
;                     *(u32x4*)(H + off + bj * 32) = pack8(h0, h1);
;                 }
;                 s += __shfl_xor(s, 16); s += __shfl_xor(s, 32);
;                 if (fq == 0) __hip_atomic_fetch_add(ss + row, s, __ATOMIC_RELAXED, __HIP_MEMORY_SCOPE_AGENT);
;                 if (m & 1) asm volatile("" ::: "memory");
;             }
.LBB0_800:
	s_or_b64 exec, exec, s[24:25]
	v_or_b32_e32 v116, 16, v138
	s_waitcnt lgkmcnt(0)
	v_ashrrev_i32_e32 v117, 31, v116
	v_lshlrev_b64 v[116:117], 12, v[116:117]
	v_lshl_add_u64 v[116:117], s[8:9], 0, v[116:117]
	v_lshl_add_u64 v[120:121], v[136:137], 1, v[116:117]
	s_nop 1
	s_waitcnt vmcnt(13)
	v_mov_b32_e32 v116, v162
	v_mov_b32_e32 v117, v163
	v_mov_b32_e32 v118, v164
	v_mov_b32_e32 v119, v165
	s_nop 0
	v_lshlrev_b32_e32 v122, 16, v116
	v_and_b32_e32 v123, 0xffff0000, v116
	v_lshlrev_b32_e32 v116, 16, v117
	v_and_b32_e32 v117, 0xffff0000, v117
	v_lshlrev_b32_e32 v124, 16, v118
	v_and_b32_e32 v125, 0xffff0000, v118
	v_lshlrev_b32_e32 v118, 16, v119
	v_and_b32_e32 v119, 0xffff0000, v119
	v_pk_add_f32 v[116:117], v[110:111], v[116:117]
	v_pk_add_f32 v[122:123], v[108:109], v[122:123]
	v_pk_add_f32 v[118:119], v[106:107], v[118:119]
	v_pk_add_f32 v[124:125], v[104:105], v[124:125]
	v_cvt_pk_bf16_f32 v104, v122, v123
	v_cvt_pk_bf16_f32 v105, v116, v117
	v_mul_f32_e32 v123, v123, v123
	v_cvt_pk_bf16_f32 v106, v124, v125
	v_cvt_pk_bf16_f32 v107, v118, v119
	s_nop 1
	s_waitcnt vmcnt(12)
	v_mov_b32_e32 v108, v166
	v_mov_b32_e32 v109, v167
	v_mov_b32_e32 v110, v168
	v_mov_b32_e32 v111, v169
	v_add_u32_e32 v220, 0xb0, v138
	v_ashrrev_i32_e32 v221, 31, v220
	v_lshlrev_b64 v[220:221], 12, v[220:221]
	v_lshl_add_u64 v[220:221], s[8:9], 0, v[220:221]
	v_lshl_add_u64 v[220:221], v[136:137], 1, v[220:221]
	global_load_dwordx4 v[162:165], v[220:221], off
	global_load_dwordx4 v[166:169], v[220:221], off offset:64
	v_mul_f32_e32 v117, v117, v117
	v_mul_f32_e32 v125, v125, v125
	v_fmac_f32_e32 v123, v122, v122
	v_fmac_f32_e32 v117, v116, v116
	v_mul_f32_e32 v119, v119, v119
	v_fmac_f32_e32 v125, v124, v124
	v_add_f32_e32 v116, v123, v117
	v_fmac_f32_e32 v119, v118, v118
	v_add_f32_e32 v116, v125, v116
	v_add_f32_e32 v122, v119, v116
	global_store_dwordx4 v[120:121], v[104:107], off
	s_nop 0
	v_lshlrev_b32_e32 v116, 16, v108
	v_and_b32_e32 v117, 0xffff0000, v108
	v_lshlrev_b32_e32 v108, 16, v109
	v_and_b32_e32 v109, 0xffff0000, v109
	v_lshlrev_b32_e32 v118, 16, v110
	v_and_b32_e32 v119, 0xffff0000, v110
	v_lshlrev_b32_e32 v110, 16, v111
	v_and_b32_e32 v111, 0xffff0000, v111
	v_pk_add_f32 v[102:103], v[102:103], v[108:109]
	v_pk_add_f32 v[100:101], v[100:101], v[116:117]
	v_pk_add_f32 v[108:109], v[98:99], v[110:111]
	v_pk_add_f32 v[110:111], v[96:97], v[118:119]
	v_mul_f32_e32 v96, v101, v101
	v_mul_f32_e32 v97, v103, v103
	v_mul_f32_e32 v98, v111, v111
	v_fmac_f32_e32 v96, v100, v100
	v_fmac_f32_e32 v97, v102, v102
	v_mul_f32_e32 v99, v109, v109
	v_fmac_f32_e32 v98, v110, v110
	v_add_f32_e32 v96, v96, v97
	v_add_f32_e32 v96, v98, v96
	v_fmac_f32_e32 v99, v108, v108
	v_add_f32_e32 v96, v99, v96
	v_add_f32_e32 v96, v122, v96
	ds_bpermute_b32 v97, v114, v96
	v_cvt_pk_bf16_f32 v98, v100, v101
	v_cvt_pk_bf16_f32 v99, v102, v103
	v_cvt_pk_bf16_f32 v100, v110, v111
	v_cvt_pk_bf16_f32 v101, v108, v109
	s_waitcnt lgkmcnt(0)
	v_add_f32_e32 v96, v96, v97
	ds_bpermute_b32 v97, v115, v96
	global_store_dwordx4 v[120:121], v[98:101], off offset:64
	s_and_saveexec_b64 s[24:25], s[2:3]
	s_cbranch_execz .LBB0_802
	s_waitcnt lgkmcnt(0)
	v_add_f32_e32 v96, v96, v97
	global_atomic_add_f32 v[112:113], v96, off offset:64
.LBB0_802:
	s_or_b64 exec, exec, s[24:25]
	v_or_b32_e32 v96, 32, v138
	s_waitcnt lgkmcnt(0)
	v_ashrrev_i32_e32 v97, 31, v96
	v_lshlrev_b64 v[96:97], 12, v[96:97]
	v_lshl_add_u64 v[96:97], s[8:9], 0, v[96:97]
	v_lshl_add_u64 v[100:101], v[136:137], 1, v[96:97]
	s_nop 1
	s_waitcnt vmcnt(15)
	v_mov_b32_e32 v96, v178
	v_mov_b32_e32 v97, v179
	v_mov_b32_e32 v98, v180
	v_mov_b32_e32 v99, v181
	s_nop 0
	v_lshlrev_b32_e32 v102, 16, v96
	v_and_b32_e32 v103, 0xffff0000, v96
	v_lshlrev_b32_e32 v96, 16, v97
	v_and_b32_e32 v97, 0xffff0000, v97
	v_lshlrev_b32_e32 v104, 16, v98
	v_and_b32_e32 v105, 0xffff0000, v98
	v_lshlrev_b32_e32 v98, 16, v99
	v_and_b32_e32 v99, 0xffff0000, v99
	v_pk_add_f32 v[96:97], v[94:95], v[96:97]
	v_pk_add_f32 v[102:103], v[92:93], v[102:103]
	v_pk_add_f32 v[98:99], v[90:91], v[98:99]
	v_pk_add_f32 v[104:105], v[88:89], v[104:105]
	v_cvt_pk_bf16_f32 v88, v102, v103
	v_cvt_pk_bf16_f32 v89, v96, v97
	v_mul_f32_e32 v103, v103, v103
	v_cvt_pk_bf16_f32 v90, v104, v105
	v_cvt_pk_bf16_f32 v91, v98, v99
	s_nop 1
	s_waitcnt vmcnt(14)
	v_mov_b32_e32 v92, v182
	v_mov_b32_e32 v93, v183
	v_mov_b32_e32 v94, v184
	v_mov_b32_e32 v95, v185
	v_mul_f32_e32 v97, v97, v97
	v_mul_f32_e32 v105, v105, v105
	v_fmac_f32_e32 v103, v102, v102
	v_fmac_f32_e32 v97, v96, v96
	v_mul_f32_e32 v99, v99, v99
	v_fmac_f32_e32 v105, v104, v104
	v_add_f32_e32 v96, v103, v97
	v_fmac_f32_e32 v99, v98, v98
	v_add_f32_e32 v96, v105, v96
	v_add_f32_e32 v102, v99, v96
	global_store_dwordx4 v[100:101], v[88:91], off
	s_nop 0
	v_lshlrev_b32_e32 v96, 16, v92
	v_and_b32_e32 v97, 0xffff0000, v92
	v_lshlrev_b32_e32 v92, 16, v93
	v_and_b32_e32 v93, 0xffff0000, v93
	v_lshlrev_b32_e32 v98, 16, v94
	v_and_b32_e32 v99, 0xffff0000, v94
	v_lshlrev_b32_e32 v94, 16, v95
	v_and_b32_e32 v95, 0xffff0000, v95
	v_pk_add_f32 v[86:87], v[86:87], v[92:93]
	v_pk_add_f32 v[84:85], v[84:85], v[96:97]
	v_pk_add_f32 v[92:93], v[82:83], v[94:95]
	v_pk_add_f32 v[94:95], v[80:81], v[98:99]
	v_mul_f32_e32 v80, v85, v85
	v_mul_f32_e32 v81, v87, v87
	v_mul_f32_e32 v82, v95, v95
	v_fmac_f32_e32 v80, v84, v84
	v_fmac_f32_e32 v81, v86, v86
	v_mul_f32_e32 v83, v93, v93
	v_fmac_f32_e32 v82, v94, v94
	v_add_f32_e32 v80, v80, v81
	v_add_f32_e32 v80, v82, v80
	v_fmac_f32_e32 v83, v92, v92
	v_add_f32_e32 v80, v83, v80
	v_add_f32_e32 v80, v102, v80
	ds_bpermute_b32 v81, v114, v80
	v_cvt_pk_bf16_f32 v82, v84, v85
	v_cvt_pk_bf16_f32 v83, v86, v87
	v_cvt_pk_bf16_f32 v84, v94, v95
	v_cvt_pk_bf16_f32 v85, v92, v93
	s_waitcnt lgkmcnt(0)
	v_add_f32_e32 v80, v80, v81
	ds_bpermute_b32 v81, v115, v80
	global_store_dwordx4 v[100:101], v[82:85], off offset:64
	s_and_saveexec_b64 s[24:25], s[2:3]
	s_cbranch_execz .LBB0_804
	s_waitcnt lgkmcnt(0)
	v_add_f32_e32 v80, v80, v81
	global_atomic_add_f32 v[112:113], v80, off offset:128
; __device__ __forceinline__ u32x4 pack8(f32x4 a, f32x4 b) { u32x4 w; w.x = cvt_pk_bf16(a[0], a[1]); w.y = cvt_pk_bf16(a[2], a[3]); w.z = cvt_pk_bf16(b[0], b[1]); w.w = cvt_pk_bf16(b[2], b[3]); return w; }
;     __device__ __forceinline__ void operator()(const f32x4 (&acc)[2][2][4][2], const Unit& u, int wr, int wc, int fr, int fq) const {
;         const int row0 = u.pm * BM + wr * 64 + fr, col = u.pn * BM + wc * 64 + 8 * fq;
; #pragma unroll
;         for (int ai = 0; ai < 2; ++ai)
; #pragma unroll
;             for (int m = 0; m < 4; ++m) {
;                 const int row = row0 + ai * HALF + m * 16; const size_t off = (size_t)row * 2048 + col;
;                 float s = 0.f;
; #pragma unroll
;                 for (int bj = 0; bj < 2; ++bj) {
;                     f32x4 b0, b1;
;                     if (BASE_F32) { const float* bp = (const float*)base + off + bj * 32; b0 = *(const f32x4*)bp; b1 = *(const f32x4*)(bp + 4); }
;                     else { const u32x4 w = *(const u32x4*)((const bf16_t*)base + off + bj * 32);
;                         b0 = (f32x4){__uint_as_float(w.x << 16), __uint_as_float(w.x & 0xffff0000u), __uint_as_float(w.y << 16), __uint_as_float(w.y & 0xffff0000u)};
;                         b1 = (f32x4){__uint_as_float(w.z << 16), __uint_as_float(w.z & 0xffff0000u), __uint_as_float(w.w << 16), __uint_as_float(w.w & 0xffff0000u)}; }
;                     const f32x4 h0 = b0 + acc[ai][bj][m][0], h1 = b1 + acc[ai][bj][m][1];
;                     s += (h0[0] * h0[0] + h0[1] * h0[1]) + (h0[2] * h0[2] + h0[3] * h0[3]) + (h1[0] * h1[0] + h1[1] * h1[1]) + (h1[2] * h1[2] + h1[3] * h1[3]);
;                     *(u32x4*)(H + off + bj * 32) = pack8(h0, h1);
;                 }
;                 s += __shfl_xor(s, 16); s += __shfl_xor(s, 32);
;                 if (fq == 0) __hip_atomic_fetch_add(ss + row, s, __ATOMIC_RELAXED, __HIP_MEMORY_SCOPE_AGENT);
;                 if (m & 1) asm volatile("" ::: "memory");
;             }
.LBB0_804:
	s_or_b64 exec, exec, s[24:25]
	v_or_b32_e32 v80, 48, v138
	s_waitcnt lgkmcnt(0)
	v_ashrrev_i32_e32 v81, 31, v80
	v_lshlrev_b64 v[80:81], 12, v[80:81]
	v_lshl_add_u64 v[80:81], s[8:9], 0, v[80:81]
	v_lshl_add_u64 v[84:85], v[136:137], 1, v[80:81]
	s_nop 1
	s_waitcnt vmcnt(15)
	v_mov_b32_e32 v80, v186
	v_mov_b32_e32 v81, v187
	v_mov_b32_e32 v82, v188
	v_mov_b32_e32 v83, v189
	s_nop 0
	v_lshlrev_b32_e32 v86, 16, v80
	v_and_b32_e32 v87, 0xffff0000, v80
	v_lshlrev_b32_e32 v80, 16, v81
	v_and_b32_e32 v81, 0xffff0000, v81
	v_lshlrev_b32_e32 v88, 16, v82
	v_and_b32_e32 v89, 0xffff0000, v82
	v_lshlrev_b32_e32 v82, 16, v83
	v_and_b32_e32 v83, 0xffff0000, v83
	v_pk_add_f32 v[80:81], v[78:79], v[80:81]
	v_pk_add_f32 v[86:87], v[76:77], v[86:87]
	v_pk_add_f32 v[82:83], v[74:75], v[82:83]
	v_pk_add_f32 v[88:89], v[72:73], v[88:89]
	v_cvt_pk_bf16_f32 v72, v86, v87
	v_cvt_pk_bf16_f32 v73, v80, v81
	v_mul_f32_e32 v87, v87, v87
	v_cvt_pk_bf16_f32 v74, v88, v89
	v_cvt_pk_bf16_f32 v75, v82, v83
	s_nop 1
	s_waitcnt vmcnt(14)
	v_mov_b32_e32 v76, v190
	v_mov_b32_e32 v77, v191
	v_mov_b32_e32 v78, v192
	v_mov_b32_e32 v79, v193
	v_mul_f32_e32 v81, v81, v81
	v_mul_f32_e32 v89, v89, v89
	v_fmac_f32_e32 v87, v86, v86
	v_fmac_f32_e32 v81, v80, v80
	v_mul_f32_e32 v83, v83, v83
	v_fmac_f32_e32 v89, v88, v88
	v_add_f32_e32 v80, v87, v81
	v_fmac_f32_e32 v83, v82, v82
	v_add_f32_e32 v80, v89, v80
	v_add_f32_e32 v86, v83, v80
	global_store_dwordx4 v[84:85], v[72:75], off
	s_nop 0
	v_lshlrev_b32_e32 v80, 16, v76
	v_and_b32_e32 v81, 0xffff0000, v76
	v_lshlrev_b32_e32 v76, 16, v77
	v_and_b32_e32 v77, 0xffff0000, v77
	v_lshlrev_b32_e32 v82, 16, v78
	v_and_b32_e32 v83, 0xffff0000, v78
	v_lshlrev_b32_e32 v78, 16, v79
	v_and_b32_e32 v79, 0xffff0000, v79
	v_pk_add_f32 v[70:71], v[70:71], v[76:77]
	v_pk_add_f32 v[68:69], v[68:69], v[80:81]
	v_pk_add_f32 v[76:77], v[66:67], v[78:79]
	v_pk_add_f32 v[78:79], v[64:65], v[82:83]
	v_mul_f32_e32 v64, v69, v69
	v_mul_f32_e32 v65, v71, v71
	v_mul_f32_e32 v66, v79, v79
	v_fmac_f32_e32 v64, v68, v68
	v_fmac_f32_e32 v65, v70, v70
	v_mul_f32_e32 v67, v77, v77
	v_fmac_f32_e32 v66, v78, v78
	v_add_f32_e32 v64, v64, v65
	v_add_f32_e32 v64, v66, v64
	v_fmac_f32_e32 v67, v76, v76
	v_add_f32_e32 v64, v67, v64
	v_add_f32_e32 v64, v86, v64
	ds_bpermute_b32 v65, v114, v64
	v_cvt_pk_bf16_f32 v66, v68, v69
	v_cvt_pk_bf16_f32 v67, v70, v71
	v_cvt_pk_bf16_f32 v68, v78, v79
	v_cvt_pk_bf16_f32 v69, v76, v77
	s_waitcnt lgkmcnt(0)
	v_add_f32_e32 v64, v64, v65
	ds_bpermute_b32 v65, v115, v64
	global_store_dwordx4 v[84:85], v[66:69], off offset:64
	s_and_saveexec_b64 s[24:25], s[2:3]
	s_cbranch_execz .LBB0_806
	s_waitcnt lgkmcnt(0)
	v_add_f32_e32 v64, v64, v65
	global_atomic_add_f32 v[112:113], v64, off offset:192
.LBB0_806:
	s_or_b64 exec, exec, s[24:25]
	v_add_co_u32_e32 v68, vcc, 0x80000, v134
	s_mov_b64 s[24:25], 0x80000
	s_nop 0
	v_addc_co_u32_e32 v69, vcc, 0, v135, vcc
	s_waitcnt lgkmcnt(0)
	s_nop 1
	s_waitcnt vmcnt(15)
	v_mov_b32_e32 v64, v194
	v_mov_b32_e32 v65, v195
	v_mov_b32_e32 v66, v196
	v_mov_b32_e32 v67, v197
	v_lshl_add_u64 v[70:71], v[134:135], 0, s[24:25]
	s_nop 0
	v_lshlrev_b32_e32 v72, 16, v64
	v_and_b32_e32 v73, 0xffff0000, v64
	v_lshlrev_b32_e32 v64, 16, v65
	v_and_b32_e32 v65, 0xffff0000, v65
	v_lshlrev_b32_e32 v74, 16, v66
	v_and_b32_e32 v75, 0xffff0000, v66
	v_lshlrev_b32_e32 v66, 16, v67
	v_and_b32_e32 v67, 0xffff0000, v67
	v_pk_add_f32 v[64:65], v[62:63], v[64:65]
	v_pk_add_f32 v[72:73], v[60:61], v[72:73]
	v_pk_add_f32 v[66:67], v[58:59], v[66:67]
	v_pk_add_f32 v[74:75], v[56:57], v[74:75]
	v_cvt_pk_bf16_f32 v56, v72, v73
	v_cvt_pk_bf16_f32 v57, v64, v65
	v_mul_f32_e32 v73, v73, v73
	v_cvt_pk_bf16_f32 v58, v74, v75
	v_cvt_pk_bf16_f32 v59, v66, v67
	s_nop 1
	s_waitcnt vmcnt(14)
	v_mov_b32_e32 v60, v198
	v_mov_b32_e32 v61, v199
	v_mov_b32_e32 v62, v200
	v_mov_b32_e32 v63, v201
	v_mul_f32_e32 v65, v65, v65
	v_mul_f32_e32 v75, v75, v75
	v_fmac_f32_e32 v73, v72, v72
	v_fmac_f32_e32 v65, v64, v64
	v_mul_f32_e32 v67, v67, v67
	v_fmac_f32_e32 v75, v74, v74
	v_add_f32_e32 v64, v73, v65
	v_fmac_f32_e32 v67, v66, v66
	v_add_f32_e32 v64, v75, v64
	v_add_f32_e32 v72, v67, v64
	global_store_dwordx4 v[68:69], v[56:59], off
	s_nop 0
	v_lshlrev_b32_e32 v64, 16, v60
	v_and_b32_e32 v65, 0xffff0000, v60
	v_lshlrev_b32_e32 v60, 16, v61
	v_and_b32_e32 v61, 0xffff0000, v61
	v_lshlrev_b32_e32 v66, 16, v62
	v_and_b32_e32 v67, 0xffff0000, v62
	v_lshlrev_b32_e32 v62, 16, v63
	v_and_b32_e32 v63, 0xffff0000, v63
	v_pk_add_f32 v[54:55], v[54:55], v[60:61]
	v_pk_add_f32 v[52:53], v[52:53], v[64:65]
	v_pk_add_f32 v[60:61], v[50:51], v[62:63]
	v_pk_add_f32 v[62:63], v[48:49], v[66:67]
	v_mul_f32_e32 v48, v53, v53
	v_mul_f32_e32 v49, v55, v55
	v_mul_f32_e32 v50, v63, v63
	v_fmac_f32_e32 v48, v52, v52
	v_fmac_f32_e32 v49, v54, v54
	v_mul_f32_e32 v51, v61, v61
	v_fmac_f32_e32 v50, v62, v62
	v_add_f32_e32 v48, v48, v49
	v_add_f32_e32 v48, v50, v48
	v_fmac_f32_e32 v51, v60, v60
	v_add_f32_e32 v48, v51, v48
	v_add_f32_e32 v48, v72, v48
	ds_bpermute_b32 v49, v114, v48
	v_cvt_pk_bf16_f32 v50, v52, v53
	v_cvt_pk_bf16_f32 v51, v54, v55
	v_cvt_pk_bf16_f32 v52, v62, v63
	v_cvt_pk_bf16_f32 v53, v60, v61
	s_waitcnt lgkmcnt(0)
	v_add_f32_e32 v48, v48, v49
	ds_bpermute_b32 v49, v115, v48
	global_store_dwordx4 v[70:71], v[50:53], off offset:64
	s_and_saveexec_b64 s[24:25], s[2:3]
	s_cbranch_execz .LBB0_808
	s_waitcnt lgkmcnt(0)
	v_add_f32_e32 v48, v48, v49
	global_atomic_add_f32 v[112:113], v48, off offset:512
; __device__ __forceinline__ u32x4 pack8(f32x4 a, f32x4 b) { u32x4 w; w.x = cvt_pk_bf16(a[0], a[1]); w.y = cvt_pk_bf16(a[2], a[3]); w.z = cvt_pk_bf16(b[0], b[1]); w.w = cvt_pk_bf16(b[2], b[3]); return w; }
;     __device__ __forceinline__ void operator()(const f32x4 (&acc)[2][2][4][2], const Unit& u, int wr, int wc, int fr, int fq) const {
;         const int row0 = u.pm * BM + wr * 64 + fr, col = u.pn * BM + wc * 64 + 8 * fq;
; #pragma unroll
;         for (int ai = 0; ai < 2; ++ai)
; #pragma unroll
;             for (int m = 0; m < 4; ++m) {
;                 const int row = row0 + ai * HALF + m * 16; const size_t off = (size_t)row * 2048 + col;
;                 float s = 0.f;
; #pragma unroll
;                 for (int bj = 0; bj < 2; ++bj) {
;                     f32x4 b0, b1;
;                     if (BASE_F32) { const float* bp = (const float*)base + off + bj * 32; b0 = *(const f32x4*)bp; b1 = *(const f32x4*)(bp + 4); }
;                     else { const u32x4 w = *(const u32x4*)((const bf16_t*)base + off + bj * 32);
;                         b0 = (f32x4){__uint_as_float(w.x << 16), __uint_as_float(w.x & 0xffff0000u), __uint_as_float(w.y << 16), __uint_as_float(w.y & 0xffff0000u)};
;                         b1 = (f32x4){__uint_as_float(w.z << 16), __uint_as_float(w.z & 0xffff0000u), __uint_as_float(w.w << 16), __uint_as_float(w.w & 0xffff0000u)}; }
;                     const f32x4 h0 = b0 + acc[ai][bj][m][0], h1 = b1 + acc[ai][bj][m][1];
;                     s += (h0[0] * h0[0] + h0[1] * h0[1]) + (h0[2] * h0[2] + h0[3] * h0[3]) + (h1[0] * h1[0] + h1[1] * h1[1]) + (h1[2] * h1[2] + h1[3] * h1[3]);
;                     *(u32x4*)(H + off + bj * 32) = pack8(h0, h1);
;                 }
;                 s += __shfl_xor(s, 16); s += __shfl_xor(s, 32);
;                 if (fq == 0) __hip_atomic_fetch_add(ss + row, s, __ATOMIC_RELAXED, __HIP_MEMORY_SCOPE_AGENT);
;                 if (m & 1) asm volatile("" ::: "memory");
;             }
.LBB0_808:
	s_or_b64 exec, exec, s[24:25]
	v_add_co_u32_e32 v52, vcc, 0x90000, v134
	s_mov_b64 s[24:25], 0x90000
	s_nop 0
	v_addc_co_u32_e32 v53, vcc, 0, v135, vcc
	s_waitcnt lgkmcnt(0)
	s_nop 1
	s_waitcnt vmcnt(15)
	v_mov_b32_e32 v48, v212
	v_mov_b32_e32 v49, v213
	v_mov_b32_e32 v50, v214
	v_mov_b32_e32 v51, v215
	v_lshl_add_u64 v[54:55], v[134:135], 0, s[24:25]
	s_nop 0
	v_lshlrev_b32_e32 v56, 16, v48
	v_and_b32_e32 v57, 0xffff0000, v48
	v_lshlrev_b32_e32 v48, 16, v49
	v_and_b32_e32 v49, 0xffff0000, v49
	v_lshlrev_b32_e32 v58, 16, v50
	v_and_b32_e32 v59, 0xffff0000, v50
	v_lshlrev_b32_e32 v50, 16, v51
	v_and_b32_e32 v51, 0xffff0000, v51
	v_pk_add_f32 v[48:49], v[46:47], v[48:49]
	v_pk_add_f32 v[56:57], v[44:45], v[56:57]
	v_pk_add_f32 v[50:51], v[42:43], v[50:51]
	v_pk_add_f32 v[58:59], v[40:41], v[58:59]
	v_cvt_pk_bf16_f32 v40, v56, v57
	v_cvt_pk_bf16_f32 v41, v48, v49
	v_mul_f32_e32 v57, v57, v57
	v_cvt_pk_bf16_f32 v42, v58, v59
	v_cvt_pk_bf16_f32 v43, v50, v51
	s_nop 1
	s_waitcnt vmcnt(14)
	v_mov_b32_e32 v44, v216
	v_mov_b32_e32 v45, v217
	v_mov_b32_e32 v46, v218
	v_mov_b32_e32 v47, v219
	v_mul_f32_e32 v49, v49, v49
	v_mul_f32_e32 v59, v59, v59
	v_fmac_f32_e32 v57, v56, v56
	v_fmac_f32_e32 v49, v48, v48
	v_mul_f32_e32 v51, v51, v51
	v_fmac_f32_e32 v59, v58, v58
	v_add_f32_e32 v48, v57, v49
	v_fmac_f32_e32 v51, v50, v50
	v_add_f32_e32 v48, v59, v48
	v_add_f32_e32 v56, v51, v48
	global_store_dwordx4 v[52:53], v[40:43], off
	s_nop 0
	v_lshlrev_b32_e32 v48, 16, v44
	v_and_b32_e32 v49, 0xffff0000, v44
	v_lshlrev_b32_e32 v44, 16, v45
	v_and_b32_e32 v45, 0xffff0000, v45
	v_lshlrev_b32_e32 v50, 16, v46
	v_and_b32_e32 v51, 0xffff0000, v46
	v_lshlrev_b32_e32 v46, 16, v47
	v_and_b32_e32 v47, 0xffff0000, v47
	v_pk_add_f32 v[38:39], v[38:39], v[44:45]
	v_pk_add_f32 v[36:37], v[36:37], v[48:49]
	v_pk_add_f32 v[44:45], v[34:35], v[46:47]
	v_pk_add_f32 v[46:47], v[32:33], v[50:51]
	v_mul_f32_e32 v32, v37, v37
	v_mul_f32_e32 v33, v39, v39
	v_mul_f32_e32 v34, v47, v47
	v_fmac_f32_e32 v32, v36, v36
	v_fmac_f32_e32 v33, v38, v38
	v_mul_f32_e32 v35, v45, v45
	v_fmac_f32_e32 v34, v46, v46
	v_add_f32_e32 v32, v32, v33
	v_add_f32_e32 v32, v34, v32
	v_fmac_f32_e32 v35, v44, v44
	v_add_f32_e32 v32, v35, v32
	v_add_f32_e32 v32, v56, v32
	ds_bpermute_b32 v33, v114, v32
	v_cvt_pk_bf16_f32 v34, v36, v37
	v_cvt_pk_bf16_f32 v35, v38, v39
	v_cvt_pk_bf16_f32 v36, v46, v47
	v_cvt_pk_bf16_f32 v37, v44, v45
	s_waitcnt lgkmcnt(0)
	v_add_f32_e32 v32, v32, v33
	ds_bpermute_b32 v33, v115, v32
	global_store_dwordx4 v[54:55], v[34:37], off offset:64
	s_and_saveexec_b64 s[24:25], s[2:3]
	s_cbranch_execz .LBB0_810
	s_waitcnt lgkmcnt(0)
	v_add_f32_e32 v32, v32, v33
	global_atomic_add_f32 v[112:113], v32, off offset:576
; __device__ __forceinline__ u32x4 pack8(f32x4 a, f32x4 b) { u32x4 w; w.x = cvt_pk_bf16(a[0], a[1]); w.y = cvt_pk_bf16(a[2], a[3]); w.z = cvt_pk_bf16(b[0], b[1]); w.w = cvt_pk_bf16(b[2], b[3]); return w; }
;     __device__ __forceinline__ void operator()(const f32x4 (&acc)[2][2][4][2], const Unit& u, int wr, int wc, int fr, int fq) const {
;         const int row0 = u.pm * BM + wr * 64 + fr, col = u.pn * BM + wc * 64 + 8 * fq;
; #pragma unroll
;         for (int ai = 0; ai < 2; ++ai)
; #pragma unroll
;             for (int m = 0; m < 4; ++m) {
;                 const int row = row0 + ai * HALF + m * 16; const size_t off = (size_t)row * 2048 + col;
;                 float s = 0.f;
; #pragma unroll
;                 for (int bj = 0; bj < 2; ++bj) {
;                     f32x4 b0, b1;
;                     if (BASE_F32) { const float* bp = (const float*)base + off + bj * 32; b0 = *(const f32x4*)bp; b1 = *(const f32x4*)(bp + 4); }
;                     else { const u32x4 w = *(const u32x4*)((const bf16_t*)base + off + bj * 32);
;                         b0 = (f32x4){__uint_as_float(w.x << 16), __uint_as_float(w.x & 0xffff0000u), __uint_as_float(w.y << 16), __uint_as_float(w.y & 0xffff0000u)};
;                         b1 = (f32x4){__uint_as_float(w.z << 16), __uint_as_float(w.z & 0xffff0000u), __uint_as_float(w.w << 16), __uint_as_float(w.w & 0xffff0000u)}; }
;                     const f32x4 h0 = b0 + acc[ai][bj][m][0], h1 = b1 + acc[ai][bj][m][1];
;                     s += (h0[0] * h0[0] + h0[1] * h0[1]) + (h0[2] * h0[2] + h0[3] * h0[3]) + (h1[0] * h1[0] + h1[1] * h1[1]) + (h1[2] * h1[2] + h1[3] * h1[3]);
;                     *(u32x4*)(H + off + bj * 32) = pack8(h0, h1);
;                 }
;                 s += __shfl_xor(s, 16); s += __shfl_xor(s, 32);
;                 if (fq == 0) __hip_atomic_fetch_add(ss + row, s, __ATOMIC_RELAXED, __HIP_MEMORY_SCOPE_AGENT);
;                 if (m & 1) asm volatile("" ::: "memory");
;             }
.LBB0_810:
	s_or_b64 exec, exec, s[24:25]
	v_add_co_u32_e32 v36, vcc, 0xa0000, v134
	s_mov_b64 s[24:25], 0xa0000
	s_nop 0
	v_addc_co_u32_e32 v37, vcc, 0, v135, vcc
	s_waitcnt lgkmcnt(0)
	s_nop 1
	s_waitcnt vmcnt(14)
	v_mov_b32_e32 v32, v154
	v_mov_b32_e32 v33, v155
	v_mov_b32_e32 v34, v156
	v_mov_b32_e32 v35, v157
	v_lshl_add_u64 v[38:39], v[134:135], 0, s[24:25]
	s_nop 0
	v_lshlrev_b32_e32 v40, 16, v32
	v_and_b32_e32 v41, 0xffff0000, v32
	v_lshlrev_b32_e32 v32, 16, v33
	v_and_b32_e32 v33, 0xffff0000, v33
	v_lshlrev_b32_e32 v42, 16, v34
	v_and_b32_e32 v43, 0xffff0000, v34
	v_lshlrev_b32_e32 v34, 16, v35
	v_and_b32_e32 v35, 0xffff0000, v35
	v_pk_add_f32 v[32:33], v[30:31], v[32:33]
	v_pk_add_f32 v[40:41], v[28:29], v[40:41]
	v_pk_add_f32 v[34:35], v[26:27], v[34:35]
	v_pk_add_f32 v[42:43], v[24:25], v[42:43]
	v_cvt_pk_bf16_f32 v24, v40, v41
	v_cvt_pk_bf16_f32 v25, v32, v33
	v_mul_f32_e32 v41, v41, v41
	v_cvt_pk_bf16_f32 v26, v42, v43
	v_cvt_pk_bf16_f32 v27, v34, v35
	s_nop 1
	s_waitcnt vmcnt(13)
	v_mov_b32_e32 v28, v158
	v_mov_b32_e32 v29, v159
	v_mov_b32_e32 v30, v160
	v_mov_b32_e32 v31, v161
	v_mul_f32_e32 v33, v33, v33
	v_mul_f32_e32 v43, v43, v43
	v_fmac_f32_e32 v41, v40, v40
	v_fmac_f32_e32 v33, v32, v32
	v_mul_f32_e32 v35, v35, v35
	v_fmac_f32_e32 v43, v42, v42
	v_add_f32_e32 v32, v41, v33
	v_fmac_f32_e32 v35, v34, v34
	v_add_f32_e32 v32, v43, v32
	v_add_f32_e32 v40, v35, v32
	global_store_dwordx4 v[36:37], v[24:27], off
	s_nop 0
	v_lshlrev_b32_e32 v32, 16, v28
	v_and_b32_e32 v33, 0xffff0000, v28
	v_lshlrev_b32_e32 v28, 16, v29
	v_and_b32_e32 v29, 0xffff0000, v29
	v_lshlrev_b32_e32 v34, 16, v30
	v_and_b32_e32 v35, 0xffff0000, v30
	v_lshlrev_b32_e32 v30, 16, v31
	v_and_b32_e32 v31, 0xffff0000, v31
	v_pk_add_f32 v[22:23], v[22:23], v[28:29]
	v_pk_add_f32 v[20:21], v[20:21], v[32:33]
	v_pk_add_f32 v[28:29], v[18:19], v[30:31]
	v_pk_add_f32 v[30:31], v[16:17], v[34:35]
	v_mul_f32_e32 v16, v21, v21
	v_mul_f32_e32 v17, v23, v23
	v_mul_f32_e32 v18, v31, v31
	v_fmac_f32_e32 v16, v20, v20
	v_fmac_f32_e32 v17, v22, v22
	v_mul_f32_e32 v19, v29, v29
	v_fmac_f32_e32 v18, v30, v30
	v_add_f32_e32 v16, v16, v17
	v_add_f32_e32 v16, v18, v16
	v_fmac_f32_e32 v19, v28, v28
	v_add_f32_e32 v16, v19, v16
	v_add_f32_e32 v16, v40, v16
	ds_bpermute_b32 v17, v114, v16
	v_cvt_pk_bf16_f32 v18, v20, v21
	v_cvt_pk_bf16_f32 v19, v22, v23
	v_cvt_pk_bf16_f32 v20, v30, v31
	v_cvt_pk_bf16_f32 v21, v28, v29
	s_waitcnt lgkmcnt(0)
	v_add_f32_e32 v16, v16, v17
	ds_bpermute_b32 v17, v115, v16
	global_store_dwordx4 v[38:39], v[18:21], off offset:64
	s_and_saveexec_b64 s[24:25], s[2:3]
	s_cbranch_execz .LBB0_812
	s_waitcnt lgkmcnt(0)
	v_add_f32_e32 v16, v16, v17
	global_atomic_add_f32 v[112:113], v16, off offset:640
.LBB0_812:
	s_or_b64 exec, exec, s[24:25]
	v_add_co_u32_e32 v20, vcc, 0xb0000, v134
	s_mov_b64 s[24:25], 0xb0000
	s_nop 0
	v_addc_co_u32_e32 v21, vcc, 0, v135, vcc
	s_waitcnt lgkmcnt(0)
	s_nop 1
	s_waitcnt vmcnt(13)
	v_mov_b32_e32 v16, v162
	v_mov_b32_e32 v17, v163
	v_mov_b32_e32 v18, v164
	v_mov_b32_e32 v19, v165
	v_lshl_add_u64 v[22:23], v[134:135], 0, s[24:25]
	s_nop 0
	v_lshlrev_b32_e32 v24, 16, v16
	v_and_b32_e32 v25, 0xffff0000, v16
	v_lshlrev_b32_e32 v16, 16, v17
	v_and_b32_e32 v17, 0xffff0000, v17
	v_lshlrev_b32_e32 v26, 16, v18
	v_and_b32_e32 v27, 0xffff0000, v18
	v_lshlrev_b32_e32 v18, 16, v19
	v_and_b32_e32 v19, 0xffff0000, v19
	v_pk_add_f32 v[16:17], v[14:15], v[16:17]
	v_pk_add_f32 v[24:25], v[12:13], v[24:25]
	v_pk_add_f32 v[18:19], v[10:11], v[18:19]
	v_pk_add_f32 v[26:27], v[8:9], v[26:27]
	v_cvt_pk_bf16_f32 v8, v24, v25
	v_cvt_pk_bf16_f32 v9, v16, v17
	v_mul_f32_e32 v25, v25, v25
	v_cvt_pk_bf16_f32 v10, v26, v27
	v_cvt_pk_bf16_f32 v11, v18, v19
	s_nop 1
	s_waitcnt vmcnt(12)
	v_mov_b32_e32 v12, v166
	v_mov_b32_e32 v13, v167
	v_mov_b32_e32 v14, v168
	v_mov_b32_e32 v15, v169
	v_mul_f32_e32 v17, v17, v17
	v_mul_f32_e32 v27, v27, v27
	v_fmac_f32_e32 v25, v24, v24
	v_fmac_f32_e32 v17, v16, v16
	v_mul_f32_e32 v19, v19, v19
	v_fmac_f32_e32 v27, v26, v26
	v_add_f32_e32 v16, v25, v17
	v_fmac_f32_e32 v19, v18, v18
	v_add_f32_e32 v16, v27, v16
	v_add_f32_e32 v24, v19, v16
	global_store_dwordx4 v[20:21], v[8:11], off
	s_nop 0
	v_lshlrev_b32_e32 v16, 16, v12
	v_and_b32_e32 v17, 0xffff0000, v12
	v_lshlrev_b32_e32 v12, 16, v13
	v_and_b32_e32 v13, 0xffff0000, v13
	v_lshlrev_b32_e32 v18, 16, v14
	v_and_b32_e32 v19, 0xffff0000, v14
	v_lshlrev_b32_e32 v14, 16, v15
	v_and_b32_e32 v15, 0xffff0000, v15
	v_pk_add_f32 v[6:7], v[6:7], v[12:13]
	v_pk_add_f32 v[4:5], v[4:5], v[16:17]
	v_pk_add_f32 v[12:13], v[2:3], v[14:15]
	v_pk_add_f32 v[14:15], v[0:1], v[18:19]
	v_mul_f32_e32 v0, v5, v5
	v_mul_f32_e32 v1, v7, v7
	v_mul_f32_e32 v2, v15, v15
	v_fmac_f32_e32 v0, v4, v4
	v_fmac_f32_e32 v1, v6, v6
	v_mul_f32_e32 v3, v13, v13
	v_fmac_f32_e32 v2, v14, v14
	v_add_f32_e32 v0, v0, v1
	v_add_f32_e32 v0, v2, v0
	v_fmac_f32_e32 v3, v12, v12
	v_add_f32_e32 v0, v3, v0
	v_add_f32_e32 v0, v24, v0
	ds_bpermute_b32 v1, v114, v0
	v_cvt_pk_bf16_f32 v2, v4, v5
	v_cvt_pk_bf16_f32 v3, v6, v7
	v_cvt_pk_bf16_f32 v4, v14, v15
	v_cvt_pk_bf16_f32 v5, v12, v13
	s_waitcnt lgkmcnt(0)
	v_add_f32_e32 v0, v0, v1
	ds_bpermute_b32 v1, v115, v0
	global_store_dwordx4 v[22:23], v[2:5], off offset:64
	s_and_saveexec_b64 s[24:25], s[2:3]
	s_cbranch_execz .LBB0_814
	s_waitcnt lgkmcnt(0)
	v_add_f32_e32 v0, v0, v1
	global_atomic_add_f32 v[112:113], v0, off offset:704
